# vY + nt (non-temporal) on the f32 weight-conversion global_load_dword in P5 and layer-0 P2 (read-once stream, keep L2 for GEMM operands)
# speedup vs baseline: 1.0261x; 1.0261x over previous
.LBB0_482:
	s_cmpk_gt_i32 s12, 0x4ff
	s_mov_b64 s[0:1], -1
	s_cbranch_scc0 .LBB0_502
	s_cmpk_gt_u32 s12, 0x53f
	s_cbranch_scc0 .LBB0_499
	s_cmpk_gt_u32 s12, 0x57f
	s_cbranch_scc0 .LBB0_496
	s_cmpk_gt_u32 s12, 0x67f
	s_cbranch_scc0 .LBB0_493
	s_cmpk_gt_u32 s12, 0xbff
	s_cbranch_scc0 .LBB0_488
	s_and_b32 s0, s6, 0x7fffffc0
	s_add_i32 s92, s0, 0xffffd000
	s_and_b32 s0, s4, 0x3c0
	s_lshl_b64 s[28:29], s[92:93], 12
	v_readlane_b32 s30, v254, 50
	v_readlane_b32 s31, v254, 51
	s_add_u32 s1, s30, s28
	s_addc_u32 s20, s31, s29
	s_lshl_b32 s27, s0, 2
	s_add_u32 s28, s1, s27
	s_addc_u32 s29, s20, 0
	v_lshl_add_u64 v[0:1], v[148:149], 2, s[28:29]
	v_add_co_u32_e32 v6, vcc, s11, v0
	s_movk_i32 s1, 0x4000
	s_nop 0
	v_addc_co_u32_e32 v7, vcc, 0, v1, vcc
	v_add_co_u32_e32 v8, vcc, s1, v0
	s_movk_i32 s1, 0x6000
	s_nop 0
	v_addc_co_u32_e32 v9, vcc, 0, v1, vcc
	v_add_co_u32_e32 v10, vcc, s1, v0
	s_mov_b32 s1, 0x8000
	s_nop 0
	v_addc_co_u32_e32 v11, vcc, 0, v1, vcc
	v_add_co_u32_e32 v12, vcc, s1, v0
	s_mov_b32 s1, 0xa000
	s_nop 0
	v_addc_co_u32_e32 v13, vcc, 0, v1, vcc
	v_add_co_u32_e32 v14, vcc, s1, v0
	s_mov_b32 s1, 0xc000
	s_nop 0
	v_addc_co_u32_e32 v15, vcc, 0, v1, vcc
	s_waitcnt vmcnt(5)
	v_add_co_u32_e32 v16, vcc, s1, v0
	s_mov_b32 s1, 0xe000
	s_nop 0
	v_addc_co_u32_e32 v17, vcc, 0, v1, vcc
	v_add_co_u32_e32 v18, vcc, s1, v0
	s_mov_b32 s1, 0x12000
	s_nop 0
	v_addc_co_u32_e32 v19, vcc, 0, v1, vcc
	v_add_co_u32_e32 v20, vcc, s67, v0
	global_load_dword v2, v[6:7], off offset:-4096 nt
	global_load_dword v3, v[0:1], off nt
	v_addc_co_u32_e32 v21, vcc, 0, v1, vcc
	global_load_dword v4, v[8:9], off offset:-4096 nt
	global_load_dword v5, v[6:7], off nt
	s_nop 0
	global_load_dword v6, v[10:11], off offset:-4096 nt
	global_load_dword v7, v[8:9], off nt
	s_nop 0
	global_load_dword v8, v[12:13], off offset:-4096 nt
	global_load_dword v9, v[10:11], off nt
	s_nop 0
	global_load_dword v10, v[14:15], off offset:-4096 nt
	global_load_dword v11, v[12:13], off nt
	s_nop 0
	global_load_dword v12, v[16:17], off offset:-4096 nt
	global_load_dword v13, v[14:15], off nt
	s_nop 0
	global_load_dword v14, v[18:19], off offset:-4096 nt
	global_load_dword v15, v[16:17], off nt
	s_nop 0
	global_load_dword v16, v[20:21], off offset:-4096 nt
	global_load_dword v17, v[18:19], off nt
	v_add_co_u32_e32 v18, vcc, s1, v0
	s_mov_b32 s1, 0x14000
	s_nop 0
	v_addc_co_u32_e32 v19, vcc, 0, v1, vcc
	global_load_dword v22, v[18:19], off offset:-4096 nt
	global_load_dword v23, v[20:21], off nt
	v_add_co_u32_e32 v20, vcc, s1, v0
	s_mov_b32 s1, 0x16000
	s_nop 0
	v_addc_co_u32_e32 v21, vcc, 0, v1, vcc
	global_load_dword v24, v[20:21], off offset:-4096 nt
	global_load_dword v25, v[18:19], off nt
	v_add_co_u32_e32 v18, vcc, s1, v0
	s_mov_b32 s1, 0x18000
	s_nop 0
	v_addc_co_u32_e32 v19, vcc, 0, v1, vcc
	global_load_dword v26, v[18:19], off offset:-4096 nt
	global_load_dword v27, v[20:21], off nt
	v_add_co_u32_e32 v20, vcc, s1, v0
	s_mov_b32 s1, 0x1a000
	s_nop 0
	v_addc_co_u32_e32 v21, vcc, 0, v1, vcc
	global_load_dword v28, v[20:21], off offset:-4096 nt
	global_load_dword v29, v[18:19], off nt
	v_add_co_u32_e32 v18, vcc, s1, v0
	s_mov_b32 s1, 0x1c000
	s_nop 0
	v_addc_co_u32_e32 v19, vcc, 0, v1, vcc
	global_load_dword v30, v[18:19], off offset:-4096 nt
	global_load_dword v31, v[20:21], off nt
	v_add_co_u32_e32 v20, vcc, s1, v0
	s_mov_b32 s1, 0x1e000
	s_nop 0
	v_addc_co_u32_e32 v21, vcc, 0, v1, vcc
	global_load_dword v32, v[20:21], off offset:-4096 nt
	global_load_dword v33, v[18:19], off nt
	v_add_co_u32_e32 v18, vcc, s1, v0
	s_mov_b32 s1, 0x20000
	s_nop 0
	v_addc_co_u32_e32 v19, vcc, 0, v1, vcc
	global_load_dword v34, v[18:19], off offset:-4096 nt
	global_load_dword v35, v[20:21], off nt
	v_add_co_u32_e32 v20, vcc, s1, v0
	s_mov_b32 s1, 0x22000
	s_nop 0
	v_addc_co_u32_e32 v21, vcc, 0, v1, vcc
	global_load_dword v36, v[20:21], off offset:-4096 nt
	global_load_dword v37, v[18:19], off nt
	v_add_co_u32_e32 v18, vcc, s1, v0
	s_mov_b32 s1, 0x24000
	s_nop 0
	v_addc_co_u32_e32 v19, vcc, 0, v1, vcc
	global_load_dword v38, v[18:19], off offset:-4096 nt
	global_load_dword v39, v[20:21], off nt
	v_add_co_u32_e32 v20, vcc, s1, v0
	s_mov_b32 s1, 0x26000
	s_nop 0
	v_addc_co_u32_e32 v21, vcc, 0, v1, vcc
	global_load_dword v40, v[20:21], off offset:-4096 nt
	global_load_dword v41, v[18:19], off nt
	v_add_co_u32_e32 v18, vcc, s1, v0
	s_mov_b32 s1, 0x2a000
	s_nop 0
	v_addc_co_u32_e32 v19, vcc, 0, v1, vcc
	global_load_dword v42, v[18:19], off offset:-4096 nt
	global_load_dword v43, v[20:21], off nt
	v_add_co_u32_e32 v20, vcc, s95, v0
	s_nop 1
	v_addc_co_u32_e32 v21, vcc, 0, v1, vcc
	global_load_dword v44, v[20:21], off offset:-4096 nt
	global_load_dword v45, v[18:19], off nt
	v_add_co_u32_e32 v18, vcc, s1, v0
	s_mov_b32 s1, 0x2c000
	s_nop 0
	v_addc_co_u32_e32 v19, vcc, 0, v1, vcc
	global_load_dword v46, v[18:19], off offset:-4096 nt
	global_load_dword v47, v[20:21], off nt
	v_add_co_u32_e32 v20, vcc, s1, v0
	s_mov_b32 s1, 0x2e000
	s_nop 0
	v_addc_co_u32_e32 v21, vcc, 0, v1, vcc
	global_load_dword v48, v[20:21], off offset:-4096 nt
	global_load_dword v49, v[18:19], off nt
	v_add_co_u32_e32 v18, vcc, s1, v0
	s_mov_b32 s1, 0x30000
	s_nop 0
	v_addc_co_u32_e32 v19, vcc, 0, v1, vcc
	global_load_dword v50, v[18:19], off offset:-4096 nt
	global_load_dword v51, v[20:21], off nt
	v_add_co_u32_e32 v20, vcc, s1, v0
	s_mov_b32 s1, 0x32000
	s_nop 0
	v_addc_co_u32_e32 v21, vcc, 0, v1, vcc
	global_load_dword v52, v[20:21], off offset:-4096 nt
	global_load_dword v53, v[18:19], off nt
	v_add_co_u32_e32 v18, vcc, s1, v0
	s_mov_b32 s1, 0x34000
	s_nop 0
	v_addc_co_u32_e32 v19, vcc, 0, v1, vcc
	global_load_dword v54, v[18:19], off offset:-4096 nt
	global_load_dword v55, v[20:21], off nt
	v_add_co_u32_e32 v20, vcc, s1, v0
	s_mov_b32 s1, 0x36000
	s_nop 0
	v_addc_co_u32_e32 v21, vcc, 0, v1, vcc
	global_load_dword v56, v[20:21], off offset:-4096 nt
	global_load_dword v57, v[18:19], off nt
	v_add_co_u32_e32 v18, vcc, s1, v0
	s_mov_b32 s1, 0x38000
	s_nop 0
	v_addc_co_u32_e32 v19, vcc, 0, v1, vcc
	global_load_dword v58, v[18:19], off offset:-4096 nt
	global_load_dword v59, v[20:21], off nt
	v_add_co_u32_e32 v20, vcc, s1, v0
	s_mov_b32 s1, 0x3a000
	s_nop 0
	v_addc_co_u32_e32 v21, vcc, 0, v1, vcc
	global_load_dword v60, v[20:21], off offset:-4096 nt
	global_load_dword v61, v[18:19], off nt
	v_add_co_u32_e32 v18, vcc, s1, v0
	s_mov_b32 s1, 0x3c000
	s_nop 0
	v_addc_co_u32_e32 v19, vcc, 0, v1, vcc
	global_load_dword v62, v[18:19], off offset:-4096 nt
	global_load_dword v63, v[20:21], off nt
	v_add_co_u32_e32 v20, vcc, s1, v0
	s_mov_b32 s1, 0x3e000
	s_nop 0
	v_addc_co_u32_e32 v21, vcc, 0, v1, vcc
	global_load_dword v66, v[20:21], off offset:-4096 nt
	global_load_dword v67, v[18:19], off nt
	v_add_co_u32_e32 v18, vcc, s1, v0
	s_mov_b32 s1, 0x3f000
	s_nop 0
	v_addc_co_u32_e32 v19, vcc, 0, v1, vcc
	v_add_co_u32_e32 v0, vcc, s1, v0
	global_load_dword v68, v[18:19], off offset:-4096 nt
	s_nop 0
	global_load_dword v20, v[20:21], off nt
	v_addc_co_u32_e32 v1, vcc, 0, v1, vcc
	global_load_dword v21, v[0:1], off nt
	s_nop 0
	global_load_dword v18, v[18:19], off nt
	v_add_u32_e32 v19, s0, v148
	v_readlane_b32 s0, v253, 25
	v_readlane_b32 s1, v253, 26
	s_nop 1
	v_mov_b64_e32 v[0:1], s[0:1]
	v_mad_i64_i32 v[0:1], s[0:1], v19, s25, v[0:1]
	v_lshl_add_u64 v[64:65], s[92:93], 1, v[0:1]
	s_waitcnt vmcnt(62)
	v_cvt_pk_bf16_f32 v0, v3, v2
	s_waitcnt vmcnt(60)
	v_cvt_pk_bf16_f32 v1, v5, v4
	s_waitcnt vmcnt(58)
	v_cvt_pk_bf16_f32 v2, v7, v6
	s_waitcnt vmcnt(56)
	v_cvt_pk_bf16_f32 v3, v9, v8
	global_store_dwordx4 v[64:65], v[0:3], off
	s_mov_b64 s[0:1], 0
	s_waitcnt vmcnt(55)
	v_cvt_pk_bf16_f32 v0, v11, v10
	s_waitcnt vmcnt(53)
	v_cvt_pk_bf16_f32 v1, v13, v12
	s_waitcnt vmcnt(51)
	v_cvt_pk_bf16_f32 v2, v15, v14
	s_waitcnt vmcnt(49)
	v_cvt_pk_bf16_f32 v3, v17, v16
	global_store_dwordx4 v[64:65], v[0:3], off offset:16
	s_waitcnt vmcnt(48)
	s_nop 0
	v_cvt_pk_bf16_f32 v0, v23, v22
	s_waitcnt vmcnt(46)
	v_cvt_pk_bf16_f32 v1, v25, v24
	s_waitcnt vmcnt(44)
	v_cvt_pk_bf16_f32 v2, v27, v26
	s_waitcnt vmcnt(42)
	v_cvt_pk_bf16_f32 v3, v29, v28
	global_store_dwordx4 v[64:65], v[0:3], off offset:32
	s_waitcnt vmcnt(41)
	s_nop 0
	v_cvt_pk_bf16_f32 v0, v31, v30
	s_waitcnt vmcnt(39)
	v_cvt_pk_bf16_f32 v1, v33, v32
	s_waitcnt vmcnt(37)
	v_cvt_pk_bf16_f32 v2, v35, v34
	s_waitcnt vmcnt(35)
	v_cvt_pk_bf16_f32 v3, v37, v36
	global_store_dwordx4 v[64:65], v[0:3], off offset:48
	s_waitcnt vmcnt(34)
	s_nop 0
	v_cvt_pk_bf16_f32 v0, v39, v38
	s_waitcnt vmcnt(32)
	v_cvt_pk_bf16_f32 v1, v41, v40
	s_waitcnt vmcnt(30)
	v_cvt_pk_bf16_f32 v2, v43, v42
	s_waitcnt vmcnt(28)
	v_cvt_pk_bf16_f32 v3, v45, v44
	global_store_dwordx4 v[64:65], v[0:3], off offset:64
	s_waitcnt vmcnt(27)
	s_nop 0
	v_cvt_pk_bf16_f32 v0, v47, v46
	s_waitcnt vmcnt(25)
	v_cvt_pk_bf16_f32 v1, v49, v48
	s_waitcnt vmcnt(23)
	v_cvt_pk_bf16_f32 v2, v51, v50
	s_waitcnt vmcnt(21)
	v_cvt_pk_bf16_f32 v3, v53, v52
	global_store_dwordx4 v[64:65], v[0:3], off offset:80
	s_waitcnt vmcnt(20)
	s_nop 0
	v_cvt_pk_bf16_f32 v0, v55, v54
	s_waitcnt vmcnt(18)
	v_cvt_pk_bf16_f32 v1, v57, v56
	s_waitcnt vmcnt(16)
	v_cvt_pk_bf16_f32 v2, v59, v58
	s_waitcnt vmcnt(14)
	v_cvt_pk_bf16_f32 v3, v61, v60
	global_store_dwordx4 v[64:65], v[0:3], off offset:96
	s_waitcnt vmcnt(13)
	s_nop 0
	v_cvt_pk_bf16_f32 v0, v63, v62
	s_waitcnt vmcnt(11)
	v_cvt_pk_bf16_f32 v1, v67, v66
	s_waitcnt vmcnt(9)
	v_cvt_pk_bf16_f32 v2, v20, v68
	s_waitcnt vmcnt(7)
	v_cvt_pk_bf16_f32 v3, v18, v21
.LBB0_488:
	s_andn2_b64 vcc, exec, s[0:1]
	s_cbranch_vccnz .LBB0_492
	s_add_i32 s0, s12, 0xf980
	s_and_b32 s1, s0, 0xffff
	s_mul_i32 s1, s1, 0xba2f
	s_lshr_b32 s20, s1, 16
	s_lshr_b32 s1, s1, 22
	s_mulk_i32 s1, 0x58
	s_sub_i32 s1, s0, s1
	s_and_b32 s0, s20, 0xffc0
	v_readlane_b32 s36, v253, 41
	s_mul_i32 s20, s0, 0x5800
	v_readlane_b32 s50, v253, 55
	v_readlane_b32 s51, v253, 56
	s_add_u32 s20, s50, s20
	s_addc_u32 s27, s51, 0
	s_lshl_b32 s28, s1, 8
	s_and_b32 s28, s28, 0x3ff00
	s_add_u32 s28, s20, s28
	s_addc_u32 s29, s27, 0
	v_lshl_add_u64 v[64:65], v[148:149], 2, s[28:29]
	s_movk_i32 s20, 0x5000
	v_add_co_u32_e32 v2, vcc, s20, v64
	s_mov_b32 s20, 0xb000
	s_nop 0
	v_addc_co_u32_e32 v3, vcc, 0, v65, vcc
	global_load_dword v1, v[2:3], off offset:2048 nt
	v_add_co_u32_e32 v2, vcc, s20, v64
	s_mov_b32 s20, 0x16000
	s_nop 0
	v_addc_co_u32_e32 v3, vcc, 0, v65, vcc
	v_add_co_u32_e32 v4, vcc, s67, v64
	global_load_dword v0, v[64:65], off nt
	s_nop 0
	v_addc_co_u32_e32 v5, vcc, 0, v65, vcc
	global_load_dword v2, v[2:3], off nt
	v_readlane_b32 s28, v253, 39
	global_load_dword v3, v[4:5], off offset:2048 nt
	v_add_co_u32_e32 v4, vcc, s20, v64
	s_mov_b32 s20, 0x1b000
	s_nop 0
	v_addc_co_u32_e32 v5, vcc, 0, v65, vcc
	v_add_co_u32_e32 v6, vcc, s20, v64
	s_mov_b32 s20, 0x21000
	s_nop 0
	v_addc_co_u32_e32 v7, vcc, 0, v65, vcc
	global_load_dword v4, v[4:5], off nt
	v_readlane_b32 s29, v253, 40
	global_load_dword v5, v[6:7], off offset:2048 nt
	v_add_co_u32_e32 v6, vcc, s20, v64
	s_mov_b32 s20, 0x26000
	s_nop 0
	v_addc_co_u32_e32 v7, vcc, 0, v65, vcc
	v_add_co_u32_e32 v8, vcc, s20, v64
	s_mov_b32 s20, 0x2c000
	s_nop 0
	v_addc_co_u32_e32 v9, vcc, 0, v65, vcc
	global_load_dword v6, v[6:7], off nt
	v_readlane_b32 s48, v253, 53
	global_load_dword v7, v[8:9], off offset:2048 nt
	v_add_co_u32_e32 v8, vcc, s20, v64
	s_mov_b32 s20, 0x31000
	s_nop 0
	v_addc_co_u32_e32 v9, vcc, 0, v65, vcc
	v_add_co_u32_e32 v10, vcc, s20, v64
	s_mov_b32 s20, 0x37000
	s_nop 0
	v_addc_co_u32_e32 v11, vcc, 0, v65, vcc
	global_load_dword v8, v[8:9], off nt
	v_readlane_b32 s49, v253, 54
	global_load_dword v9, v[10:11], off offset:2048 nt
	v_add_co_u32_e32 v10, vcc, s20, v64
	s_mov_b32 s20, 0x3c000
	s_nop 0
	v_addc_co_u32_e32 v11, vcc, 0, v65, vcc
	v_add_co_u32_e32 v12, vcc, s20, v64
	s_mov_b32 s20, 0x42000
	s_nop 0
	v_addc_co_u32_e32 v13, vcc, 0, v65, vcc
	global_load_dword v10, v[10:11], off nt
	v_readlane_b32 s37, v253, 42
	global_load_dword v11, v[12:13], off offset:2048 nt
	v_add_co_u32_e32 v12, vcc, s20, v64
	s_mov_b32 s20, 0x47000
	s_nop 0
	v_addc_co_u32_e32 v13, vcc, 0, v65, vcc
	v_add_co_u32_e32 v14, vcc, s20, v64
	s_mov_b32 s20, 0x4d000
	s_nop 0
	v_addc_co_u32_e32 v15, vcc, 0, v65, vcc
	global_load_dword v12, v[12:13], off nt
	v_readlane_b32 s38, v253, 43
	global_load_dword v13, v[14:15], off offset:2048 nt
	v_add_co_u32_e32 v14, vcc, s20, v64
	s_mov_b32 s20, 0x52000
	s_nop 0
	v_addc_co_u32_e32 v15, vcc, 0, v65, vcc
	s_waitcnt vmcnt(19)
	v_add_co_u32_e32 v16, vcc, s20, v64
	s_mov_b32 s20, 0x58000
	s_nop 0
	v_addc_co_u32_e32 v17, vcc, 0, v65, vcc
	global_load_dword v14, v[14:15], off nt
	v_readlane_b32 s39, v253, 44
	global_load_dword v15, v[16:17], off offset:2048 nt
	v_add_co_u32_e32 v16, vcc, s20, v64
	s_mov_b32 s20, 0x5d000
	s_nop 0
	v_addc_co_u32_e32 v17, vcc, 0, v65, vcc
	v_add_co_u32_e32 v18, vcc, s20, v64
	s_mov_b32 s20, 0x63000
	s_nop 0
	v_addc_co_u32_e32 v19, vcc, 0, v65, vcc
	global_load_dword v16, v[16:17], off nt
	v_readlane_b32 s40, v253, 45
	global_load_dword v17, v[18:19], off offset:2048 nt
	v_add_co_u32_e32 v18, vcc, s20, v64
	s_mov_b32 s20, 0x68000
	s_nop 0
	v_addc_co_u32_e32 v19, vcc, 0, v65, vcc
	v_add_co_u32_e32 v20, vcc, s20, v64
	s_mov_b32 s20, 0x6e000
	s_nop 0
	v_addc_co_u32_e32 v21, vcc, 0, v65, vcc
	global_load_dword v18, v[18:19], off nt
	v_readlane_b32 s41, v253, 46
	global_load_dword v19, v[20:21], off offset:2048 nt
	v_add_co_u32_e32 v20, vcc, s20, v64
	s_mov_b32 s20, 0x73000
	s_nop 0
	v_addc_co_u32_e32 v21, vcc, 0, v65, vcc
	v_add_co_u32_e32 v22, vcc, s20, v64
	s_mov_b32 s20, 0x79000
	s_nop 0
	v_addc_co_u32_e32 v23, vcc, 0, v65, vcc
	global_load_dword v20, v[20:21], off nt
	v_readlane_b32 s42, v253, 47
	global_load_dword v21, v[22:23], off offset:2048 nt
	v_add_co_u32_e32 v22, vcc, s20, v64
	s_mov_b32 s20, 0x7e000
	s_nop 0
	v_addc_co_u32_e32 v23, vcc, 0, v65, vcc
	v_add_co_u32_e32 v24, vcc, s20, v64
	s_mov_b32 s20, 0x84000
	s_nop 0
	v_addc_co_u32_e32 v25, vcc, 0, v65, vcc
	global_load_dword v22, v[22:23], off nt
	v_readlane_b32 s43, v253, 48
	global_load_dword v23, v[24:25], off offset:2048 nt
	v_add_co_u32_e32 v24, vcc, s20, v64
	s_mov_b32 s20, 0x89000
	s_nop 0
	v_addc_co_u32_e32 v25, vcc, 0, v65, vcc
	v_add_co_u32_e32 v26, vcc, s20, v64
	s_mov_b32 s20, 0x8f000
	s_nop 0
	v_addc_co_u32_e32 v27, vcc, 0, v65, vcc
	global_load_dword v24, v[24:25], off nt
	v_readlane_b32 s44, v253, 49
	global_load_dword v25, v[26:27], off offset:2048 nt
	v_add_co_u32_e32 v26, vcc, s20, v64
	s_mov_b32 s20, 0x94000
	s_nop 0
	v_addc_co_u32_e32 v27, vcc, 0, v65, vcc
	s_waitcnt vmcnt(30)
	v_add_co_u32_e32 v28, vcc, s20, v64
	s_mov_b32 s20, 0x9a000
	s_nop 0
	v_addc_co_u32_e32 v29, vcc, 0, v65, vcc
	global_load_dword v26, v[26:27], off nt
	v_readlane_b32 s45, v253, 50
	global_load_dword v27, v[28:29], off offset:2048 nt
	v_add_co_u32_e32 v28, vcc, s20, v64
	s_mov_b32 s20, 0x9f000
	s_nop 0
	v_addc_co_u32_e32 v29, vcc, 0, v65, vcc
	v_add_co_u32_e32 v30, vcc, s20, v64
	s_mov_b32 s20, 0xa5000
	s_nop 0
	v_addc_co_u32_e32 v31, vcc, 0, v65, vcc
	global_load_dword v28, v[28:29], off nt
	v_readlane_b32 s46, v253, 51
	global_load_dword v29, v[30:31], off offset:2048 nt
	v_add_co_u32_e32 v30, vcc, s20, v64
	s_mov_b32 s20, 0xaa000
	s_nop 0
	v_addc_co_u32_e32 v31, vcc, 0, v65, vcc
	s_waitcnt vmcnt(31)
	v_add_co_u32_e32 v32, vcc, s20, v64
	s_mov_b32 s20, 0xb0000
	s_nop 0
	v_addc_co_u32_e32 v33, vcc, 0, v65, vcc
	global_load_dword v30, v[30:31], off nt
	v_readlane_b32 s47, v253, 52
	global_load_dword v31, v[32:33], off offset:2048 nt
	v_add_co_u32_e32 v32, vcc, s20, v64
	s_mov_b32 s20, 0xb5000
	s_nop 0
	v_addc_co_u32_e32 v33, vcc, 0, v65, vcc
	v_add_co_u32_e32 v34, vcc, s20, v64
	s_mov_b32 s20, 0xbb000
	s_nop 0
	v_addc_co_u32_e32 v35, vcc, 0, v65, vcc
	global_load_dword v32, v[32:33], off nt
	s_nop 0
	global_load_dword v33, v[34:35], off offset:2048 nt
	v_add_co_u32_e32 v34, vcc, s20, v64
	s_mov_b32 s20, 0xc0000
	s_nop 0
	v_addc_co_u32_e32 v35, vcc, 0, v65, vcc
	s_waitcnt vmcnt(34)
	v_add_co_u32_e32 v36, vcc, s20, v64
	s_mov_b32 s20, 0xc6000
	s_nop 0
	v_addc_co_u32_e32 v37, vcc, 0, v65, vcc
	global_load_dword v34, v[34:35], off nt
	s_nop 0
	global_load_dword v35, v[36:37], off offset:2048 nt
	v_add_co_u32_e32 v36, vcc, s20, v64
	s_mov_b32 s20, 0xcb000
	s_nop 0
	v_addc_co_u32_e32 v37, vcc, 0, v65, vcc
	v_add_co_u32_e32 v38, vcc, s20, v64
	s_mov_b32 s20, 0xd1000
	s_nop 0
	v_addc_co_u32_e32 v39, vcc, 0, v65, vcc
	global_load_dword v36, v[36:37], off nt
	s_nop 0
	global_load_dword v37, v[38:39], off offset:2048 nt
	v_add_co_u32_e32 v38, vcc, s20, v64
	s_mov_b32 s20, 0xd6000
	s_nop 0
	v_addc_co_u32_e32 v39, vcc, 0, v65, vcc
	v_add_co_u32_e32 v40, vcc, s20, v64
	s_mov_b32 s20, 0xdc000
	s_nop 0
	v_addc_co_u32_e32 v41, vcc, 0, v65, vcc
	global_load_dword v38, v[38:39], off nt
	s_nop 0
	global_load_dword v39, v[40:41], off offset:2048 nt
	v_add_co_u32_e32 v40, vcc, s20, v64
	s_mov_b32 s20, 0xe1000
	s_nop 0
	v_addc_co_u32_e32 v41, vcc, 0, v65, vcc
	v_add_co_u32_e32 v42, vcc, s20, v64
	s_mov_b32 s20, 0xe7000
	s_nop 0
	v_addc_co_u32_e32 v43, vcc, 0, v65, vcc
	global_load_dword v40, v[40:41], off nt
	s_nop 0
	global_load_dword v41, v[42:43], off offset:2048 nt
	v_add_co_u32_e32 v42, vcc, s20, v64
	s_mov_b32 s20, 0xec000
	s_nop 0
	v_addc_co_u32_e32 v43, vcc, 0, v65, vcc
	v_add_co_u32_e32 v44, vcc, s20, v64
	s_mov_b32 s20, 0xf2000
	s_nop 0
	v_addc_co_u32_e32 v45, vcc, 0, v65, vcc
	global_load_dword v42, v[42:43], off nt
	s_nop 0
	global_load_dword v43, v[44:45], off offset:2048 nt
	v_add_co_u32_e32 v44, vcc, s20, v64
	s_mov_b32 s20, 0xf7000
	s_nop 0
	v_addc_co_u32_e32 v45, vcc, 0, v65, vcc
	v_add_co_u32_e32 v46, vcc, s20, v64
	s_mov_b32 s20, 0xfd000
	s_nop 0
	v_addc_co_u32_e32 v47, vcc, 0, v65, vcc
	global_load_dword v44, v[44:45], off nt
	s_nop 0
	global_load_dword v45, v[46:47], off offset:2048 nt
	v_add_co_u32_e32 v46, vcc, s20, v64
	s_mov_b32 s20, 0x102000
	s_nop 0
	v_addc_co_u32_e32 v47, vcc, 0, v65, vcc
	v_add_co_u32_e32 v48, vcc, s20, v64
	s_mov_b32 s20, 0x108000
	s_nop 0
	v_addc_co_u32_e32 v49, vcc, 0, v65, vcc
	global_load_dword v46, v[46:47], off nt
	s_nop 0
	global_load_dword v47, v[48:49], off offset:2048 nt
	v_add_co_u32_e32 v48, vcc, s20, v64
	s_mov_b32 s20, 0x10d000
	s_nop 0
	v_addc_co_u32_e32 v49, vcc, 0, v65, vcc
	v_add_co_u32_e32 v50, vcc, s20, v64
	s_mov_b32 s20, 0x113000
	s_nop 0
	v_addc_co_u32_e32 v51, vcc, 0, v65, vcc
	global_load_dword v48, v[48:49], off nt
	s_nop 0
	global_load_dword v49, v[50:51], off offset:2048 nt
	v_add_co_u32_e32 v50, vcc, s20, v64
	s_mov_b32 s20, 0x118000
	s_nop 0
	v_addc_co_u32_e32 v51, vcc, 0, v65, vcc
	v_add_co_u32_e32 v52, vcc, s20, v64
	s_mov_b32 s20, 0x11e000
	s_nop 0
	v_addc_co_u32_e32 v53, vcc, 0, v65, vcc
	global_load_dword v50, v[50:51], off nt
	s_nop 0
	global_load_dword v51, v[52:53], off offset:2048 nt
	v_add_co_u32_e32 v52, vcc, s20, v64
	s_mov_b32 s20, 0x123000
	s_nop 0
	v_addc_co_u32_e32 v53, vcc, 0, v65, vcc
	v_add_co_u32_e32 v54, vcc, s20, v64
	s_mov_b32 s20, 0x129000
	s_nop 0
	v_addc_co_u32_e32 v55, vcc, 0, v65, vcc
	global_load_dword v52, v[52:53], off nt
	s_nop 0
	global_load_dword v53, v[54:55], off offset:2048 nt
	v_add_co_u32_e32 v54, vcc, s20, v64
	s_mov_b32 s20, 0x12e000
	s_nop 0
	v_addc_co_u32_e32 v55, vcc, 0, v65, vcc
	v_add_co_u32_e32 v56, vcc, s20, v64
	s_mov_b32 s20, 0x134000
	s_nop 0
	v_addc_co_u32_e32 v57, vcc, 0, v65, vcc
	global_load_dword v54, v[54:55], off nt
	s_nop 0
	global_load_dword v55, v[56:57], off offset:2048 nt
	v_add_co_u32_e32 v56, vcc, s20, v64
	s_mov_b32 s20, 0x139000
	s_nop 0
	v_addc_co_u32_e32 v57, vcc, 0, v65, vcc
	v_add_co_u32_e32 v58, vcc, s20, v64
	s_mov_b32 s20, 0x13f000
	s_nop 0
	v_addc_co_u32_e32 v59, vcc, 0, v65, vcc
	global_load_dword v56, v[56:57], off nt
	s_nop 0
	global_load_dword v57, v[58:59], off offset:2048 nt
	v_add_co_u32_e32 v58, vcc, s20, v64
	s_mov_b32 s20, 0x144000
	s_nop 0
	v_addc_co_u32_e32 v59, vcc, 0, v65, vcc
	v_add_co_u32_e32 v60, vcc, s20, v64
	s_mov_b32 s20, 0x14a000
	s_nop 0
	v_addc_co_u32_e32 v61, vcc, 0, v65, vcc
	global_load_dword v58, v[58:59], off nt
	s_nop 0
	global_load_dword v59, v[60:61], off offset:2048 nt
	v_add_co_u32_e32 v60, vcc, s20, v64
	s_nop 1
	v_addc_co_u32_e32 v61, vcc, 0, v65, vcc
	v_add_co_u32_e32 v62, vcc, 0x14f000, v64
	global_load_dword v60, v[60:61], off nt
	s_nop 0
	v_addc_co_u32_e32 v63, vcc, 0, v65, vcc
	global_load_dword v61, v[62:63], off offset:2048 nt
	v_add_co_u32_e32 v62, vcc, 0x155000, v64
	s_nop 1
	v_addc_co_u32_e32 v63, vcc, 0, v65, vcc
	v_add_co_u32_e32 v64, vcc, 0x15a000, v64
	global_load_dword v62, v[62:63], off nt
	s_nop 0
	v_addc_co_u32_e32 v65, vcc, 0, v65, vcc
	global_load_dword v63, v[64:65], off offset:2048 nt
	s_andn2_b64 vcc, exec, s[28:29]
	s_cbranch_vccnz .LBB0_491
	s_lshl_b32 s20, s0, 2
	v_mov_b32_e32 v80, s20
	global_load_dwordx4 v[64:67], v80, s[48:49] offset:48
	global_load_dwordx4 v[68:71], v80, s[48:49] offset:32
	global_load_dwordx4 v[72:75], v80, s[48:49] offset:16
	global_load_dwordx4 v[76:79], v80, s[48:49]
	s_waitcnt vmcnt(3)
	v_pk_mul_f32 v[12:13], v[12:13], v[64:65]
	s_waitcnt vmcnt(2)
	v_pk_mul_f32 v[8:9], v[8:9], v[68:69]
	s_waitcnt vmcnt(1)
	v_pk_mul_f32 v[4:5], v[4:5], v[72:73]
	s_waitcnt vmcnt(0)
	v_pk_mul_f32 v[0:1], v[0:1], v[76:77]
	v_pk_mul_f32 v[2:3], v[2:3], v[78:79]
	v_pk_mul_f32 v[6:7], v[6:7], v[74:75]
	v_pk_mul_f32 v[10:11], v[10:11], v[70:71]
	v_pk_mul_f32 v[14:15], v[14:15], v[66:67]
	global_load_dwordx4 v[64:67], v80, s[48:49] offset:112
	global_load_dwordx4 v[68:71], v80, s[48:49] offset:96
	global_load_dwordx4 v[72:75], v80, s[48:49] offset:80
	global_load_dwordx4 v[76:79], v80, s[48:49] offset:64
	s_waitcnt vmcnt(3)
	v_pk_mul_f32 v[28:29], v[28:29], v[64:65]
	s_waitcnt vmcnt(2)
	v_pk_mul_f32 v[24:25], v[24:25], v[68:69]
	s_waitcnt vmcnt(1)
	v_pk_mul_f32 v[20:21], v[20:21], v[72:73]
	s_waitcnt vmcnt(0)
	v_pk_mul_f32 v[16:17], v[16:17], v[76:77]
	v_pk_mul_f32 v[18:19], v[18:19], v[78:79]
	v_pk_mul_f32 v[22:23], v[22:23], v[74:75]
	v_pk_mul_f32 v[26:27], v[26:27], v[70:71]
	v_pk_mul_f32 v[30:31], v[30:31], v[66:67]
	global_load_dwordx4 v[64:67], v80, s[48:49] offset:176
	global_load_dwordx4 v[68:71], v80, s[48:49] offset:160
	global_load_dwordx4 v[72:75], v80, s[48:49] offset:144
	global_load_dwordx4 v[76:79], v80, s[48:49] offset:128
	s_waitcnt vmcnt(3)
	v_pk_mul_f32 v[44:45], v[44:45], v[64:65]
	s_waitcnt vmcnt(2)
	v_pk_mul_f32 v[40:41], v[40:41], v[68:69]
	s_waitcnt vmcnt(1)
	v_pk_mul_f32 v[36:37], v[36:37], v[72:73]
	s_waitcnt vmcnt(0)
	v_pk_mul_f32 v[32:33], v[32:33], v[76:77]
	v_pk_mul_f32 v[34:35], v[34:35], v[78:79]
	v_pk_mul_f32 v[38:39], v[38:39], v[74:75]
	v_pk_mul_f32 v[42:43], v[42:43], v[70:71]
	v_pk_mul_f32 v[46:47], v[46:47], v[66:67]
	global_load_dwordx4 v[64:67], v80, s[48:49] offset:240
	global_load_dwordx4 v[68:71], v80, s[48:49] offset:224
	global_load_dwordx4 v[72:75], v80, s[48:49] offset:208
	global_load_dwordx4 v[76:79], v80, s[48:49] offset:192
	s_waitcnt vmcnt(3)
	v_pk_mul_f32 v[60:61], v[60:61], v[64:65]
	s_waitcnt vmcnt(2)
	v_pk_mul_f32 v[56:57], v[56:57], v[68:69]
	s_waitcnt vmcnt(1)
	v_pk_mul_f32 v[52:53], v[52:53], v[72:73]
	s_waitcnt vmcnt(0)
	v_pk_mul_f32 v[48:49], v[48:49], v[76:77]
	v_pk_mul_f32 v[50:51], v[50:51], v[78:79]
	v_pk_mul_f32 v[54:55], v[54:55], v[74:75]
	v_pk_mul_f32 v[58:59], v[58:59], v[70:71]
	v_pk_mul_f32 v[62:63], v[62:63], v[66:67]

.LBB0_493:
	s_andn2_b64 vcc, exec, s[0:1]
	s_cbranch_vccnz .LBB0_495
	s_and_b32 s0, s6, 0x3c0
	s_xor_b32 s0, s0, 0x200
	v_readlane_b32 s36, v253, 41
	s_and_b32 s1, s4, 0x3c0
	s_lshl_b32 s20, s0, 12
	v_readlane_b32 s46, v253, 51
	v_readlane_b32 s47, v253, 52
	s_add_u32 s20, s46, s20
	s_addc_u32 s27, s47, 0
	s_lshl_b32 s28, s1, 2
	s_add_u32 s28, s20, s28
	s_addc_u32 s29, s27, 0
	v_lshl_add_u64 v[0:1], v[148:149], 2, s[28:29]
	v_add_co_u32_e32 v6, vcc, s11, v0
	s_movk_i32 s20, 0x4000
	s_nop 0
	v_addc_co_u32_e32 v7, vcc, 0, v1, vcc
	v_add_co_u32_e32 v8, vcc, s20, v0
	s_movk_i32 s20, 0x6000
	s_nop 0
	v_addc_co_u32_e32 v9, vcc, 0, v1, vcc
	v_add_co_u32_e32 v10, vcc, s20, v0
	s_mov_b32 s20, 0x8000
	s_nop 0
	v_addc_co_u32_e32 v11, vcc, 0, v1, vcc
	v_add_co_u32_e32 v12, vcc, s20, v0
	s_mov_b32 s20, 0xa000
	s_nop 0
	v_addc_co_u32_e32 v13, vcc, 0, v1, vcc
	v_add_co_u32_e32 v14, vcc, s20, v0
	s_mov_b32 s20, 0xc000
	s_nop 0
	v_addc_co_u32_e32 v15, vcc, 0, v1, vcc
	s_waitcnt vmcnt(5)
	v_add_co_u32_e32 v16, vcc, s20, v0
	s_mov_b32 s20, 0xe000
	s_nop 0
	v_addc_co_u32_e32 v17, vcc, 0, v1, vcc
	v_add_co_u32_e32 v18, vcc, s20, v0
	s_mov_b32 s20, 0x12000
	s_nop 0
	v_addc_co_u32_e32 v19, vcc, 0, v1, vcc
	v_add_co_u32_e32 v20, vcc, s67, v0
	global_load_dword v2, v[6:7], off offset:-4096 nt
	global_load_dword v3, v[0:1], off nt
	v_addc_co_u32_e32 v21, vcc, 0, v1, vcc
	global_load_dword v4, v[8:9], off offset:-4096 nt
	global_load_dword v5, v[6:7], off nt
	s_nop 0
	global_load_dword v6, v[10:11], off offset:-4096 nt
	global_load_dword v7, v[8:9], off nt
	s_nop 0
	global_load_dword v8, v[12:13], off offset:-4096 nt
	global_load_dword v9, v[10:11], off nt
	s_nop 0
	global_load_dword v10, v[14:15], off offset:-4096 nt
	global_load_dword v11, v[12:13], off nt
	s_nop 0
	global_load_dword v12, v[16:17], off offset:-4096 nt
	global_load_dword v13, v[14:15], off nt
	s_nop 0
	global_load_dword v14, v[18:19], off offset:-4096 nt
	global_load_dword v15, v[16:17], off nt
	s_nop 0
	global_load_dword v16, v[20:21], off offset:-4096 nt
	global_load_dword v17, v[18:19], off nt
	v_add_co_u32_e32 v18, vcc, s20, v0
	s_mov_b32 s20, 0x14000
	s_nop 0
	v_addc_co_u32_e32 v19, vcc, 0, v1, vcc
	global_load_dword v22, v[18:19], off offset:-4096 nt
	global_load_dword v23, v[20:21], off nt
	v_add_co_u32_e32 v20, vcc, s20, v0
	s_mov_b32 s20, 0x16000
	s_nop 0
	v_addc_co_u32_e32 v21, vcc, 0, v1, vcc
	global_load_dword v24, v[20:21], off offset:-4096 nt
	global_load_dword v25, v[18:19], off nt
	v_add_co_u32_e32 v18, vcc, s20, v0
	s_mov_b32 s20, 0x18000
	s_nop 0
	v_addc_co_u32_e32 v19, vcc, 0, v1, vcc
	global_load_dword v26, v[18:19], off offset:-4096 nt
	global_load_dword v27, v[20:21], off nt
	v_add_co_u32_e32 v20, vcc, s20, v0
	s_mov_b32 s20, 0x1a000
	s_nop 0
	v_addc_co_u32_e32 v21, vcc, 0, v1, vcc
	global_load_dword v28, v[20:21], off offset:-4096 nt
	global_load_dword v29, v[18:19], off nt
	v_add_co_u32_e32 v18, vcc, s20, v0
	s_mov_b32 s20, 0x1c000
	s_nop 0
	v_addc_co_u32_e32 v19, vcc, 0, v1, vcc
	global_load_dword v30, v[18:19], off offset:-4096 nt
	global_load_dword v31, v[20:21], off nt
	v_add_co_u32_e32 v20, vcc, s20, v0
	s_mov_b32 s20, 0x1e000
	s_nop 0
	v_addc_co_u32_e32 v21, vcc, 0, v1, vcc
	global_load_dword v32, v[20:21], off offset:-4096 nt
	global_load_dword v33, v[18:19], off nt
	v_add_co_u32_e32 v18, vcc, s20, v0
	s_mov_b32 s20, 0x20000
	s_nop 0
	v_addc_co_u32_e32 v19, vcc, 0, v1, vcc
	global_load_dword v34, v[18:19], off offset:-4096 nt
	global_load_dword v35, v[20:21], off nt
	v_add_co_u32_e32 v20, vcc, s20, v0
	s_mov_b32 s20, 0x22000
	s_nop 0
	v_addc_co_u32_e32 v21, vcc, 0, v1, vcc
	global_load_dword v36, v[20:21], off offset:-4096 nt
	global_load_dword v37, v[18:19], off nt
	v_add_co_u32_e32 v18, vcc, s20, v0
	s_mov_b32 s20, 0x24000
	s_nop 0
	v_addc_co_u32_e32 v19, vcc, 0, v1, vcc
	global_load_dword v38, v[18:19], off offset:-4096 nt
	global_load_dword v39, v[20:21], off nt
	v_add_co_u32_e32 v20, vcc, s20, v0
	s_mov_b32 s20, 0x26000
	s_nop 0
	v_addc_co_u32_e32 v21, vcc, 0, v1, vcc
	global_load_dword v40, v[20:21], off offset:-4096 nt
	global_load_dword v41, v[18:19], off nt
	v_add_co_u32_e32 v18, vcc, s20, v0
	s_mov_b32 s20, 0x2a000
	s_nop 0
	v_addc_co_u32_e32 v19, vcc, 0, v1, vcc
	global_load_dword v42, v[18:19], off offset:-4096 nt
	global_load_dword v43, v[20:21], off nt
	v_add_co_u32_e32 v20, vcc, s95, v0
	v_readlane_b32 s28, v253, 29
	s_nop 0
	v_addc_co_u32_e32 v21, vcc, 0, v1, vcc
	global_load_dword v44, v[20:21], off offset:-4096 nt
	global_load_dword v45, v[18:19], off nt
	v_add_co_u32_e32 v18, vcc, s20, v0
	s_mov_b32 s20, 0x2c000
	s_nop 0
	v_addc_co_u32_e32 v19, vcc, 0, v1, vcc
	global_load_dword v46, v[18:19], off offset:-4096 nt
	global_load_dword v47, v[20:21], off nt
	v_add_co_u32_e32 v20, vcc, s20, v0
	s_mov_b32 s20, 0x2e000
	s_nop 0
	v_addc_co_u32_e32 v21, vcc, 0, v1, vcc
	global_load_dword v48, v[20:21], off offset:-4096 nt
	global_load_dword v49, v[18:19], off nt
	v_add_co_u32_e32 v18, vcc, s20, v0
	s_mov_b32 s20, 0x30000
	s_nop 0
	v_addc_co_u32_e32 v19, vcc, 0, v1, vcc
	global_load_dword v50, v[18:19], off offset:-4096 nt
	global_load_dword v51, v[20:21], off nt
	v_add_co_u32_e32 v20, vcc, s20, v0
	s_mov_b32 s20, 0x32000
	s_nop 0
	v_addc_co_u32_e32 v21, vcc, 0, v1, vcc
	global_load_dword v52, v[20:21], off offset:-4096 nt
	global_load_dword v53, v[18:19], off nt
	v_add_co_u32_e32 v18, vcc, s20, v0
	s_mov_b32 s20, 0x34000
	s_nop 0
	v_addc_co_u32_e32 v19, vcc, 0, v1, vcc
	global_load_dword v54, v[18:19], off offset:-4096 nt
	global_load_dword v55, v[20:21], off nt
	v_add_co_u32_e32 v20, vcc, s20, v0
	s_mov_b32 s20, 0x36000
	s_nop 0
	v_addc_co_u32_e32 v21, vcc, 0, v1, vcc
	global_load_dword v56, v[20:21], off offset:-4096 nt
	global_load_dword v57, v[18:19], off nt
	v_add_co_u32_e32 v18, vcc, s20, v0
	s_mov_b32 s20, 0x38000
	s_nop 0
	v_addc_co_u32_e32 v19, vcc, 0, v1, vcc
	global_load_dword v58, v[18:19], off offset:-4096 nt
	global_load_dword v59, v[20:21], off nt
	v_add_co_u32_e32 v20, vcc, s20, v0
	s_mov_b32 s20, 0x3a000
	s_nop 0
	v_addc_co_u32_e32 v21, vcc, 0, v1, vcc
	global_load_dword v60, v[20:21], off offset:-4096 nt
	global_load_dword v61, v[18:19], off nt
	v_add_co_u32_e32 v18, vcc, s20, v0
	s_mov_b32 s20, 0x3c000
	s_nop 0
	v_addc_co_u32_e32 v19, vcc, 0, v1, vcc
	global_load_dword v62, v[18:19], off offset:-4096 nt
	global_load_dword v63, v[20:21], off nt
	v_add_co_u32_e32 v20, vcc, s20, v0
	s_mov_b32 s20, 0x3e000
	s_nop 0
	v_addc_co_u32_e32 v21, vcc, 0, v1, vcc
	global_load_dword v66, v[20:21], off offset:-4096 nt
	global_load_dword v67, v[18:19], off nt
	v_add_co_u32_e32 v18, vcc, s20, v0
	s_mov_b32 s20, 0x3f000
	s_nop 0
	v_addc_co_u32_e32 v19, vcc, 0, v1, vcc
	v_add_co_u32_e32 v0, vcc, s20, v0
	global_load_dword v68, v[18:19], off offset:-4096 nt
	s_nop 0
	global_load_dword v20, v[20:21], off nt
	v_addc_co_u32_e32 v1, vcc, 0, v1, vcc
	global_load_dword v21, v[0:1], off nt
	s_nop 0
	global_load_dword v18, v[18:19], off nt
	v_add_u32_e32 v0, s1, v148
	v_ashrrev_i32_e32 v1, 31, v0
	v_lshlrev_b64 v[0:1], 11, v[0:1]
	v_readlane_b32 s29, v253, 30
	s_lshl_b32 s92, s0, 1
	v_readlane_b32 s37, v253, 42
	v_lshl_add_u64 v[0:1], s[28:29], 0, v[0:1]
	v_lshl_add_u64 v[64:65], v[0:1], 0, s[92:93]
	s_waitcnt vmcnt(62)
	v_cvt_pk_bf16_f32 v0, v3, v2
	s_waitcnt vmcnt(60)
	v_cvt_pk_bf16_f32 v1, v5, v4
	s_waitcnt vmcnt(58)
	v_cvt_pk_bf16_f32 v2, v7, v6
	s_waitcnt vmcnt(56)
	v_cvt_pk_bf16_f32 v3, v9, v8
	global_store_dwordx4 v[64:65], v[0:3], off
	v_readlane_b32 s38, v253, 43
	v_readlane_b32 s39, v253, 44
	s_waitcnt vmcnt(55)
	v_cvt_pk_bf16_f32 v0, v11, v10
	s_waitcnt vmcnt(53)
	v_cvt_pk_bf16_f32 v1, v13, v12
	s_waitcnt vmcnt(51)
	v_cvt_pk_bf16_f32 v2, v15, v14
	s_waitcnt vmcnt(49)
	v_cvt_pk_bf16_f32 v3, v17, v16
	global_store_dwordx4 v[64:65], v[0:3], off offset:16
	v_readlane_b32 s40, v253, 45
	v_readlane_b32 s41, v253, 46
	s_waitcnt vmcnt(48)
	v_cvt_pk_bf16_f32 v0, v23, v22
	s_waitcnt vmcnt(46)
	v_cvt_pk_bf16_f32 v1, v25, v24
	s_waitcnt vmcnt(44)
	v_cvt_pk_bf16_f32 v2, v27, v26
	s_waitcnt vmcnt(42)
	v_cvt_pk_bf16_f32 v3, v29, v28
	global_store_dwordx4 v[64:65], v[0:3], off offset:32
	v_readlane_b32 s42, v253, 47
	v_readlane_b32 s43, v253, 48
	s_waitcnt vmcnt(41)
	v_cvt_pk_bf16_f32 v0, v31, v30
	s_waitcnt vmcnt(39)
	v_cvt_pk_bf16_f32 v1, v33, v32
	s_waitcnt vmcnt(37)
	v_cvt_pk_bf16_f32 v2, v35, v34
	s_waitcnt vmcnt(35)
	v_cvt_pk_bf16_f32 v3, v37, v36
	global_store_dwordx4 v[64:65], v[0:3], off offset:48
	v_readlane_b32 s44, v253, 49
	v_readlane_b32 s45, v253, 50
	s_waitcnt vmcnt(34)
	v_cvt_pk_bf16_f32 v0, v39, v38
	s_waitcnt vmcnt(32)
	v_cvt_pk_bf16_f32 v1, v41, v40
	s_waitcnt vmcnt(30)
	v_cvt_pk_bf16_f32 v2, v43, v42
	s_waitcnt vmcnt(28)
	v_cvt_pk_bf16_f32 v3, v45, v44
	global_store_dwordx4 v[64:65], v[0:3], off offset:64
	v_readlane_b32 s48, v253, 53
	v_readlane_b32 s49, v253, 54
	s_waitcnt vmcnt(27)
	v_cvt_pk_bf16_f32 v0, v47, v46
	s_waitcnt vmcnt(25)
	v_cvt_pk_bf16_f32 v1, v49, v48
	s_waitcnt vmcnt(23)
	v_cvt_pk_bf16_f32 v2, v51, v50
	s_waitcnt vmcnt(21)
	v_cvt_pk_bf16_f32 v3, v53, v52
	global_store_dwordx4 v[64:65], v[0:3], off offset:80
	v_readlane_b32 s50, v253, 55
	v_readlane_b32 s51, v253, 56
	s_waitcnt vmcnt(20)
	v_cvt_pk_bf16_f32 v0, v55, v54
	s_waitcnt vmcnt(18)
	v_cvt_pk_bf16_f32 v1, v57, v56
	s_waitcnt vmcnt(16)
	v_cvt_pk_bf16_f32 v2, v59, v58
	s_waitcnt vmcnt(14)
	v_cvt_pk_bf16_f32 v3, v61, v60
	global_store_dwordx4 v[64:65], v[0:3], off offset:96
	s_waitcnt vmcnt(13)
	s_nop 0
	v_cvt_pk_bf16_f32 v0, v63, v62
	s_waitcnt vmcnt(11)
	v_cvt_pk_bf16_f32 v1, v67, v66
	s_waitcnt vmcnt(9)
	v_cvt_pk_bf16_f32 v2, v20, v68
	s_waitcnt vmcnt(7)
	v_cvt_pk_bf16_f32 v3, v18, v21

.LBB0_496:
	s_andn2_b64 vcc, exec, s[0:1]
	s_cbranch_vccnz .LBB0_498
	s_add_i32 s0, s6, 0x300
	s_and_b32 s0, s0, 0x3c0
	v_readlane_b32 s36, v253, 41
	s_and_b32 s1, s4, 0x3c0
	s_lshl_b32 s20, s0, 12
	v_readlane_b32 s44, v253, 49
	v_readlane_b32 s45, v253, 50
	s_add_u32 s20, s44, s20
	s_addc_u32 s27, s45, 0
	s_lshl_b32 s28, s1, 2
	s_add_u32 s28, s20, s28
	s_addc_u32 s29, s27, 0
	v_lshl_add_u64 v[0:1], v[148:149], 2, s[28:29]
	v_add_co_u32_e32 v6, vcc, s11, v0
	s_movk_i32 s20, 0x4000
	s_nop 0
	v_addc_co_u32_e32 v7, vcc, 0, v1, vcc
	v_add_co_u32_e32 v8, vcc, s20, v0
	s_movk_i32 s20, 0x6000
	s_nop 0
	v_addc_co_u32_e32 v9, vcc, 0, v1, vcc
	v_add_co_u32_e32 v10, vcc, s20, v0
	s_mov_b32 s20, 0x8000
	s_nop 0
	v_addc_co_u32_e32 v11, vcc, 0, v1, vcc
	v_add_co_u32_e32 v12, vcc, s20, v0
	s_mov_b32 s20, 0xa000
	s_nop 0
	v_addc_co_u32_e32 v13, vcc, 0, v1, vcc
	v_add_co_u32_e32 v14, vcc, s20, v0
	s_mov_b32 s20, 0xc000
	s_nop 0
	v_addc_co_u32_e32 v15, vcc, 0, v1, vcc
	s_waitcnt vmcnt(5)
	v_add_co_u32_e32 v16, vcc, s20, v0
	s_mov_b32 s20, 0xe000
	s_nop 0
	v_addc_co_u32_e32 v17, vcc, 0, v1, vcc
	v_add_co_u32_e32 v18, vcc, s20, v0
	s_mov_b32 s20, 0x12000
	s_nop 0
	v_addc_co_u32_e32 v19, vcc, 0, v1, vcc
	v_add_co_u32_e32 v20, vcc, s67, v0
	global_load_dword v2, v[6:7], off offset:-4096 nt
	global_load_dword v3, v[0:1], off nt
	v_addc_co_u32_e32 v21, vcc, 0, v1, vcc
	global_load_dword v4, v[8:9], off offset:-4096 nt
	global_load_dword v5, v[6:7], off nt
	s_nop 0
	global_load_dword v6, v[10:11], off offset:-4096 nt
	global_load_dword v7, v[8:9], off nt
	s_nop 0
	global_load_dword v8, v[12:13], off offset:-4096 nt
	global_load_dword v9, v[10:11], off nt
	s_nop 0
	global_load_dword v10, v[14:15], off offset:-4096 nt
	global_load_dword v11, v[12:13], off nt
	s_nop 0
	global_load_dword v12, v[16:17], off offset:-4096 nt
	global_load_dword v13, v[14:15], off nt
	s_nop 0
	global_load_dword v14, v[18:19], off offset:-4096 nt
	global_load_dword v15, v[16:17], off nt
	s_nop 0
	global_load_dword v16, v[20:21], off offset:-4096 nt
	global_load_dword v17, v[18:19], off nt
	v_add_co_u32_e32 v18, vcc, s20, v0
	s_mov_b32 s20, 0x14000
	s_nop 0
	v_addc_co_u32_e32 v19, vcc, 0, v1, vcc
	global_load_dword v22, v[18:19], off offset:-4096 nt
	global_load_dword v23, v[20:21], off nt
	v_add_co_u32_e32 v20, vcc, s20, v0
	s_mov_b32 s20, 0x16000
	s_nop 0
	v_addc_co_u32_e32 v21, vcc, 0, v1, vcc
	global_load_dword v24, v[20:21], off offset:-4096 nt
	global_load_dword v25, v[18:19], off nt
	v_add_co_u32_e32 v18, vcc, s20, v0
	s_mov_b32 s20, 0x18000
	s_nop 0
	v_addc_co_u32_e32 v19, vcc, 0, v1, vcc
	global_load_dword v26, v[18:19], off offset:-4096 nt
	global_load_dword v27, v[20:21], off nt
	v_add_co_u32_e32 v20, vcc, s20, v0
	s_mov_b32 s20, 0x1a000
	s_nop 0
	v_addc_co_u32_e32 v21, vcc, 0, v1, vcc
	global_load_dword v28, v[20:21], off offset:-4096 nt
	global_load_dword v29, v[18:19], off nt
	v_add_co_u32_e32 v18, vcc, s20, v0
	s_mov_b32 s20, 0x1c000
	s_nop 0
	v_addc_co_u32_e32 v19, vcc, 0, v1, vcc
	global_load_dword v30, v[18:19], off offset:-4096 nt
	global_load_dword v31, v[20:21], off nt
	v_add_co_u32_e32 v20, vcc, s20, v0
	s_mov_b32 s20, 0x1e000
	s_nop 0
	v_addc_co_u32_e32 v21, vcc, 0, v1, vcc
	global_load_dword v32, v[20:21], off offset:-4096 nt
	global_load_dword v33, v[18:19], off nt
	v_add_co_u32_e32 v18, vcc, s20, v0
	s_mov_b32 s20, 0x20000
	s_nop 0
	v_addc_co_u32_e32 v19, vcc, 0, v1, vcc
	global_load_dword v34, v[18:19], off offset:-4096 nt
	global_load_dword v35, v[20:21], off nt
	v_add_co_u32_e32 v20, vcc, s20, v0
	s_mov_b32 s20, 0x22000
	s_nop 0
	v_addc_co_u32_e32 v21, vcc, 0, v1, vcc
	global_load_dword v36, v[20:21], off offset:-4096 nt
	global_load_dword v37, v[18:19], off nt
	v_add_co_u32_e32 v18, vcc, s20, v0
	s_mov_b32 s20, 0x24000
	s_nop 0
	v_addc_co_u32_e32 v19, vcc, 0, v1, vcc
	global_load_dword v38, v[18:19], off offset:-4096 nt
	global_load_dword v39, v[20:21], off nt
	v_add_co_u32_e32 v20, vcc, s20, v0
	s_mov_b32 s20, 0x26000
	s_nop 0
	v_addc_co_u32_e32 v21, vcc, 0, v1, vcc
	global_load_dword v40, v[20:21], off offset:-4096 nt
	global_load_dword v41, v[18:19], off nt
	v_add_co_u32_e32 v18, vcc, s20, v0
	s_mov_b32 s20, 0x2a000
	s_nop 0
	v_addc_co_u32_e32 v19, vcc, 0, v1, vcc
	global_load_dword v42, v[18:19], off offset:-4096 nt
	global_load_dword v43, v[20:21], off nt
	v_add_co_u32_e32 v20, vcc, s95, v0
	v_readlane_b32 s28, v253, 31
	s_nop 0
	v_addc_co_u32_e32 v21, vcc, 0, v1, vcc
	global_load_dword v44, v[20:21], off offset:-4096 nt
	global_load_dword v45, v[18:19], off nt
	v_add_co_u32_e32 v18, vcc, s20, v0
	s_mov_b32 s20, 0x2c000
	s_nop 0
	v_addc_co_u32_e32 v19, vcc, 0, v1, vcc
	global_load_dword v46, v[18:19], off offset:-4096 nt
	global_load_dword v47, v[20:21], off nt
	v_add_co_u32_e32 v20, vcc, s20, v0
	s_mov_b32 s20, 0x2e000
	s_nop 0
	v_addc_co_u32_e32 v21, vcc, 0, v1, vcc
	global_load_dword v48, v[20:21], off offset:-4096 nt
	global_load_dword v49, v[18:19], off nt
	v_add_co_u32_e32 v18, vcc, s20, v0
	s_mov_b32 s20, 0x30000
	s_nop 0
	v_addc_co_u32_e32 v19, vcc, 0, v1, vcc
	global_load_dword v50, v[18:19], off offset:-4096 nt
	global_load_dword v51, v[20:21], off nt
	v_add_co_u32_e32 v20, vcc, s20, v0
	s_mov_b32 s20, 0x32000
	s_nop 0
	v_addc_co_u32_e32 v21, vcc, 0, v1, vcc
	global_load_dword v52, v[20:21], off offset:-4096 nt
	global_load_dword v53, v[18:19], off nt
	v_add_co_u32_e32 v18, vcc, s20, v0
	s_mov_b32 s20, 0x34000
	s_nop 0
	v_addc_co_u32_e32 v19, vcc, 0, v1, vcc
	global_load_dword v54, v[18:19], off offset:-4096 nt
	global_load_dword v55, v[20:21], off nt
	v_add_co_u32_e32 v20, vcc, s20, v0
	s_mov_b32 s20, 0x36000
	s_nop 0
	v_addc_co_u32_e32 v21, vcc, 0, v1, vcc
	global_load_dword v56, v[20:21], off offset:-4096 nt
	global_load_dword v57, v[18:19], off nt
	v_add_co_u32_e32 v18, vcc, s20, v0
	s_mov_b32 s20, 0x38000
	s_nop 0
	v_addc_co_u32_e32 v19, vcc, 0, v1, vcc
	global_load_dword v58, v[18:19], off offset:-4096 nt
	global_load_dword v59, v[20:21], off nt
	v_add_co_u32_e32 v20, vcc, s20, v0
	s_mov_b32 s20, 0x3a000
	s_nop 0
	v_addc_co_u32_e32 v21, vcc, 0, v1, vcc
	global_load_dword v60, v[20:21], off offset:-4096 nt
	global_load_dword v61, v[18:19], off nt
	v_add_co_u32_e32 v18, vcc, s20, v0
	s_mov_b32 s20, 0x3c000
	s_nop 0
	v_addc_co_u32_e32 v19, vcc, 0, v1, vcc
	global_load_dword v62, v[18:19], off offset:-4096 nt
	global_load_dword v63, v[20:21], off nt
	v_add_co_u32_e32 v20, vcc, s20, v0
	s_mov_b32 s20, 0x3e000
	s_nop 0
	v_addc_co_u32_e32 v21, vcc, 0, v1, vcc
	global_load_dword v66, v[20:21], off offset:-4096 nt
	global_load_dword v67, v[18:19], off nt
	v_add_co_u32_e32 v18, vcc, s20, v0
	s_mov_b32 s20, 0x3f000
	s_nop 0
	v_addc_co_u32_e32 v19, vcc, 0, v1, vcc
	v_add_co_u32_e32 v0, vcc, s20, v0
	global_load_dword v68, v[18:19], off offset:-4096 nt
	s_nop 0
	global_load_dword v20, v[20:21], off nt
	v_addc_co_u32_e32 v1, vcc, 0, v1, vcc
	global_load_dword v21, v[0:1], off nt
	s_nop 0
	global_load_dword v18, v[18:19], off nt
	v_add_u32_e32 v0, s1, v148
	v_ashrrev_i32_e32 v1, 31, v0
	v_lshlrev_b64 v[0:1], 9, v[0:1]
	v_readlane_b32 s29, v253, 32
	s_lshl_b32 s92, s0, 1
	v_readlane_b32 s37, v253, 42
	v_lshl_add_u64 v[0:1], s[28:29], 0, v[0:1]
	v_lshl_add_u64 v[64:65], v[0:1], 0, s[92:93]
	s_waitcnt vmcnt(62)
	v_cvt_pk_bf16_f32 v0, v3, v2
	s_waitcnt vmcnt(60)
	v_cvt_pk_bf16_f32 v1, v5, v4
	s_waitcnt vmcnt(58)
	v_cvt_pk_bf16_f32 v2, v7, v6
	s_waitcnt vmcnt(56)
	v_cvt_pk_bf16_f32 v3, v9, v8
	global_store_dwordx4 v[64:65], v[0:3], off
	v_readlane_b32 s38, v253, 43
	v_readlane_b32 s39, v253, 44
	s_waitcnt vmcnt(55)
	v_cvt_pk_bf16_f32 v0, v11, v10
	s_waitcnt vmcnt(53)
	v_cvt_pk_bf16_f32 v1, v13, v12
	s_waitcnt vmcnt(51)
	v_cvt_pk_bf16_f32 v2, v15, v14
	s_waitcnt vmcnt(49)
	v_cvt_pk_bf16_f32 v3, v17, v16
	global_store_dwordx4 v[64:65], v[0:3], off offset:16
	v_readlane_b32 s40, v253, 45
	v_readlane_b32 s41, v253, 46
	s_waitcnt vmcnt(48)
	v_cvt_pk_bf16_f32 v0, v23, v22
	s_waitcnt vmcnt(46)
	v_cvt_pk_bf16_f32 v1, v25, v24
	s_waitcnt vmcnt(44)
	v_cvt_pk_bf16_f32 v2, v27, v26
	s_waitcnt vmcnt(42)
	v_cvt_pk_bf16_f32 v3, v29, v28
	global_store_dwordx4 v[64:65], v[0:3], off offset:32
	v_readlane_b32 s42, v253, 47
	v_readlane_b32 s43, v253, 48
	s_waitcnt vmcnt(41)
	v_cvt_pk_bf16_f32 v0, v31, v30
	s_waitcnt vmcnt(39)
	v_cvt_pk_bf16_f32 v1, v33, v32
	s_waitcnt vmcnt(37)
	v_cvt_pk_bf16_f32 v2, v35, v34
	s_waitcnt vmcnt(35)
	v_cvt_pk_bf16_f32 v3, v37, v36
	global_store_dwordx4 v[64:65], v[0:3], off offset:48
	v_readlane_b32 s46, v253, 51
	v_readlane_b32 s47, v253, 52
	s_waitcnt vmcnt(34)
	v_cvt_pk_bf16_f32 v0, v39, v38
	s_waitcnt vmcnt(32)
	v_cvt_pk_bf16_f32 v1, v41, v40
	s_waitcnt vmcnt(30)
	v_cvt_pk_bf16_f32 v2, v43, v42
	s_waitcnt vmcnt(28)
	v_cvt_pk_bf16_f32 v3, v45, v44
	global_store_dwordx4 v[64:65], v[0:3], off offset:64
	v_readlane_b32 s48, v253, 53
	v_readlane_b32 s49, v253, 54
	s_waitcnt vmcnt(27)
	v_cvt_pk_bf16_f32 v0, v47, v46
	s_waitcnt vmcnt(25)
	v_cvt_pk_bf16_f32 v1, v49, v48
	s_waitcnt vmcnt(23)
	v_cvt_pk_bf16_f32 v2, v51, v50
	s_waitcnt vmcnt(21)
	v_cvt_pk_bf16_f32 v3, v53, v52
	global_store_dwordx4 v[64:65], v[0:3], off offset:80
	v_readlane_b32 s50, v253, 55
	v_readlane_b32 s51, v253, 56
	s_waitcnt vmcnt(20)
	v_cvt_pk_bf16_f32 v0, v55, v54
	s_waitcnt vmcnt(18)
	v_cvt_pk_bf16_f32 v1, v57, v56
	s_waitcnt vmcnt(16)
	v_cvt_pk_bf16_f32 v2, v59, v58
	s_waitcnt vmcnt(14)
	v_cvt_pk_bf16_f32 v3, v61, v60
	global_store_dwordx4 v[64:65], v[0:3], off offset:96
	s_waitcnt vmcnt(13)
	s_nop 0
	v_cvt_pk_bf16_f32 v0, v63, v62
	s_waitcnt vmcnt(11)
	v_cvt_pk_bf16_f32 v1, v67, v66
	s_waitcnt vmcnt(9)
	v_cvt_pk_bf16_f32 v2, v20, v68
	s_waitcnt vmcnt(7)
	v_cvt_pk_bf16_f32 v3, v18, v21

.LBB0_499:
	s_andn2_b64 vcc, exec, s[0:1]
	s_cbranch_vccnz .LBB0_501
	s_and_b32 s0, s6, 0x3c0
	v_readlane_b32 s36, v253, 41
	s_and_b32 s1, s4, 0x3c0
	s_lshl_b32 s20, s0, 12
	v_readlane_b32 s42, v253, 47
	v_readlane_b32 s43, v253, 48
	s_add_u32 s20, s42, s20
	s_addc_u32 s27, s43, 0
	s_lshl_b32 s28, s1, 2
	s_add_u32 s28, s20, s28
	s_addc_u32 s29, s27, 0
	v_lshl_add_u64 v[0:1], v[148:149], 2, s[28:29]
	v_add_co_u32_e32 v6, vcc, s11, v0
	s_movk_i32 s20, 0x4000
	s_nop 0
	v_addc_co_u32_e32 v7, vcc, 0, v1, vcc
	v_add_co_u32_e32 v8, vcc, s20, v0
	s_movk_i32 s20, 0x6000
	s_nop 0
	v_addc_co_u32_e32 v9, vcc, 0, v1, vcc
	v_add_co_u32_e32 v10, vcc, s20, v0
	s_mov_b32 s20, 0x8000
	s_nop 0
	v_addc_co_u32_e32 v11, vcc, 0, v1, vcc
	v_add_co_u32_e32 v12, vcc, s20, v0
	s_mov_b32 s20, 0xa000
	s_nop 0
	v_addc_co_u32_e32 v13, vcc, 0, v1, vcc
	v_add_co_u32_e32 v14, vcc, s20, v0
	s_mov_b32 s20, 0xc000
	s_nop 0
	v_addc_co_u32_e32 v15, vcc, 0, v1, vcc
	s_waitcnt vmcnt(5)
	v_add_co_u32_e32 v16, vcc, s20, v0
	s_mov_b32 s20, 0xe000
	s_nop 0
	v_addc_co_u32_e32 v17, vcc, 0, v1, vcc
	v_add_co_u32_e32 v18, vcc, s20, v0
	s_mov_b32 s20, 0x12000
	s_nop 0
	v_addc_co_u32_e32 v19, vcc, 0, v1, vcc
	v_add_co_u32_e32 v20, vcc, s67, v0
	global_load_dword v2, v[6:7], off offset:-4096 nt
	global_load_dword v3, v[0:1], off nt
	v_addc_co_u32_e32 v21, vcc, 0, v1, vcc
	global_load_dword v4, v[8:9], off offset:-4096 nt
	global_load_dword v5, v[6:7], off nt
	s_nop 0
	global_load_dword v6, v[10:11], off offset:-4096 nt
	global_load_dword v7, v[8:9], off nt
	s_nop 0
	global_load_dword v8, v[12:13], off offset:-4096 nt
	global_load_dword v9, v[10:11], off nt
	s_nop 0
	global_load_dword v10, v[14:15], off offset:-4096 nt
	global_load_dword v11, v[12:13], off nt
	s_nop 0
	global_load_dword v12, v[16:17], off offset:-4096 nt
	global_load_dword v13, v[14:15], off nt
	s_nop 0
	global_load_dword v14, v[18:19], off offset:-4096 nt
	global_load_dword v15, v[16:17], off nt
	s_nop 0
	global_load_dword v16, v[20:21], off offset:-4096 nt
	global_load_dword v17, v[18:19], off nt
	v_add_co_u32_e32 v18, vcc, s20, v0
	s_mov_b32 s20, 0x14000
	s_nop 0
	v_addc_co_u32_e32 v19, vcc, 0, v1, vcc
	global_load_dword v22, v[18:19], off offset:-4096 nt
	global_load_dword v23, v[20:21], off nt
	v_add_co_u32_e32 v20, vcc, s20, v0
	s_mov_b32 s20, 0x16000
	s_nop 0
	v_addc_co_u32_e32 v21, vcc, 0, v1, vcc
	global_load_dword v24, v[20:21], off offset:-4096 nt
	global_load_dword v25, v[18:19], off nt
	v_add_co_u32_e32 v18, vcc, s20, v0
	s_mov_b32 s20, 0x18000
	s_nop 0
	v_addc_co_u32_e32 v19, vcc, 0, v1, vcc
	global_load_dword v26, v[18:19], off offset:-4096 nt
	global_load_dword v27, v[20:21], off nt
	v_add_co_u32_e32 v20, vcc, s20, v0
	s_mov_b32 s20, 0x1a000
	s_nop 0
	v_addc_co_u32_e32 v21, vcc, 0, v1, vcc
	global_load_dword v28, v[20:21], off offset:-4096 nt
	global_load_dword v29, v[18:19], off nt
	v_add_co_u32_e32 v18, vcc, s20, v0
	s_mov_b32 s20, 0x1c000
	s_nop 0
	v_addc_co_u32_e32 v19, vcc, 0, v1, vcc
	global_load_dword v30, v[18:19], off offset:-4096 nt
	global_load_dword v31, v[20:21], off nt
	v_add_co_u32_e32 v20, vcc, s20, v0
	s_mov_b32 s20, 0x1e000
	s_nop 0
	v_addc_co_u32_e32 v21, vcc, 0, v1, vcc
	global_load_dword v32, v[20:21], off offset:-4096 nt
	global_load_dword v33, v[18:19], off nt
	v_add_co_u32_e32 v18, vcc, s20, v0
	s_mov_b32 s20, 0x20000
	s_nop 0
	v_addc_co_u32_e32 v19, vcc, 0, v1, vcc
	global_load_dword v34, v[18:19], off offset:-4096 nt
	global_load_dword v35, v[20:21], off nt
	v_add_co_u32_e32 v20, vcc, s20, v0
	s_mov_b32 s20, 0x22000
	s_nop 0
	v_addc_co_u32_e32 v21, vcc, 0, v1, vcc
	global_load_dword v36, v[20:21], off offset:-4096 nt
	global_load_dword v37, v[18:19], off nt
	v_add_co_u32_e32 v18, vcc, s20, v0
	s_mov_b32 s20, 0x24000
	s_nop 0
	v_addc_co_u32_e32 v19, vcc, 0, v1, vcc
	global_load_dword v38, v[18:19], off offset:-4096 nt
	global_load_dword v39, v[20:21], off nt
	v_add_co_u32_e32 v20, vcc, s20, v0
	s_mov_b32 s20, 0x26000
	s_nop 0
	v_addc_co_u32_e32 v21, vcc, 0, v1, vcc
	global_load_dword v40, v[20:21], off offset:-4096 nt
	global_load_dword v41, v[18:19], off nt
	v_add_co_u32_e32 v18, vcc, s20, v0
	s_mov_b32 s20, 0x2a000
	s_nop 0
	v_addc_co_u32_e32 v19, vcc, 0, v1, vcc
	global_load_dword v42, v[18:19], off offset:-4096 nt
	global_load_dword v43, v[20:21], off nt
	v_add_co_u32_e32 v20, vcc, s95, v0
	v_readlane_b32 s28, v253, 37
	s_nop 0
	v_addc_co_u32_e32 v21, vcc, 0, v1, vcc
	global_load_dword v44, v[20:21], off offset:-4096 nt
	global_load_dword v45, v[18:19], off nt
	v_add_co_u32_e32 v18, vcc, s20, v0
	s_mov_b32 s20, 0x2c000
	s_nop 0
	v_addc_co_u32_e32 v19, vcc, 0, v1, vcc
	global_load_dword v46, v[18:19], off offset:-4096 nt
	global_load_dword v47, v[20:21], off nt
	v_add_co_u32_e32 v20, vcc, s20, v0
	s_mov_b32 s20, 0x2e000
	s_nop 0
	v_addc_co_u32_e32 v21, vcc, 0, v1, vcc
	global_load_dword v48, v[20:21], off offset:-4096 nt
	global_load_dword v49, v[18:19], off nt
	v_add_co_u32_e32 v18, vcc, s20, v0
	s_mov_b32 s20, 0x30000
	s_nop 0
	v_addc_co_u32_e32 v19, vcc, 0, v1, vcc
	global_load_dword v50, v[18:19], off offset:-4096 nt
	global_load_dword v51, v[20:21], off nt
	v_add_co_u32_e32 v20, vcc, s20, v0
	s_mov_b32 s20, 0x32000
	s_nop 0
	v_addc_co_u32_e32 v21, vcc, 0, v1, vcc
	global_load_dword v52, v[20:21], off offset:-4096 nt
	global_load_dword v53, v[18:19], off nt
	v_add_co_u32_e32 v18, vcc, s20, v0
	s_mov_b32 s20, 0x34000
	s_nop 0
	v_addc_co_u32_e32 v19, vcc, 0, v1, vcc
	global_load_dword v54, v[18:19], off offset:-4096 nt
	global_load_dword v55, v[20:21], off nt
	v_add_co_u32_e32 v20, vcc, s20, v0
	s_mov_b32 s20, 0x36000
	s_nop 0
	v_addc_co_u32_e32 v21, vcc, 0, v1, vcc
	global_load_dword v56, v[20:21], off offset:-4096 nt
	global_load_dword v57, v[18:19], off nt
	v_add_co_u32_e32 v18, vcc, s20, v0
	s_mov_b32 s20, 0x38000
	s_nop 0
	v_addc_co_u32_e32 v19, vcc, 0, v1, vcc
	global_load_dword v58, v[18:19], off offset:-4096 nt
	global_load_dword v59, v[20:21], off nt
	v_add_co_u32_e32 v20, vcc, s20, v0
	s_mov_b32 s20, 0x3a000
	s_nop 0
	v_addc_co_u32_e32 v21, vcc, 0, v1, vcc
	global_load_dword v60, v[20:21], off offset:-4096 nt
	global_load_dword v61, v[18:19], off nt
	v_add_co_u32_e32 v18, vcc, s20, v0
	s_mov_b32 s20, 0x3c000
	s_nop 0
	v_addc_co_u32_e32 v19, vcc, 0, v1, vcc
	global_load_dword v62, v[18:19], off offset:-4096 nt
	global_load_dword v63, v[20:21], off nt
	v_add_co_u32_e32 v20, vcc, s20, v0
	s_mov_b32 s20, 0x3e000
	s_nop 0
	v_addc_co_u32_e32 v21, vcc, 0, v1, vcc
	global_load_dword v66, v[20:21], off offset:-4096 nt
	global_load_dword v67, v[18:19], off nt
	v_add_co_u32_e32 v18, vcc, s20, v0
	s_mov_b32 s20, 0x3f000
	s_nop 0
	v_addc_co_u32_e32 v19, vcc, 0, v1, vcc
	v_add_co_u32_e32 v0, vcc, s20, v0
	global_load_dword v68, v[18:19], off offset:-4096 nt
	s_nop 0
	global_load_dword v20, v[20:21], off nt
	v_addc_co_u32_e32 v1, vcc, 0, v1, vcc
	global_load_dword v21, v[0:1], off nt
	s_nop 0
	global_load_dword v18, v[18:19], off nt
	v_add_u32_e32 v0, s1, v148
	v_ashrrev_i32_e32 v1, 31, v0
	v_lshlrev_b64 v[0:1], 9, v[0:1]
	v_readlane_b32 s29, v253, 38
	s_lshl_b32 s92, s0, 1
	v_readlane_b32 s37, v253, 42
	v_lshl_add_u64 v[0:1], s[28:29], 0, v[0:1]
	v_lshl_add_u64 v[64:65], v[0:1], 0, s[92:93]
	s_waitcnt vmcnt(62)
	v_cvt_pk_bf16_f32 v0, v3, v2
	s_waitcnt vmcnt(60)
	v_cvt_pk_bf16_f32 v1, v5, v4
	s_waitcnt vmcnt(58)
	v_cvt_pk_bf16_f32 v2, v7, v6
	s_waitcnt vmcnt(56)
	v_cvt_pk_bf16_f32 v3, v9, v8
	global_store_dwordx4 v[64:65], v[0:3], off
	v_readlane_b32 s38, v253, 43
	v_readlane_b32 s39, v253, 44
	s_waitcnt vmcnt(55)
	v_cvt_pk_bf16_f32 v0, v11, v10
	s_waitcnt vmcnt(53)
	v_cvt_pk_bf16_f32 v1, v13, v12
	s_waitcnt vmcnt(51)
	v_cvt_pk_bf16_f32 v2, v15, v14
	s_waitcnt vmcnt(49)
	v_cvt_pk_bf16_f32 v3, v17, v16
	global_store_dwordx4 v[64:65], v[0:3], off offset:16
	v_readlane_b32 s40, v253, 45
	v_readlane_b32 s41, v253, 46
	s_waitcnt vmcnt(48)
	v_cvt_pk_bf16_f32 v0, v23, v22
	s_waitcnt vmcnt(46)
	v_cvt_pk_bf16_f32 v1, v25, v24
	s_waitcnt vmcnt(44)
	v_cvt_pk_bf16_f32 v2, v27, v26
	s_waitcnt vmcnt(42)
	v_cvt_pk_bf16_f32 v3, v29, v28
	global_store_dwordx4 v[64:65], v[0:3], off offset:32
	v_readlane_b32 s44, v253, 49
	v_readlane_b32 s45, v253, 50
	s_waitcnt vmcnt(41)
	v_cvt_pk_bf16_f32 v0, v31, v30
	s_waitcnt vmcnt(39)
	v_cvt_pk_bf16_f32 v1, v33, v32
	s_waitcnt vmcnt(37)
	v_cvt_pk_bf16_f32 v2, v35, v34
	s_waitcnt vmcnt(35)
	v_cvt_pk_bf16_f32 v3, v37, v36
	global_store_dwordx4 v[64:65], v[0:3], off offset:48
	v_readlane_b32 s46, v253, 51
	v_readlane_b32 s47, v253, 52
	s_waitcnt vmcnt(34)
	v_cvt_pk_bf16_f32 v0, v39, v38
	s_waitcnt vmcnt(32)
	v_cvt_pk_bf16_f32 v1, v41, v40
	s_waitcnt vmcnt(30)
	v_cvt_pk_bf16_f32 v2, v43, v42
	s_waitcnt vmcnt(28)
	v_cvt_pk_bf16_f32 v3, v45, v44
	global_store_dwordx4 v[64:65], v[0:3], off offset:64
	v_readlane_b32 s48, v253, 53
	v_readlane_b32 s49, v253, 54
	s_waitcnt vmcnt(27)
	v_cvt_pk_bf16_f32 v0, v47, v46
	s_waitcnt vmcnt(25)
	v_cvt_pk_bf16_f32 v1, v49, v48
	s_waitcnt vmcnt(23)
	v_cvt_pk_bf16_f32 v2, v51, v50
	s_waitcnt vmcnt(21)
	v_cvt_pk_bf16_f32 v3, v53, v52
	global_store_dwordx4 v[64:65], v[0:3], off offset:80
	v_readlane_b32 s50, v253, 55
	v_readlane_b32 s51, v253, 56
	s_waitcnt vmcnt(20)
	v_cvt_pk_bf16_f32 v0, v55, v54
	s_waitcnt vmcnt(18)
	v_cvt_pk_bf16_f32 v1, v57, v56
	s_waitcnt vmcnt(16)
	v_cvt_pk_bf16_f32 v2, v59, v58
	s_waitcnt vmcnt(14)
	v_cvt_pk_bf16_f32 v3, v61, v60
	global_store_dwordx4 v[64:65], v[0:3], off offset:96
	s_waitcnt vmcnt(13)
	s_nop 0
	v_cvt_pk_bf16_f32 v0, v63, v62
	s_waitcnt vmcnt(11)
	v_cvt_pk_bf16_f32 v1, v67, v66
	s_waitcnt vmcnt(9)
	v_cvt_pk_bf16_f32 v2, v20, v68
	s_waitcnt vmcnt(7)
	v_cvt_pk_bf16_f32 v3, v18, v21

.LBB0_502:
	s_andn2_b64 vcc, exec, s[0:1]
	s_cbranch_vccnz .LBB0_481
	s_mul_hi_i32 s0, s12, 0x66666667
	s_lshr_b32 s1, s0, 31
	s_ashr_i32 s0, s0, 5
	s_add_i32 s0, s0, s1
	s_lshl_b32 s28, s0, 6
	s_mul_i32 s1, s0, 0xffffec00
	v_readlane_b32 s36, v253, 41
	s_add_i32 s30, s4, s1
	s_ashr_i32 s29, s28, 31
	s_mul_i32 s0, s0, 0x140000
	v_readlane_b32 s38, v253, 43
	s_mul_hi_i32 s1, s28, 0x5000
	v_readlane_b32 s39, v253, 44
	s_add_u32 s20, s38, s0
	s_addc_u32 s27, s39, s1
	s_ashr_i32 s31, s30, 31
	s_lshl_b64 s[0:1], s[30:31], 2
	s_add_u32 s0, s20, s0
	s_addc_u32 s1, s27, s1
	v_lshl_add_u64 v[64:65], v[148:149], 2, s[0:1]
	s_movk_i32 s0, 0x5000
	v_add_co_u32_e32 v2, vcc, s0, v64
	s_mov_b32 s0, 0xa000
	s_nop 0
	v_addc_co_u32_e32 v3, vcc, 0, v65, vcc
	global_load_dword v0, v[64:65], off nt
	global_load_dword v1, v[2:3], off nt
	v_add_co_u32_e32 v2, vcc, s0, v64
	s_mov_b32 s0, 0xf000
	s_nop 0
	v_addc_co_u32_e32 v3, vcc, 0, v65, vcc
	v_add_co_u32_e32 v4, vcc, s0, v64
	s_mov_b32 s0, 0x14000
	s_nop 0
	v_addc_co_u32_e32 v5, vcc, 0, v65, vcc
	global_load_dword v2, v[2:3], off nt
	v_readlane_b32 s37, v253, 42
	global_load_dword v3, v[4:5], off nt
	v_add_co_u32_e32 v4, vcc, s0, v64
	s_mov_b32 s0, 0x1e000
	s_nop 0
	v_addc_co_u32_e32 v5, vcc, 0, v65, vcc
	v_add_co_u32_e32 v6, vcc, s66, v64
	global_load_dword v4, v[4:5], off nt
	s_nop 0
	v_addc_co_u32_e32 v7, vcc, 0, v65, vcc
	global_load_dword v5, v[6:7], off nt
	v_add_co_u32_e32 v6, vcc, s0, v64
	s_mov_b32 s0, 0x23000
	s_nop 0
	v_addc_co_u32_e32 v7, vcc, 0, v65, vcc
	v_add_co_u32_e32 v8, vcc, s0, v64
	global_load_dword v6, v[6:7], off nt
	s_nop 0
	v_addc_co_u32_e32 v9, vcc, 0, v65, vcc
	global_load_dword v7, v[8:9], off nt
	v_add_co_u32_e32 v8, vcc, s95, v64
	s_mov_b32 s0, 0x2d000
	s_nop 0
	v_addc_co_u32_e32 v9, vcc, 0, v65, vcc
	v_add_co_u32_e32 v10, vcc, s0, v64
	s_mov_b32 s0, 0x32000
	s_nop 0
	v_addc_co_u32_e32 v11, vcc, 0, v65, vcc
	global_load_dword v8, v[8:9], off nt
	v_readlane_b32 s40, v253, 45
	global_load_dword v9, v[10:11], off nt
	v_add_co_u32_e32 v10, vcc, s0, v64
	s_mov_b32 s0, 0x37000
	s_nop 0
	v_addc_co_u32_e32 v11, vcc, 0, v65, vcc
	v_add_co_u32_e32 v12, vcc, s0, v64
	s_mov_b32 s0, 0x3c000
	s_nop 0
	v_addc_co_u32_e32 v13, vcc, 0, v65, vcc
	global_load_dword v10, v[10:11], off nt
	v_readlane_b32 s41, v253, 46
	global_load_dword v11, v[12:13], off nt
	v_add_co_u32_e32 v12, vcc, s0, v64
	s_mov_b32 s0, 0x41000
	s_nop 0
	v_addc_co_u32_e32 v13, vcc, 0, v65, vcc
	v_add_co_u32_e32 v14, vcc, s0, v64
	s_mov_b32 s0, 0x46000
	s_nop 0
	v_addc_co_u32_e32 v15, vcc, 0, v65, vcc
	global_load_dword v12, v[12:13], off nt
	v_readlane_b32 s42, v253, 47
	global_load_dword v13, v[14:15], off nt
	v_add_co_u32_e32 v14, vcc, s0, v64
	s_mov_b32 s0, 0x4b000
	s_nop 0
	v_addc_co_u32_e32 v15, vcc, 0, v65, vcc
	s_waitcnt vmcnt(19)
	v_add_co_u32_e32 v16, vcc, s0, v64
	s_mov_b32 s0, 0x50000
	s_nop 0
	v_addc_co_u32_e32 v17, vcc, 0, v65, vcc
	global_load_dword v14, v[14:15], off nt
	v_readlane_b32 s43, v253, 48
	global_load_dword v15, v[16:17], off nt
	v_add_co_u32_e32 v16, vcc, s0, v64
	s_mov_b32 s0, 0x55000
	s_nop 0
	v_addc_co_u32_e32 v17, vcc, 0, v65, vcc
	v_add_co_u32_e32 v18, vcc, s0, v64
	s_mov_b32 s0, 0x5a000
	s_nop 0
	v_addc_co_u32_e32 v19, vcc, 0, v65, vcc
	global_load_dword v16, v[16:17], off nt
	v_readlane_b32 s44, v253, 49
	global_load_dword v17, v[18:19], off nt
	v_add_co_u32_e32 v18, vcc, s0, v64
	s_mov_b32 s0, 0x5f000
	s_nop 0
	v_addc_co_u32_e32 v19, vcc, 0, v65, vcc
	v_add_co_u32_e32 v20, vcc, s0, v64
	s_mov_b32 s0, 0x64000
	s_nop 0
	v_addc_co_u32_e32 v21, vcc, 0, v65, vcc
	global_load_dword v18, v[18:19], off nt
	v_readlane_b32 s45, v253, 50
	global_load_dword v19, v[20:21], off nt
	v_add_co_u32_e32 v20, vcc, s0, v64
	s_mov_b32 s0, 0x69000
	s_nop 0
	v_addc_co_u32_e32 v21, vcc, 0, v65, vcc
	v_add_co_u32_e32 v22, vcc, s0, v64
	s_mov_b32 s0, 0x6e000
	s_nop 0
	v_addc_co_u32_e32 v23, vcc, 0, v65, vcc
	global_load_dword v20, v[20:21], off nt
	v_readlane_b32 s46, v253, 51
	global_load_dword v21, v[22:23], off nt
	v_add_co_u32_e32 v22, vcc, s0, v64
	s_mov_b32 s0, 0x73000
	s_nop 0
	v_addc_co_u32_e32 v23, vcc, 0, v65, vcc
	v_add_co_u32_e32 v24, vcc, s0, v64
	s_mov_b32 s0, 0x78000
	s_nop 0
	v_addc_co_u32_e32 v25, vcc, 0, v65, vcc
	global_load_dword v22, v[22:23], off nt
	v_readlane_b32 s47, v253, 52
	global_load_dword v23, v[24:25], off nt
	v_add_co_u32_e32 v24, vcc, s0, v64
	s_mov_b32 s0, 0x7d000
	s_nop 0
	v_addc_co_u32_e32 v25, vcc, 0, v65, vcc
	v_add_co_u32_e32 v26, vcc, s0, v64
	s_mov_b32 s0, 0x82000
	s_nop 0
	v_addc_co_u32_e32 v27, vcc, 0, v65, vcc
	global_load_dword v24, v[24:25], off nt
	v_readlane_b32 s48, v253, 53
	global_load_dword v25, v[26:27], off nt
	v_add_co_u32_e32 v26, vcc, s0, v64
	s_mov_b32 s0, 0x87000
	s_nop 0
	v_addc_co_u32_e32 v27, vcc, 0, v65, vcc
	s_waitcnt vmcnt(30)
	v_add_co_u32_e32 v28, vcc, s0, v64
	s_mov_b32 s0, 0x8c000
	s_nop 0
	v_addc_co_u32_e32 v29, vcc, 0, v65, vcc
	global_load_dword v26, v[26:27], off nt
	v_readlane_b32 s49, v253, 54
	global_load_dword v27, v[28:29], off nt
	v_add_co_u32_e32 v28, vcc, s0, v64
	s_mov_b32 s0, 0x91000
	s_nop 0
	v_addc_co_u32_e32 v29, vcc, 0, v65, vcc
	v_add_co_u32_e32 v30, vcc, s0, v64
	s_mov_b32 s0, 0x96000
	s_nop 0
	v_addc_co_u32_e32 v31, vcc, 0, v65, vcc
	global_load_dword v28, v[28:29], off nt
	v_readlane_b32 s50, v253, 55
	global_load_dword v29, v[30:31], off nt
	v_add_co_u32_e32 v30, vcc, s0, v64
	s_mov_b32 s0, 0x9b000
	s_nop 0
	v_addc_co_u32_e32 v31, vcc, 0, v65, vcc
	s_waitcnt vmcnt(31)
	v_add_co_u32_e32 v32, vcc, s0, v64
	s_mov_b32 s0, 0xa0000
	s_nop 0
	v_addc_co_u32_e32 v33, vcc, 0, v65, vcc
	global_load_dword v30, v[30:31], off nt
	v_readlane_b32 s51, v253, 56
	global_load_dword v31, v[32:33], off nt
	v_add_co_u32_e32 v32, vcc, s0, v64
	s_mov_b32 s0, 0xa5000
	s_nop 0
	v_addc_co_u32_e32 v33, vcc, 0, v65, vcc
	v_add_co_u32_e32 v34, vcc, s0, v64
	s_mov_b32 s0, 0xaa000
	s_nop 0
	v_addc_co_u32_e32 v35, vcc, 0, v65, vcc
	global_load_dword v32, v[32:33], off nt
	s_nop 0
	global_load_dword v33, v[34:35], off nt
	v_add_co_u32_e32 v34, vcc, s0, v64
	s_mov_b32 s0, 0xaf000
	s_nop 0
	v_addc_co_u32_e32 v35, vcc, 0, v65, vcc
	s_waitcnt vmcnt(34)
	v_add_co_u32_e32 v36, vcc, s0, v64
	s_mov_b32 s0, 0xb4000
	s_nop 0
	v_addc_co_u32_e32 v37, vcc, 0, v65, vcc
	global_load_dword v34, v[34:35], off nt
	s_nop 0
	global_load_dword v35, v[36:37], off nt
	v_add_co_u32_e32 v36, vcc, s0, v64
	s_mov_b32 s0, 0xb9000
	s_nop 0
	v_addc_co_u32_e32 v37, vcc, 0, v65, vcc
	v_add_co_u32_e32 v38, vcc, s0, v64
	s_mov_b32 s0, 0xbe000
	s_nop 0
	v_addc_co_u32_e32 v39, vcc, 0, v65, vcc
	global_load_dword v36, v[36:37], off nt
	s_nop 0
	global_load_dword v37, v[38:39], off nt
	v_add_co_u32_e32 v38, vcc, s0, v64
	s_mov_b32 s0, 0xc3000
	s_nop 0
	v_addc_co_u32_e32 v39, vcc, 0, v65, vcc
	v_add_co_u32_e32 v40, vcc, s0, v64
	s_mov_b32 s0, 0xc8000
	s_nop 0
	v_addc_co_u32_e32 v41, vcc, 0, v65, vcc
	global_load_dword v38, v[38:39], off nt
	s_nop 0
	global_load_dword v39, v[40:41], off nt
	v_add_co_u32_e32 v40, vcc, s0, v64
	s_mov_b32 s0, 0xcd000
	s_nop 0
	v_addc_co_u32_e32 v41, vcc, 0, v65, vcc
	v_add_co_u32_e32 v42, vcc, s0, v64
	s_mov_b32 s0, 0xd2000
	s_nop 0
	v_addc_co_u32_e32 v43, vcc, 0, v65, vcc
	global_load_dword v40, v[40:41], off nt
	s_nop 0
	global_load_dword v41, v[42:43], off nt
	v_add_co_u32_e32 v42, vcc, s0, v64
	s_mov_b32 s0, 0xd7000
	s_nop 0
	v_addc_co_u32_e32 v43, vcc, 0, v65, vcc
	v_add_co_u32_e32 v44, vcc, s0, v64
	s_mov_b32 s0, 0xdc000
	s_nop 0
	v_addc_co_u32_e32 v45, vcc, 0, v65, vcc
	global_load_dword v42, v[42:43], off nt
	s_nop 0
	global_load_dword v43, v[44:45], off nt
	v_add_co_u32_e32 v44, vcc, s0, v64
	s_mov_b32 s0, 0xe1000
	s_nop 0
	v_addc_co_u32_e32 v45, vcc, 0, v65, vcc
	v_add_co_u32_e32 v46, vcc, s0, v64
	s_mov_b32 s0, 0xe6000
	s_nop 0
	v_addc_co_u32_e32 v47, vcc, 0, v65, vcc
	global_load_dword v44, v[44:45], off nt
	s_nop 0
	global_load_dword v45, v[46:47], off nt
	v_add_co_u32_e32 v46, vcc, s0, v64
	s_mov_b32 s0, 0xeb000
	s_nop 0
	v_addc_co_u32_e32 v47, vcc, 0, v65, vcc
	v_add_co_u32_e32 v48, vcc, s0, v64
	s_mov_b32 s0, 0xf0000
	s_nop 0
	v_addc_co_u32_e32 v49, vcc, 0, v65, vcc
	global_load_dword v46, v[46:47], off nt
	s_nop 0
	global_load_dword v47, v[48:49], off nt
	v_add_co_u32_e32 v48, vcc, s0, v64
	s_mov_b32 s0, 0xf5000
	s_nop 0
	v_addc_co_u32_e32 v49, vcc, 0, v65, vcc
	v_add_co_u32_e32 v50, vcc, s0, v64
	s_mov_b32 s0, 0xfa000
	s_nop 0
	v_addc_co_u32_e32 v51, vcc, 0, v65, vcc
	global_load_dword v48, v[48:49], off nt
	s_nop 0
	global_load_dword v49, v[50:51], off nt
	v_add_co_u32_e32 v50, vcc, s0, v64
	s_mov_b32 s0, 0xff000
	s_nop 0
	v_addc_co_u32_e32 v51, vcc, 0, v65, vcc
	v_add_co_u32_e32 v52, vcc, s0, v64
	s_mov_b32 s0, 0x104000
	s_nop 0
	v_addc_co_u32_e32 v53, vcc, 0, v65, vcc
	global_load_dword v50, v[50:51], off nt
	s_nop 0
	global_load_dword v51, v[52:53], off nt
	v_add_co_u32_e32 v52, vcc, s0, v64
	s_mov_b32 s0, 0x109000
	s_nop 0
	v_addc_co_u32_e32 v53, vcc, 0, v65, vcc
	v_add_co_u32_e32 v54, vcc, s0, v64
	s_mov_b32 s0, 0x10e000
	s_nop 0
	v_addc_co_u32_e32 v55, vcc, 0, v65, vcc
	global_load_dword v52, v[52:53], off nt
	s_nop 0
	global_load_dword v53, v[54:55], off nt
	v_add_co_u32_e32 v54, vcc, s0, v64
	s_mov_b32 s0, 0x113000
	s_nop 0
	v_addc_co_u32_e32 v55, vcc, 0, v65, vcc
	v_add_co_u32_e32 v56, vcc, s0, v64
	s_mov_b32 s0, 0x118000
	s_nop 0
	v_addc_co_u32_e32 v57, vcc, 0, v65, vcc
	global_load_dword v54, v[54:55], off nt
	s_nop 0
	global_load_dword v55, v[56:57], off nt
	v_add_co_u32_e32 v56, vcc, s0, v64
	s_mov_b32 s0, 0x11d000
	s_nop 0
	v_addc_co_u32_e32 v57, vcc, 0, v65, vcc
	v_add_co_u32_e32 v58, vcc, s0, v64
	s_mov_b32 s0, 0x122000
	s_nop 0
	v_addc_co_u32_e32 v59, vcc, 0, v65, vcc
	global_load_dword v56, v[56:57], off nt
	s_nop 0
	global_load_dword v57, v[58:59], off nt
	v_add_co_u32_e32 v58, vcc, s0, v64
	s_mov_b32 s0, 0x127000
	s_nop 0
	v_addc_co_u32_e32 v59, vcc, 0, v65, vcc
	v_add_co_u32_e32 v60, vcc, s0, v64
	s_mov_b32 s0, 0x12c000
	s_nop 0
	v_addc_co_u32_e32 v61, vcc, 0, v65, vcc
	global_load_dword v58, v[58:59], off nt
	s_nop 0
	global_load_dword v59, v[60:61], off nt
	v_add_co_u32_e32 v60, vcc, s0, v64
	v_readlane_b32 s0, v253, 57
	s_nop 0
	v_addc_co_u32_e32 v61, vcc, 0, v65, vcc
	v_add_co_u32_e32 v62, vcc, 0x131000, v64
	global_load_dword v60, v[60:61], off nt
	s_nop 0
	v_addc_co_u32_e32 v63, vcc, 0, v65, vcc
	global_load_dword v61, v[62:63], off nt
	v_add_co_u32_e32 v62, vcc, 0x136000, v64
	v_readlane_b32 s1, v253, 58
	s_nop 0
	v_addc_co_u32_e32 v63, vcc, 0, v65, vcc
	v_add_co_u32_e32 v64, vcc, 0x13b000, v64
	global_load_dword v62, v[62:63], off nt
	s_nop 0
	v_addc_co_u32_e32 v65, vcc, 0, v65, vcc
	global_load_dword v63, v[64:65], off nt
	s_andn2_b64 vcc, exec, s[0:1]
	s_cbranch_vccnz .LBB0_480
	s_lshl_b64 s[0:1], s[28:29], 2
	s_add_u32 s0, s36, s0
	s_addc_u32 s1, s37, s1
	global_load_dwordx4 v[64:67], v177, s[0:1] offset:48
	global_load_dwordx4 v[68:71], v177, s[0:1] offset:32
	global_load_dwordx4 v[72:75], v177, s[0:1] offset:16
	global_load_dwordx4 v[76:79], v177, s[0:1]
	s_waitcnt vmcnt(3)
	v_pk_mul_f32 v[12:13], v[12:13], v[64:65]
	s_waitcnt vmcnt(2)
	v_pk_mul_f32 v[8:9], v[8:9], v[68:69]
	s_waitcnt vmcnt(1)
	v_pk_mul_f32 v[4:5], v[4:5], v[72:73]
	s_waitcnt vmcnt(0)
	v_pk_mul_f32 v[0:1], v[0:1], v[76:77]
	v_pk_mul_f32 v[2:3], v[2:3], v[78:79]
	v_pk_mul_f32 v[6:7], v[6:7], v[74:75]
	v_pk_mul_f32 v[10:11], v[10:11], v[70:71]
	v_pk_mul_f32 v[14:15], v[14:15], v[66:67]
	global_load_dwordx4 v[64:67], v177, s[0:1] offset:112
	global_load_dwordx4 v[68:71], v177, s[0:1] offset:96
	global_load_dwordx4 v[72:75], v177, s[0:1] offset:80
	global_load_dwordx4 v[76:79], v177, s[0:1] offset:64
	s_waitcnt vmcnt(3)
	v_pk_mul_f32 v[28:29], v[28:29], v[64:65]
	s_waitcnt vmcnt(2)
	v_pk_mul_f32 v[24:25], v[24:25], v[68:69]
	s_waitcnt vmcnt(1)
	v_pk_mul_f32 v[20:21], v[20:21], v[72:73]
	s_waitcnt vmcnt(0)
	v_pk_mul_f32 v[16:17], v[16:17], v[76:77]
	v_pk_mul_f32 v[18:19], v[18:19], v[78:79]
	v_pk_mul_f32 v[22:23], v[22:23], v[74:75]
	v_pk_mul_f32 v[26:27], v[26:27], v[70:71]
	v_pk_mul_f32 v[30:31], v[30:31], v[66:67]
	global_load_dwordx4 v[64:67], v177, s[0:1] offset:176
	global_load_dwordx4 v[68:71], v177, s[0:1] offset:160
	global_load_dwordx4 v[72:75], v177, s[0:1] offset:144
	global_load_dwordx4 v[76:79], v177, s[0:1] offset:128
	s_waitcnt vmcnt(3)
	v_pk_mul_f32 v[44:45], v[44:45], v[64:65]
	s_waitcnt vmcnt(2)
	v_pk_mul_f32 v[40:41], v[40:41], v[68:69]
	s_waitcnt vmcnt(1)
	v_pk_mul_f32 v[36:37], v[36:37], v[72:73]
	s_waitcnt vmcnt(0)
	v_pk_mul_f32 v[32:33], v[32:33], v[76:77]
	v_pk_mul_f32 v[34:35], v[34:35], v[78:79]
	v_pk_mul_f32 v[38:39], v[38:39], v[74:75]
	v_pk_mul_f32 v[42:43], v[42:43], v[70:71]
	v_pk_mul_f32 v[46:47], v[46:47], v[66:67]
	global_load_dwordx4 v[64:67], v177, s[0:1] offset:240
	global_load_dwordx4 v[68:71], v177, s[0:1] offset:224
	global_load_dwordx4 v[72:75], v177, s[0:1] offset:208
	global_load_dwordx4 v[76:79], v177, s[0:1] offset:192
	s_waitcnt vmcnt(3)
	v_pk_mul_f32 v[60:61], v[60:61], v[64:65]
	s_waitcnt vmcnt(2)
	v_pk_mul_f32 v[56:57], v[56:57], v[68:69]
	s_waitcnt vmcnt(1)
	v_pk_mul_f32 v[52:53], v[52:53], v[72:73]
	s_waitcnt vmcnt(0)
	v_pk_mul_f32 v[48:49], v[48:49], v[76:77]
	v_pk_mul_f32 v[50:51], v[50:51], v[78:79]
	v_pk_mul_f32 v[54:55], v[54:55], v[74:75]
	v_pk_mul_f32 v[58:59], v[58:59], v[70:71]
	v_pk_mul_f32 v[62:63], v[62:63], v[66:67]
	s_branch .LBB0_480

.LBB0_795:
	s_cmpk_gt_i32 s62, 0x4ff
	s_mov_b64 s[0:1], -1
	s_cbranch_scc0 .LBB0_815
	s_cmpk_gt_u32 s62, 0x53f
	s_cbranch_scc0 .LBB0_812
	s_cmpk_gt_u32 s62, 0x57f
	s_cbranch_scc0 .LBB0_809
	s_cmpk_gt_u32 s62, 0x67f
	s_cbranch_scc0 .LBB0_806
	s_cmpk_gt_u32 s62, 0xbff
	s_cbranch_scc0 .LBB0_801
	s_and_b32 s0, s60, 0x7fffffc0
	s_add_i32 s92, s0, 0xffffd000
	s_and_b32 s0, s12, 0x3c0
	s_lshl_b64 s[28:29], s[92:93], 12
	s_add_u32 s1, s4, s28
	s_addc_u32 s29, s5, s29
	s_lshl_b32 s28, s0, 2
	s_add_u32 s28, s1, s28
	s_addc_u32 s29, s29, 0
	v_lshl_add_u64 v[0:1], v[4:5], 2, s[28:29]
	v_add_co_u32_e32 v8, vcc, s11, v0
	s_movk_i32 s1, 0x4000
	s_nop 0
	v_addc_co_u32_e32 v9, vcc, 0, v1, vcc
	v_add_co_u32_e32 v10, vcc, s1, v0
	s_movk_i32 s1, 0x6000
	s_nop 0
	v_addc_co_u32_e32 v11, vcc, 0, v1, vcc
	v_add_co_u32_e32 v12, vcc, s1, v0
	s_mov_b32 s1, 0x8000
	s_nop 0
	v_addc_co_u32_e32 v13, vcc, 0, v1, vcc
	v_add_co_u32_e32 v14, vcc, s1, v0
	s_mov_b32 s1, 0xa000
	s_nop 0
	v_addc_co_u32_e32 v15, vcc, 0, v1, vcc
	s_waitcnt vmcnt(5)
	v_add_co_u32_e32 v16, vcc, s1, v0
	s_mov_b32 s1, 0xc000
	s_nop 0
	v_addc_co_u32_e32 v17, vcc, 0, v1, vcc
	v_add_co_u32_e32 v18, vcc, s1, v0
	s_mov_b32 s1, 0xe000
	s_nop 0
	v_addc_co_u32_e32 v19, vcc, 0, v1, vcc
	v_add_co_u32_e32 v20, vcc, s1, v0
	s_mov_b32 s1, 0x12000
	s_nop 0
	v_addc_co_u32_e32 v21, vcc, 0, v1, vcc
	v_add_co_u32_e32 v22, vcc, s67, v0
	global_load_dword v2, v[8:9], off offset:-4096 nt
	global_load_dword v3, v[0:1], off nt
	v_addc_co_u32_e32 v23, vcc, 0, v1, vcc
	global_load_dword v6, v[10:11], off offset:-4096 nt
	global_load_dword v7, v[8:9], off nt
	s_nop 0
	global_load_dword v8, v[12:13], off offset:-4096 nt
	global_load_dword v9, v[10:11], off nt
	s_nop 0
	global_load_dword v10, v[14:15], off offset:-4096 nt
	global_load_dword v11, v[12:13], off nt
	s_nop 0
	global_load_dword v12, v[16:17], off offset:-4096 nt
	global_load_dword v13, v[14:15], off nt
	s_nop 0
	global_load_dword v14, v[18:19], off offset:-4096 nt
	global_load_dword v15, v[16:17], off nt
	s_nop 0
	global_load_dword v16, v[20:21], off offset:-4096 nt
	global_load_dword v17, v[18:19], off nt
	s_nop 0
	global_load_dword v18, v[22:23], off offset:-4096 nt
	global_load_dword v19, v[20:21], off nt
	v_add_co_u32_e32 v20, vcc, s1, v0
	s_mov_b32 s1, 0x14000
	s_nop 0
	v_addc_co_u32_e32 v21, vcc, 0, v1, vcc
	global_load_dword v24, v[20:21], off offset:-4096 nt
	global_load_dword v25, v[22:23], off nt
	v_add_co_u32_e32 v22, vcc, s1, v0
	s_mov_b32 s1, 0x16000
	s_nop 0
	v_addc_co_u32_e32 v23, vcc, 0, v1, vcc
	global_load_dword v26, v[22:23], off offset:-4096 nt
	global_load_dword v27, v[20:21], off nt
	v_add_co_u32_e32 v20, vcc, s1, v0
	s_mov_b32 s1, 0x18000
	s_nop 0
	v_addc_co_u32_e32 v21, vcc, 0, v1, vcc
	global_load_dword v28, v[20:21], off offset:-4096 nt
	global_load_dword v29, v[22:23], off nt
	v_add_co_u32_e32 v22, vcc, s1, v0
	s_mov_b32 s1, 0x1a000
	s_nop 0
	v_addc_co_u32_e32 v23, vcc, 0, v1, vcc
	global_load_dword v30, v[22:23], off offset:-4096 nt
	global_load_dword v31, v[20:21], off nt
	v_add_co_u32_e32 v20, vcc, s1, v0
	s_mov_b32 s1, 0x1c000
	s_nop 0
	v_addc_co_u32_e32 v21, vcc, 0, v1, vcc
	global_load_dword v32, v[20:21], off offset:-4096 nt
	global_load_dword v33, v[22:23], off nt
	v_add_co_u32_e32 v22, vcc, s1, v0
	s_mov_b32 s1, 0x1e000
	s_nop 0
	v_addc_co_u32_e32 v23, vcc, 0, v1, vcc
	global_load_dword v34, v[22:23], off offset:-4096 nt
	global_load_dword v35, v[20:21], off nt
	v_add_co_u32_e32 v20, vcc, s1, v0
	s_mov_b32 s1, 0x20000
	s_nop 0
	v_addc_co_u32_e32 v21, vcc, 0, v1, vcc
	global_load_dword v36, v[20:21], off offset:-4096 nt
	global_load_dword v37, v[22:23], off nt
	v_add_co_u32_e32 v22, vcc, s1, v0
	s_mov_b32 s1, 0x22000
	s_nop 0
	v_addc_co_u32_e32 v23, vcc, 0, v1, vcc
	global_load_dword v38, v[22:23], off offset:-4096 nt
	global_load_dword v39, v[20:21], off nt
	v_add_co_u32_e32 v20, vcc, s1, v0
	s_mov_b32 s1, 0x24000
	s_nop 0
	v_addc_co_u32_e32 v21, vcc, 0, v1, vcc
	global_load_dword v40, v[20:21], off offset:-4096 nt
	global_load_dword v41, v[22:23], off nt
	v_add_co_u32_e32 v22, vcc, s1, v0
	s_mov_b32 s1, 0x26000
	s_nop 0
	v_addc_co_u32_e32 v23, vcc, 0, v1, vcc
	global_load_dword v42, v[22:23], off offset:-4096 nt
	global_load_dword v43, v[20:21], off nt
	v_add_co_u32_e32 v20, vcc, s1, v0
	s_mov_b32 s1, 0x2a000
	s_nop 0
	v_addc_co_u32_e32 v21, vcc, 0, v1, vcc
	global_load_dword v44, v[20:21], off offset:-4096 nt
	global_load_dword v45, v[22:23], off nt
	v_add_co_u32_e32 v22, vcc, s95, v0
	s_nop 1
	v_addc_co_u32_e32 v23, vcc, 0, v1, vcc
	global_load_dword v46, v[22:23], off offset:-4096 nt
	global_load_dword v47, v[20:21], off nt
	v_add_co_u32_e32 v20, vcc, s1, v0
	s_mov_b32 s1, 0x2c000
	s_nop 0
	v_addc_co_u32_e32 v21, vcc, 0, v1, vcc
	global_load_dword v48, v[20:21], off offset:-4096 nt
	global_load_dword v49, v[22:23], off nt
	v_add_co_u32_e32 v22, vcc, s1, v0
	s_mov_b32 s1, 0x2e000
	s_nop 0
	v_addc_co_u32_e32 v23, vcc, 0, v1, vcc
	global_load_dword v50, v[22:23], off offset:-4096 nt
	global_load_dword v51, v[20:21], off nt
	v_add_co_u32_e32 v20, vcc, s1, v0
	s_mov_b32 s1, 0x30000
	s_nop 0
	v_addc_co_u32_e32 v21, vcc, 0, v1, vcc
	global_load_dword v52, v[20:21], off offset:-4096 nt
	global_load_dword v53, v[22:23], off nt
	v_add_co_u32_e32 v22, vcc, s1, v0
	s_mov_b32 s1, 0x32000
	s_nop 0
	v_addc_co_u32_e32 v23, vcc, 0, v1, vcc
	global_load_dword v54, v[22:23], off offset:-4096 nt
	global_load_dword v55, v[20:21], off nt
	v_add_co_u32_e32 v20, vcc, s1, v0
	s_mov_b32 s1, 0x34000
	s_nop 0
	v_addc_co_u32_e32 v21, vcc, 0, v1, vcc
	global_load_dword v56, v[20:21], off offset:-4096 nt
	global_load_dword v57, v[22:23], off nt
	v_add_co_u32_e32 v22, vcc, s1, v0
	s_mov_b32 s1, 0x36000
	s_nop 0
	v_addc_co_u32_e32 v23, vcc, 0, v1, vcc
	global_load_dword v58, v[22:23], off offset:-4096 nt
	global_load_dword v59, v[20:21], off nt
	v_add_co_u32_e32 v20, vcc, s1, v0
	s_mov_b32 s1, 0x38000
	s_nop 0
	v_addc_co_u32_e32 v21, vcc, 0, v1, vcc
	global_load_dword v60, v[20:21], off offset:-4096 nt
	global_load_dword v61, v[22:23], off nt
	v_add_co_u32_e32 v22, vcc, s1, v0
	s_mov_b32 s1, 0x3a000
	s_nop 0
	v_addc_co_u32_e32 v23, vcc, 0, v1, vcc
	global_load_dword v62, v[22:23], off offset:-4096 nt
	global_load_dword v63, v[20:21], off nt
	v_add_co_u32_e32 v20, vcc, s1, v0
	s_mov_b32 s1, 0x3c000
	s_nop 0
	v_addc_co_u32_e32 v21, vcc, 0, v1, vcc
	global_load_dword v64, v[20:21], off offset:-4096 nt
	global_load_dword v65, v[22:23], off nt
	v_add_co_u32_e32 v22, vcc, s1, v0
	s_mov_b32 s1, 0x3e000
	s_nop 0
	v_addc_co_u32_e32 v23, vcc, 0, v1, vcc
	global_load_dword v68, v[22:23], off offset:-4096 nt
	global_load_dword v69, v[20:21], off nt
	v_add_co_u32_e32 v20, vcc, s1, v0
	s_mov_b32 s1, 0x3f000
	s_nop 0
	v_addc_co_u32_e32 v21, vcc, 0, v1, vcc
	v_add_co_u32_e32 v0, vcc, s1, v0
	global_load_dword v70, v[20:21], off offset:-4096 nt
	s_nop 0
	global_load_dword v22, v[22:23], off nt
	v_addc_co_u32_e32 v1, vcc, 0, v1, vcc
	global_load_dword v23, v[0:1], off nt
	s_nop 0
	global_load_dword v20, v[20:21], off nt
	v_add_u32_e32 v21, s0, v4
	v_mov_b64_e32 v[0:1], s[44:45]
	v_mad_i64_i32 v[0:1], s[0:1], v21, s25, v[0:1]
	v_lshl_add_u64 v[66:67], s[92:93], 1, v[0:1]
	s_waitcnt vmcnt(62)
	v_cvt_pk_bf16_f32 v0, v3, v2
	s_waitcnt vmcnt(60)
	v_cvt_pk_bf16_f32 v1, v7, v6
	s_waitcnt vmcnt(58)
	v_cvt_pk_bf16_f32 v2, v9, v8
	s_waitcnt vmcnt(56)
	v_cvt_pk_bf16_f32 v3, v11, v10
	global_store_dwordx4 v[66:67], v[0:3], off
	s_mov_b64 s[0:1], 0
	s_waitcnt vmcnt(55)
	v_cvt_pk_bf16_f32 v0, v13, v12
	s_waitcnt vmcnt(53)
	v_cvt_pk_bf16_f32 v1, v15, v14
	s_waitcnt vmcnt(51)
	v_cvt_pk_bf16_f32 v2, v17, v16
	s_waitcnt vmcnt(49)
	v_cvt_pk_bf16_f32 v3, v19, v18
	global_store_dwordx4 v[66:67], v[0:3], off offset:16
	s_waitcnt vmcnt(48)
	s_nop 0
	v_cvt_pk_bf16_f32 v0, v25, v24
	s_waitcnt vmcnt(46)
	v_cvt_pk_bf16_f32 v1, v27, v26
	s_waitcnt vmcnt(44)
	v_cvt_pk_bf16_f32 v2, v29, v28
	s_waitcnt vmcnt(42)
	v_cvt_pk_bf16_f32 v3, v31, v30
	global_store_dwordx4 v[66:67], v[0:3], off offset:32
	s_waitcnt vmcnt(41)
	s_nop 0
	v_cvt_pk_bf16_f32 v0, v33, v32
	s_waitcnt vmcnt(39)
	v_cvt_pk_bf16_f32 v1, v35, v34
	s_waitcnt vmcnt(37)
	v_cvt_pk_bf16_f32 v2, v37, v36
	s_waitcnt vmcnt(35)
	v_cvt_pk_bf16_f32 v3, v39, v38
	global_store_dwordx4 v[66:67], v[0:3], off offset:48
	s_waitcnt vmcnt(34)
	s_nop 0
	v_cvt_pk_bf16_f32 v0, v41, v40
	s_waitcnt vmcnt(32)
	v_cvt_pk_bf16_f32 v1, v43, v42
	s_waitcnt vmcnt(30)
	v_cvt_pk_bf16_f32 v2, v45, v44
	s_waitcnt vmcnt(28)
	v_cvt_pk_bf16_f32 v3, v47, v46
	global_store_dwordx4 v[66:67], v[0:3], off offset:64
	s_waitcnt vmcnt(27)
	s_nop 0
	v_cvt_pk_bf16_f32 v0, v49, v48
	s_waitcnt vmcnt(25)
	v_cvt_pk_bf16_f32 v1, v51, v50
	s_waitcnt vmcnt(23)
	v_cvt_pk_bf16_f32 v2, v53, v52
	s_waitcnt vmcnt(21)
	v_cvt_pk_bf16_f32 v3, v55, v54
	global_store_dwordx4 v[66:67], v[0:3], off offset:80
	s_waitcnt vmcnt(20)
	s_nop 0
	v_cvt_pk_bf16_f32 v0, v57, v56
	s_waitcnt vmcnt(18)
	v_cvt_pk_bf16_f32 v1, v59, v58
	s_waitcnt vmcnt(16)
	v_cvt_pk_bf16_f32 v2, v61, v60
	s_waitcnt vmcnt(14)
	v_cvt_pk_bf16_f32 v3, v63, v62
	global_store_dwordx4 v[66:67], v[0:3], off offset:96
	s_waitcnt vmcnt(13)
	s_nop 0
	v_cvt_pk_bf16_f32 v0, v65, v64
	s_waitcnt vmcnt(11)
	v_cvt_pk_bf16_f32 v1, v69, v68
	s_waitcnt vmcnt(9)
	v_cvt_pk_bf16_f32 v2, v22, v70
	s_waitcnt vmcnt(7)
	v_cvt_pk_bf16_f32 v3, v20, v23
.LBB0_801:
	s_andn2_b64 vcc, exec, s[0:1]
	s_cbranch_vccnz .LBB0_805
	s_add_i32 s0, s62, 0xf980
	s_and_b32 s1, s0, 0xffff
	s_mul_i32 s1, s1, 0xba2f
	s_lshr_b32 s28, s1, 16
	s_lshr_b32 s1, s1, 22
	s_mulk_i32 s1, 0x58
	s_sub_i32 s1, s0, s1
	s_and_b32 s0, s28, 0xffc0
	s_mul_i32 s28, s0, 0x5800
	s_add_u32 s28, s6, s28
	s_addc_u32 s29, s7, 0
	s_lshl_b32 s30, s1, 8
	s_and_b32 s30, s30, 0x3ff00
	s_add_u32 s28, s28, s30
	s_addc_u32 s29, s29, 0
	v_lshl_add_u64 v[66:67], v[4:5], 2, s[28:29]
	s_movk_i32 s28, 0x5000
	v_add_co_u32_e32 v2, vcc, s28, v66
	s_mov_b32 s28, 0xb000
	s_nop 0
	v_addc_co_u32_e32 v3, vcc, 0, v67, vcc
	global_load_dword v1, v[2:3], off offset:2048 nt
	v_add_co_u32_e32 v2, vcc, s28, v66
	s_mov_b32 s28, 0x16000
	s_nop 0
	v_addc_co_u32_e32 v3, vcc, 0, v67, vcc
	v_add_co_u32_e32 v6, vcc, s67, v66
	global_load_dword v0, v[66:67], off nt
	s_nop 0
	v_addc_co_u32_e32 v7, vcc, 0, v67, vcc
	global_load_dword v2, v[2:3], off nt
	s_nop 0
	global_load_dword v3, v[6:7], off offset:2048 nt
	v_add_co_u32_e32 v6, vcc, s28, v66
	s_mov_b32 s28, 0x1b000
	s_nop 0
	v_addc_co_u32_e32 v7, vcc, 0, v67, vcc
	v_add_co_u32_e32 v8, vcc, s28, v66
	s_mov_b32 s28, 0x21000
	s_nop 0
	v_addc_co_u32_e32 v9, vcc, 0, v67, vcc
	global_load_dword v6, v[6:7], off nt
	s_nop 0
	global_load_dword v7, v[8:9], off offset:2048 nt
	v_add_co_u32_e32 v8, vcc, s28, v66
	s_mov_b32 s28, 0x26000
	s_nop 0
	v_addc_co_u32_e32 v9, vcc, 0, v67, vcc
	v_add_co_u32_e32 v10, vcc, s28, v66
	s_mov_b32 s28, 0x2c000
	s_nop 0
	v_addc_co_u32_e32 v11, vcc, 0, v67, vcc
	global_load_dword v8, v[8:9], off nt
	s_nop 0
	global_load_dword v9, v[10:11], off offset:2048 nt
	v_add_co_u32_e32 v10, vcc, s28, v66
	s_mov_b32 s28, 0x31000
	s_nop 0
	v_addc_co_u32_e32 v11, vcc, 0, v67, vcc
	v_add_co_u32_e32 v12, vcc, s28, v66
	s_mov_b32 s28, 0x37000
	s_nop 0
	v_addc_co_u32_e32 v13, vcc, 0, v67, vcc
	global_load_dword v10, v[10:11], off nt
	s_nop 0
	global_load_dword v11, v[12:13], off offset:2048 nt
	v_add_co_u32_e32 v12, vcc, s28, v66
	s_mov_b32 s28, 0x3c000
	s_nop 0
	v_addc_co_u32_e32 v13, vcc, 0, v67, vcc
	v_add_co_u32_e32 v14, vcc, s28, v66
	s_mov_b32 s28, 0x42000
	s_nop 0
	v_addc_co_u32_e32 v15, vcc, 0, v67, vcc
	global_load_dword v12, v[12:13], off nt
	s_nop 0
	global_load_dword v13, v[14:15], off offset:2048 nt
	v_add_co_u32_e32 v14, vcc, s28, v66
	s_mov_b32 s28, 0x47000
	s_nop 0
	v_addc_co_u32_e32 v15, vcc, 0, v67, vcc
	s_waitcnt vmcnt(17)
	v_add_co_u32_e32 v16, vcc, s28, v66
	s_mov_b32 s28, 0x4d000
	s_nop 0
	v_addc_co_u32_e32 v17, vcc, 0, v67, vcc
	global_load_dword v14, v[14:15], off nt
	s_nop 0
	global_load_dword v15, v[16:17], off offset:2048 nt
	v_add_co_u32_e32 v16, vcc, s28, v66
	s_mov_b32 s28, 0x52000
	s_nop 0
	v_addc_co_u32_e32 v17, vcc, 0, v67, vcc
	v_add_co_u32_e32 v18, vcc, s28, v66
	s_mov_b32 s28, 0x58000
	s_nop 0
	v_addc_co_u32_e32 v19, vcc, 0, v67, vcc
	global_load_dword v16, v[16:17], off nt
	s_nop 0
	global_load_dword v17, v[18:19], off offset:2048 nt
	v_add_co_u32_e32 v18, vcc, s28, v66
	s_mov_b32 s28, 0x5d000
	s_nop 0
	v_addc_co_u32_e32 v19, vcc, 0, v67, vcc
	v_add_co_u32_e32 v20, vcc, s28, v66
	s_mov_b32 s28, 0x63000
	s_nop 0
	v_addc_co_u32_e32 v21, vcc, 0, v67, vcc
	global_load_dword v18, v[18:19], off nt
	s_nop 0
	global_load_dword v19, v[20:21], off offset:2048 nt
	v_add_co_u32_e32 v20, vcc, s28, v66
	s_mov_b32 s28, 0x68000
	s_nop 0
	v_addc_co_u32_e32 v21, vcc, 0, v67, vcc
	v_add_co_u32_e32 v22, vcc, s28, v66
	s_mov_b32 s28, 0x6e000
	s_nop 0
	v_addc_co_u32_e32 v23, vcc, 0, v67, vcc
	global_load_dword v20, v[20:21], off nt
	s_nop 0
	global_load_dword v21, v[22:23], off offset:2048 nt
	v_add_co_u32_e32 v22, vcc, s28, v66
	s_mov_b32 s28, 0x73000
	s_nop 0
	v_addc_co_u32_e32 v23, vcc, 0, v67, vcc
	v_add_co_u32_e32 v24, vcc, s28, v66
	s_mov_b32 s28, 0x79000
	s_nop 0
	v_addc_co_u32_e32 v25, vcc, 0, v67, vcc
	global_load_dword v22, v[22:23], off nt
	s_nop 0
	global_load_dword v23, v[24:25], off offset:2048 nt
	v_add_co_u32_e32 v24, vcc, s28, v66
	s_mov_b32 s28, 0x7e000
	s_nop 0
	v_addc_co_u32_e32 v25, vcc, 0, v67, vcc
	v_add_co_u32_e32 v26, vcc, s28, v66
	s_mov_b32 s28, 0x84000
	s_nop 0
	v_addc_co_u32_e32 v27, vcc, 0, v67, vcc
	global_load_dword v24, v[24:25], off nt
	s_nop 0
	global_load_dword v25, v[26:27], off offset:2048 nt
	v_add_co_u32_e32 v26, vcc, s28, v66
	s_mov_b32 s28, 0x89000
	s_nop 0
	v_addc_co_u32_e32 v27, vcc, 0, v67, vcc
	s_waitcnt vmcnt(28)
	v_add_co_u32_e32 v28, vcc, s28, v66
	s_mov_b32 s28, 0x8f000
	s_nop 0
	v_addc_co_u32_e32 v29, vcc, 0, v67, vcc
	global_load_dword v26, v[26:27], off nt
	s_nop 0
	global_load_dword v27, v[28:29], off offset:2048 nt
	v_add_co_u32_e32 v28, vcc, s28, v66
	s_mov_b32 s28, 0x94000
	s_nop 0
	v_addc_co_u32_e32 v29, vcc, 0, v67, vcc
	v_add_co_u32_e32 v30, vcc, s28, v66
	s_mov_b32 s28, 0x9a000
	s_nop 0
	v_addc_co_u32_e32 v31, vcc, 0, v67, vcc
	global_load_dword v28, v[28:29], off nt
	s_nop 0
	global_load_dword v29, v[30:31], off offset:2048 nt
	v_add_co_u32_e32 v30, vcc, s28, v66
	s_mov_b32 s28, 0x9f000
	s_nop 0
	v_addc_co_u32_e32 v31, vcc, 0, v67, vcc
	s_waitcnt vmcnt(29)
	v_add_co_u32_e32 v32, vcc, s28, v66
	s_mov_b32 s28, 0xa5000
	s_nop 0
	v_addc_co_u32_e32 v33, vcc, 0, v67, vcc
	global_load_dword v30, v[30:31], off nt
	s_nop 0
	global_load_dword v31, v[32:33], off offset:2048 nt
	v_add_co_u32_e32 v32, vcc, s28, v66
	s_mov_b32 s28, 0xaa000
	s_nop 0
	v_addc_co_u32_e32 v33, vcc, 0, v67, vcc
	v_add_co_u32_e32 v34, vcc, s28, v66
	s_mov_b32 s28, 0xb0000
	s_nop 0
	v_addc_co_u32_e32 v35, vcc, 0, v67, vcc
	global_load_dword v32, v[32:33], off nt
	s_nop 0
	global_load_dword v33, v[34:35], off offset:2048 nt
	v_add_co_u32_e32 v34, vcc, s28, v66
	s_mov_b32 s28, 0xb5000
	s_nop 0
	v_addc_co_u32_e32 v35, vcc, 0, v67, vcc
	s_waitcnt vmcnt(32)
	v_add_co_u32_e32 v36, vcc, s28, v66
	s_mov_b32 s28, 0xbb000
	s_nop 0
	v_addc_co_u32_e32 v37, vcc, 0, v67, vcc
	global_load_dword v34, v[34:35], off nt
	s_nop 0
	global_load_dword v35, v[36:37], off offset:2048 nt
	v_add_co_u32_e32 v36, vcc, s28, v66
	s_mov_b32 s28, 0xc0000
	s_nop 0
	v_addc_co_u32_e32 v37, vcc, 0, v67, vcc
	v_add_co_u32_e32 v38, vcc, s28, v66
	s_mov_b32 s28, 0xc6000
	s_nop 0
	v_addc_co_u32_e32 v39, vcc, 0, v67, vcc
	global_load_dword v36, v[36:37], off nt
	s_nop 0
	global_load_dword v37, v[38:39], off offset:2048 nt
	v_add_co_u32_e32 v38, vcc, s28, v66
	s_mov_b32 s28, 0xcb000
	s_nop 0
	v_addc_co_u32_e32 v39, vcc, 0, v67, vcc
	v_add_co_u32_e32 v40, vcc, s28, v66
	s_mov_b32 s28, 0xd1000
	s_nop 0
	v_addc_co_u32_e32 v41, vcc, 0, v67, vcc
	global_load_dword v38, v[38:39], off nt
	s_nop 0
	global_load_dword v39, v[40:41], off offset:2048 nt
	v_add_co_u32_e32 v40, vcc, s28, v66
	s_mov_b32 s28, 0xd6000
	s_nop 0
	v_addc_co_u32_e32 v41, vcc, 0, v67, vcc
	v_add_co_u32_e32 v42, vcc, s28, v66
	s_mov_b32 s28, 0xdc000
	s_nop 0
	v_addc_co_u32_e32 v43, vcc, 0, v67, vcc
	global_load_dword v40, v[40:41], off nt
	s_nop 0
	global_load_dword v41, v[42:43], off offset:2048 nt
	v_add_co_u32_e32 v42, vcc, s28, v66
	s_mov_b32 s28, 0xe1000
	s_nop 0
	v_addc_co_u32_e32 v43, vcc, 0, v67, vcc
	v_add_co_u32_e32 v44, vcc, s28, v66
	s_mov_b32 s28, 0xe7000
	s_nop 0
	v_addc_co_u32_e32 v45, vcc, 0, v67, vcc
	global_load_dword v42, v[42:43], off nt
	s_nop 0
	global_load_dword v43, v[44:45], off offset:2048 nt
	v_add_co_u32_e32 v44, vcc, s28, v66
	s_mov_b32 s28, 0xec000
	s_nop 0
	v_addc_co_u32_e32 v45, vcc, 0, v67, vcc
	v_add_co_u32_e32 v46, vcc, s28, v66
	s_mov_b32 s28, 0xf2000
	s_nop 0
	v_addc_co_u32_e32 v47, vcc, 0, v67, vcc
	global_load_dword v44, v[44:45], off nt
	s_nop 0
	global_load_dword v45, v[46:47], off offset:2048 nt
	v_add_co_u32_e32 v46, vcc, s28, v66
	s_mov_b32 s28, 0xf7000
	s_nop 0
	v_addc_co_u32_e32 v47, vcc, 0, v67, vcc
	v_add_co_u32_e32 v48, vcc, s28, v66
	s_mov_b32 s28, 0xfd000
	s_nop 0
	v_addc_co_u32_e32 v49, vcc, 0, v67, vcc
	global_load_dword v46, v[46:47], off nt
	s_nop 0
	global_load_dword v47, v[48:49], off offset:2048 nt
	v_add_co_u32_e32 v48, vcc, s28, v66
	s_mov_b32 s28, 0x102000
	s_nop 0
	v_addc_co_u32_e32 v49, vcc, 0, v67, vcc
	v_add_co_u32_e32 v50, vcc, s28, v66
	s_mov_b32 s28, 0x108000
	s_nop 0
	v_addc_co_u32_e32 v51, vcc, 0, v67, vcc
	global_load_dword v48, v[48:49], off nt
	s_nop 0
	global_load_dword v49, v[50:51], off offset:2048 nt
	v_add_co_u32_e32 v50, vcc, s28, v66
	s_mov_b32 s28, 0x10d000
	s_nop 0
	v_addc_co_u32_e32 v51, vcc, 0, v67, vcc
	v_add_co_u32_e32 v52, vcc, s28, v66
	s_mov_b32 s28, 0x113000
	s_nop 0
	v_addc_co_u32_e32 v53, vcc, 0, v67, vcc
	global_load_dword v50, v[50:51], off nt
	s_nop 0
	global_load_dword v51, v[52:53], off offset:2048 nt
	v_add_co_u32_e32 v52, vcc, s28, v66
	s_mov_b32 s28, 0x118000
	s_nop 0
	v_addc_co_u32_e32 v53, vcc, 0, v67, vcc
	v_add_co_u32_e32 v54, vcc, s28, v66
	s_mov_b32 s28, 0x11e000
	s_nop 0
	v_addc_co_u32_e32 v55, vcc, 0, v67, vcc
	global_load_dword v52, v[52:53], off nt
	s_nop 0
	global_load_dword v53, v[54:55], off offset:2048 nt
	v_add_co_u32_e32 v54, vcc, s28, v66
	s_mov_b32 s28, 0x123000
	s_nop 0
	v_addc_co_u32_e32 v55, vcc, 0, v67, vcc
	v_add_co_u32_e32 v56, vcc, s28, v66
	s_mov_b32 s28, 0x129000
	s_nop 0
	v_addc_co_u32_e32 v57, vcc, 0, v67, vcc
	global_load_dword v54, v[54:55], off nt
	s_nop 0
	global_load_dword v55, v[56:57], off offset:2048 nt
	v_add_co_u32_e32 v56, vcc, s28, v66
	s_mov_b32 s28, 0x12e000
	s_nop 0
	v_addc_co_u32_e32 v57, vcc, 0, v67, vcc
	v_add_co_u32_e32 v58, vcc, s28, v66
	s_mov_b32 s28, 0x134000
	s_nop 0
	v_addc_co_u32_e32 v59, vcc, 0, v67, vcc
	global_load_dword v56, v[56:57], off nt
	s_nop 0
	global_load_dword v57, v[58:59], off offset:2048 nt
	v_add_co_u32_e32 v58, vcc, s28, v66
	s_mov_b32 s28, 0x139000
	s_nop 0
	v_addc_co_u32_e32 v59, vcc, 0, v67, vcc
	v_add_co_u32_e32 v60, vcc, s28, v66
	s_mov_b32 s28, 0x13f000
	s_nop 0
	v_addc_co_u32_e32 v61, vcc, 0, v67, vcc
	global_load_dword v58, v[58:59], off nt
	s_nop 0
	global_load_dword v59, v[60:61], off offset:2048 nt
	v_add_co_u32_e32 v60, vcc, s28, v66
	s_mov_b32 s28, 0x144000
	s_nop 0
	v_addc_co_u32_e32 v61, vcc, 0, v67, vcc
	v_add_co_u32_e32 v62, vcc, s28, v66
	s_mov_b32 s28, 0x14a000
	s_nop 0
	v_addc_co_u32_e32 v63, vcc, 0, v67, vcc
	global_load_dword v60, v[60:61], off nt
	s_nop 0
	global_load_dword v61, v[62:63], off offset:2048 nt
	v_add_co_u32_e32 v62, vcc, s28, v66
	v_readlane_b32 s28, v253, 39
	s_nop 0
	v_addc_co_u32_e32 v63, vcc, 0, v67, vcc
	v_add_co_u32_e32 v64, vcc, 0x14f000, v66
	global_load_dword v62, v[62:63], off nt
	s_nop 0
	v_addc_co_u32_e32 v65, vcc, 0, v67, vcc
	global_load_dword v63, v[64:65], off offset:2048 nt
	v_add_co_u32_e32 v64, vcc, 0x155000, v66
	v_readlane_b32 s29, v253, 40
	s_nop 0
	v_addc_co_u32_e32 v65, vcc, 0, v67, vcc
	v_add_co_u32_e32 v66, vcc, 0x15a000, v66
	global_load_dword v64, v[64:65], off nt
	s_nop 0
	v_addc_co_u32_e32 v67, vcc, 0, v67, vcc
	global_load_dword v65, v[66:67], off offset:2048 nt
	s_andn2_b64 vcc, exec, s[28:29]
	s_cbranch_vccnz .LBB0_804
	s_lshl_b32 s28, s0, 2
	v_mov_b32_e32 v82, s28
	global_load_dwordx4 v[66:69], v82, s[56:57] offset:48
	global_load_dwordx4 v[70:73], v82, s[56:57] offset:32
	global_load_dwordx4 v[74:77], v82, s[56:57] offset:16
	global_load_dwordx4 v[78:81], v82, s[56:57]
	s_waitcnt vmcnt(3)
	v_pk_mul_f32 v[14:15], v[14:15], v[66:67]
	s_waitcnt vmcnt(2)
	v_pk_mul_f32 v[10:11], v[10:11], v[70:71]
	s_waitcnt vmcnt(1)
	v_pk_mul_f32 v[6:7], v[6:7], v[74:75]
	s_waitcnt vmcnt(0)
	v_pk_mul_f32 v[0:1], v[0:1], v[78:79]
	v_pk_mul_f32 v[2:3], v[2:3], v[80:81]
	v_pk_mul_f32 v[8:9], v[8:9], v[76:77]
	v_pk_mul_f32 v[12:13], v[12:13], v[72:73]
	v_pk_mul_f32 v[16:17], v[16:17], v[68:69]
	global_load_dwordx4 v[66:69], v82, s[56:57] offset:112
	global_load_dwordx4 v[70:73], v82, s[56:57] offset:96
	global_load_dwordx4 v[74:77], v82, s[56:57] offset:80
	global_load_dwordx4 v[78:81], v82, s[56:57] offset:64
	s_waitcnt vmcnt(3)
	v_pk_mul_f32 v[30:31], v[30:31], v[66:67]
	s_waitcnt vmcnt(2)
	v_pk_mul_f32 v[26:27], v[26:27], v[70:71]
	s_waitcnt vmcnt(1)
	v_pk_mul_f32 v[22:23], v[22:23], v[74:75]
	s_waitcnt vmcnt(0)
	v_pk_mul_f32 v[18:19], v[18:19], v[78:79]
	v_pk_mul_f32 v[20:21], v[20:21], v[80:81]
	v_pk_mul_f32 v[24:25], v[24:25], v[76:77]
	v_pk_mul_f32 v[28:29], v[28:29], v[72:73]
	v_pk_mul_f32 v[32:33], v[32:33], v[68:69]
	global_load_dwordx4 v[66:69], v82, s[56:57] offset:176
	global_load_dwordx4 v[70:73], v82, s[56:57] offset:160
	global_load_dwordx4 v[74:77], v82, s[56:57] offset:144
	global_load_dwordx4 v[78:81], v82, s[56:57] offset:128
	s_waitcnt vmcnt(3)
	v_pk_mul_f32 v[46:47], v[46:47], v[66:67]
	s_waitcnt vmcnt(2)
	v_pk_mul_f32 v[42:43], v[42:43], v[70:71]
	s_waitcnt vmcnt(1)
	v_pk_mul_f32 v[38:39], v[38:39], v[74:75]
	s_waitcnt vmcnt(0)
	v_pk_mul_f32 v[34:35], v[34:35], v[78:79]
	v_pk_mul_f32 v[36:37], v[36:37], v[80:81]
	v_pk_mul_f32 v[40:41], v[40:41], v[76:77]
	v_pk_mul_f32 v[44:45], v[44:45], v[72:73]
	v_pk_mul_f32 v[48:49], v[48:49], v[68:69]
	global_load_dwordx4 v[66:69], v82, s[56:57] offset:240
	global_load_dwordx4 v[70:73], v82, s[56:57] offset:224
	global_load_dwordx4 v[74:77], v82, s[56:57] offset:208
	global_load_dwordx4 v[78:81], v82, s[56:57] offset:192
	s_waitcnt vmcnt(3)
	v_pk_mul_f32 v[62:63], v[62:63], v[66:67]
	s_waitcnt vmcnt(2)
	v_pk_mul_f32 v[58:59], v[58:59], v[70:71]
	s_waitcnt vmcnt(1)
	v_pk_mul_f32 v[54:55], v[54:55], v[74:75]
	s_waitcnt vmcnt(0)
	v_pk_mul_f32 v[50:51], v[50:51], v[78:79]
	v_pk_mul_f32 v[52:53], v[52:53], v[80:81]
	v_pk_mul_f32 v[56:57], v[56:57], v[76:77]
	v_pk_mul_f32 v[60:61], v[60:61], v[72:73]
	v_pk_mul_f32 v[64:65], v[64:65], v[68:69]

.LBB0_806:
	s_andn2_b64 vcc, exec, s[0:1]
	s_cbranch_vccnz .LBB0_808
	s_and_b32 s0, s60, 0x3c0
	s_xor_b32 s0, s0, 0x200
	s_and_b32 s1, s12, 0x3c0
	s_lshl_b32 s28, s0, 12
	s_add_u32 s28, s27, s28
	s_addc_u32 s29, s36, 0
	s_lshl_b32 s30, s1, 2
	s_add_u32 s28, s28, s30
	s_addc_u32 s29, s29, 0
	v_lshl_add_u64 v[0:1], v[4:5], 2, s[28:29]
	v_add_co_u32_e32 v8, vcc, s11, v0
	s_movk_i32 s28, 0x4000
	s_nop 0
	v_addc_co_u32_e32 v9, vcc, 0, v1, vcc
	v_add_co_u32_e32 v10, vcc, s28, v0
	s_movk_i32 s28, 0x6000
	s_nop 0
	v_addc_co_u32_e32 v11, vcc, 0, v1, vcc
	v_add_co_u32_e32 v12, vcc, s28, v0
	s_mov_b32 s28, 0x8000
	s_nop 0
	v_addc_co_u32_e32 v13, vcc, 0, v1, vcc
	v_add_co_u32_e32 v14, vcc, s28, v0
	s_mov_b32 s28, 0xa000
	s_nop 0
	v_addc_co_u32_e32 v15, vcc, 0, v1, vcc
	s_waitcnt vmcnt(5)
	v_add_co_u32_e32 v16, vcc, s28, v0
	s_mov_b32 s28, 0xc000
	s_nop 0
	v_addc_co_u32_e32 v17, vcc, 0, v1, vcc
	v_add_co_u32_e32 v18, vcc, s28, v0
	s_mov_b32 s28, 0xe000
	s_nop 0
	v_addc_co_u32_e32 v19, vcc, 0, v1, vcc
	v_add_co_u32_e32 v20, vcc, s28, v0
	s_mov_b32 s28, 0x12000
	s_nop 0
	v_addc_co_u32_e32 v21, vcc, 0, v1, vcc
	v_add_co_u32_e32 v22, vcc, s67, v0
	global_load_dword v2, v[8:9], off offset:-4096 nt
	global_load_dword v3, v[0:1], off nt
	v_addc_co_u32_e32 v23, vcc, 0, v1, vcc
	global_load_dword v6, v[10:11], off offset:-4096 nt
	global_load_dword v7, v[8:9], off nt
	s_nop 0
	global_load_dword v8, v[12:13], off offset:-4096 nt
	global_load_dword v9, v[10:11], off nt
	s_nop 0
	global_load_dword v10, v[14:15], off offset:-4096 nt
	global_load_dword v11, v[12:13], off nt
	s_nop 0
	global_load_dword v12, v[16:17], off offset:-4096 nt
	global_load_dword v13, v[14:15], off nt
	s_nop 0
	global_load_dword v14, v[18:19], off offset:-4096 nt
	global_load_dword v15, v[16:17], off nt
	s_nop 0
	global_load_dword v16, v[20:21], off offset:-4096 nt
	global_load_dword v17, v[18:19], off nt
	s_nop 0
	global_load_dword v18, v[22:23], off offset:-4096 nt
	global_load_dword v19, v[20:21], off nt
	v_add_co_u32_e32 v20, vcc, s28, v0
	s_mov_b32 s28, 0x14000
	s_nop 0
	v_addc_co_u32_e32 v21, vcc, 0, v1, vcc
	global_load_dword v24, v[20:21], off offset:-4096 nt
	global_load_dword v25, v[22:23], off nt
	v_add_co_u32_e32 v22, vcc, s28, v0
	s_mov_b32 s28, 0x16000
	s_nop 0
	v_addc_co_u32_e32 v23, vcc, 0, v1, vcc
	global_load_dword v26, v[22:23], off offset:-4096 nt
	global_load_dword v27, v[20:21], off nt
	v_add_co_u32_e32 v20, vcc, s28, v0
	s_mov_b32 s28, 0x18000
	s_nop 0
	v_addc_co_u32_e32 v21, vcc, 0, v1, vcc
	global_load_dword v28, v[20:21], off offset:-4096 nt
	global_load_dword v29, v[22:23], off nt
	v_add_co_u32_e32 v22, vcc, s28, v0
	s_mov_b32 s28, 0x1a000
	s_nop 0
	v_addc_co_u32_e32 v23, vcc, 0, v1, vcc
	global_load_dword v30, v[22:23], off offset:-4096 nt
	global_load_dword v31, v[20:21], off nt
	v_add_co_u32_e32 v20, vcc, s28, v0
	s_mov_b32 s28, 0x1c000
	s_nop 0
	v_addc_co_u32_e32 v21, vcc, 0, v1, vcc
	global_load_dword v32, v[20:21], off offset:-4096 nt
	global_load_dword v33, v[22:23], off nt
	v_add_co_u32_e32 v22, vcc, s28, v0
	s_mov_b32 s28, 0x1e000
	s_nop 0
	v_addc_co_u32_e32 v23, vcc, 0, v1, vcc
	global_load_dword v34, v[22:23], off offset:-4096 nt
	global_load_dword v35, v[20:21], off nt
	v_add_co_u32_e32 v20, vcc, s28, v0
	s_mov_b32 s28, 0x20000
	s_nop 0
	v_addc_co_u32_e32 v21, vcc, 0, v1, vcc
	global_load_dword v36, v[20:21], off offset:-4096 nt
	global_load_dword v37, v[22:23], off nt
	v_add_co_u32_e32 v22, vcc, s28, v0
	s_mov_b32 s28, 0x22000
	s_nop 0
	v_addc_co_u32_e32 v23, vcc, 0, v1, vcc
	global_load_dword v38, v[22:23], off offset:-4096 nt
	global_load_dword v39, v[20:21], off nt
	v_add_co_u32_e32 v20, vcc, s28, v0
	s_mov_b32 s28, 0x24000
	s_nop 0
	v_addc_co_u32_e32 v21, vcc, 0, v1, vcc
	global_load_dword v40, v[20:21], off offset:-4096 nt
	global_load_dword v41, v[22:23], off nt
	v_add_co_u32_e32 v22, vcc, s28, v0
	s_mov_b32 s28, 0x26000
	s_nop 0
	v_addc_co_u32_e32 v23, vcc, 0, v1, vcc
	global_load_dword v42, v[22:23], off offset:-4096 nt
	global_load_dword v43, v[20:21], off nt
	v_add_co_u32_e32 v20, vcc, s28, v0
	s_mov_b32 s28, 0x2a000
	s_nop 0
	v_addc_co_u32_e32 v21, vcc, 0, v1, vcc
	global_load_dword v44, v[20:21], off offset:-4096 nt
	global_load_dword v45, v[22:23], off nt
	v_add_co_u32_e32 v22, vcc, s95, v0
	s_lshl_b32 s92, s0, 1
	s_nop 0
	v_addc_co_u32_e32 v23, vcc, 0, v1, vcc
	global_load_dword v46, v[22:23], off offset:-4096 nt
	global_load_dword v47, v[20:21], off nt
	v_add_co_u32_e32 v20, vcc, s28, v0
	s_mov_b32 s28, 0x2c000
	s_nop 0
	v_addc_co_u32_e32 v21, vcc, 0, v1, vcc
	global_load_dword v48, v[20:21], off offset:-4096 nt
	global_load_dword v49, v[22:23], off nt
	v_add_co_u32_e32 v22, vcc, s28, v0
	s_mov_b32 s28, 0x2e000
	s_nop 0
	v_addc_co_u32_e32 v23, vcc, 0, v1, vcc
	global_load_dword v50, v[22:23], off offset:-4096 nt
	global_load_dword v51, v[20:21], off nt
	v_add_co_u32_e32 v20, vcc, s28, v0
	s_mov_b32 s28, 0x30000
	s_nop 0
	v_addc_co_u32_e32 v21, vcc, 0, v1, vcc
	global_load_dword v52, v[20:21], off offset:-4096 nt
	global_load_dword v53, v[22:23], off nt
	v_add_co_u32_e32 v22, vcc, s28, v0
	s_mov_b32 s28, 0x32000
	s_nop 0
	v_addc_co_u32_e32 v23, vcc, 0, v1, vcc
	global_load_dword v54, v[22:23], off offset:-4096 nt
	global_load_dword v55, v[20:21], off nt
	v_add_co_u32_e32 v20, vcc, s28, v0
	s_mov_b32 s28, 0x34000
	s_nop 0
	v_addc_co_u32_e32 v21, vcc, 0, v1, vcc
	global_load_dword v56, v[20:21], off offset:-4096 nt
	global_load_dword v57, v[22:23], off nt
	v_add_co_u32_e32 v22, vcc, s28, v0
	s_mov_b32 s28, 0x36000
	s_nop 0
	v_addc_co_u32_e32 v23, vcc, 0, v1, vcc
	global_load_dword v58, v[22:23], off offset:-4096 nt
	global_load_dword v59, v[20:21], off nt
	v_add_co_u32_e32 v20, vcc, s28, v0
	s_mov_b32 s28, 0x38000
	s_nop 0
	v_addc_co_u32_e32 v21, vcc, 0, v1, vcc
	global_load_dword v60, v[20:21], off offset:-4096 nt
	global_load_dword v61, v[22:23], off nt
	v_add_co_u32_e32 v22, vcc, s28, v0
	s_mov_b32 s28, 0x3a000
	s_nop 0
	v_addc_co_u32_e32 v23, vcc, 0, v1, vcc
	global_load_dword v62, v[22:23], off offset:-4096 nt
	global_load_dword v63, v[20:21], off nt
	v_add_co_u32_e32 v20, vcc, s28, v0
	s_mov_b32 s28, 0x3c000
	s_nop 0
	v_addc_co_u32_e32 v21, vcc, 0, v1, vcc
	global_load_dword v64, v[20:21], off offset:-4096 nt
	global_load_dword v65, v[22:23], off nt
	v_add_co_u32_e32 v22, vcc, s28, v0
	s_mov_b32 s28, 0x3e000
	s_nop 0
	v_addc_co_u32_e32 v23, vcc, 0, v1, vcc
	global_load_dword v68, v[22:23], off offset:-4096 nt
	global_load_dword v69, v[20:21], off nt
	v_add_co_u32_e32 v20, vcc, s28, v0
	s_mov_b32 s28, 0x3f000
	s_nop 0
	v_addc_co_u32_e32 v21, vcc, 0, v1, vcc
	v_add_co_u32_e32 v0, vcc, s28, v0
	global_load_dword v70, v[20:21], off offset:-4096 nt
	s_nop 0
	global_load_dword v22, v[22:23], off nt
	v_addc_co_u32_e32 v1, vcc, 0, v1, vcc
	global_load_dword v23, v[0:1], off nt
	s_nop 0
	global_load_dword v20, v[20:21], off nt
	v_add_u32_e32 v0, s1, v4
	v_ashrrev_i32_e32 v1, 31, v0
	v_lshlrev_b64 v[0:1], 11, v[0:1]
	v_lshl_add_u64 v[0:1], s[50:51], 0, v[0:1]
	v_lshl_add_u64 v[66:67], v[0:1], 0, s[92:93]
	s_waitcnt vmcnt(62)
	v_cvt_pk_bf16_f32 v0, v3, v2
	s_waitcnt vmcnt(60)
	v_cvt_pk_bf16_f32 v1, v7, v6
	s_waitcnt vmcnt(58)
	v_cvt_pk_bf16_f32 v2, v9, v8
	s_waitcnt vmcnt(56)
	v_cvt_pk_bf16_f32 v3, v11, v10
	global_store_dwordx4 v[66:67], v[0:3], off
	s_waitcnt vmcnt(55)
	s_nop 0
	v_cvt_pk_bf16_f32 v0, v13, v12
	s_waitcnt vmcnt(53)
	v_cvt_pk_bf16_f32 v1, v15, v14
	s_waitcnt vmcnt(51)
	v_cvt_pk_bf16_f32 v2, v17, v16
	s_waitcnt vmcnt(49)
	v_cvt_pk_bf16_f32 v3, v19, v18
	global_store_dwordx4 v[66:67], v[0:3], off offset:16
	s_waitcnt vmcnt(48)
	s_nop 0
	v_cvt_pk_bf16_f32 v0, v25, v24
	s_waitcnt vmcnt(46)
	v_cvt_pk_bf16_f32 v1, v27, v26
	s_waitcnt vmcnt(44)
	v_cvt_pk_bf16_f32 v2, v29, v28
	s_waitcnt vmcnt(42)
	v_cvt_pk_bf16_f32 v3, v31, v30
	global_store_dwordx4 v[66:67], v[0:3], off offset:32
	s_waitcnt vmcnt(41)
	s_nop 0
	v_cvt_pk_bf16_f32 v0, v33, v32
	s_waitcnt vmcnt(39)
	v_cvt_pk_bf16_f32 v1, v35, v34
	s_waitcnt vmcnt(37)
	v_cvt_pk_bf16_f32 v2, v37, v36
	s_waitcnt vmcnt(35)
	v_cvt_pk_bf16_f32 v3, v39, v38
	global_store_dwordx4 v[66:67], v[0:3], off offset:48
	s_waitcnt vmcnt(34)
	s_nop 0
	v_cvt_pk_bf16_f32 v0, v41, v40
	s_waitcnt vmcnt(32)
	v_cvt_pk_bf16_f32 v1, v43, v42
	s_waitcnt vmcnt(30)
	v_cvt_pk_bf16_f32 v2, v45, v44
	s_waitcnt vmcnt(28)
	v_cvt_pk_bf16_f32 v3, v47, v46
	global_store_dwordx4 v[66:67], v[0:3], off offset:64
	s_waitcnt vmcnt(27)
	s_nop 0
	v_cvt_pk_bf16_f32 v0, v49, v48
	s_waitcnt vmcnt(25)
	v_cvt_pk_bf16_f32 v1, v51, v50
	s_waitcnt vmcnt(23)
	v_cvt_pk_bf16_f32 v2, v53, v52
	s_waitcnt vmcnt(21)
	v_cvt_pk_bf16_f32 v3, v55, v54
	global_store_dwordx4 v[66:67], v[0:3], off offset:80
	s_waitcnt vmcnt(20)
	s_nop 0
	v_cvt_pk_bf16_f32 v0, v57, v56
	s_waitcnt vmcnt(18)
	v_cvt_pk_bf16_f32 v1, v59, v58
	s_waitcnt vmcnt(16)
	v_cvt_pk_bf16_f32 v2, v61, v60
	s_waitcnt vmcnt(14)
	v_cvt_pk_bf16_f32 v3, v63, v62
	global_store_dwordx4 v[66:67], v[0:3], off offset:96
	s_waitcnt vmcnt(13)
	s_nop 0
	v_cvt_pk_bf16_f32 v0, v65, v64
	s_waitcnt vmcnt(11)
	v_cvt_pk_bf16_f32 v1, v69, v68
	s_waitcnt vmcnt(9)
	v_cvt_pk_bf16_f32 v2, v22, v70
	s_waitcnt vmcnt(7)
	v_cvt_pk_bf16_f32 v3, v20, v23

.LBB0_809:
	s_andn2_b64 vcc, exec, s[0:1]
	s_cbranch_vccnz .LBB0_811
	s_add_i32 s0, s60, 0x300
	s_and_b32 s0, s0, 0x3c0
	s_and_b32 s1, s12, 0x3c0
	s_lshl_b32 s28, s0, 12
	s_add_u32 s28, s37, s28
	s_addc_u32 s29, s38, 0
	s_lshl_b32 s30, s1, 2
	s_add_u32 s28, s28, s30
	s_addc_u32 s29, s29, 0
	v_lshl_add_u64 v[0:1], v[4:5], 2, s[28:29]
	v_add_co_u32_e32 v8, vcc, s11, v0
	s_movk_i32 s28, 0x4000
	s_nop 0
	v_addc_co_u32_e32 v9, vcc, 0, v1, vcc
	v_add_co_u32_e32 v10, vcc, s28, v0
	s_movk_i32 s28, 0x6000
	s_nop 0
	v_addc_co_u32_e32 v11, vcc, 0, v1, vcc
	v_add_co_u32_e32 v12, vcc, s28, v0
	s_mov_b32 s28, 0x8000
	s_nop 0
	v_addc_co_u32_e32 v13, vcc, 0, v1, vcc
	v_add_co_u32_e32 v14, vcc, s28, v0
	s_mov_b32 s28, 0xa000
	s_nop 0
	v_addc_co_u32_e32 v15, vcc, 0, v1, vcc
	s_waitcnt vmcnt(5)
	v_add_co_u32_e32 v16, vcc, s28, v0
	s_mov_b32 s28, 0xc000
	s_nop 0
	v_addc_co_u32_e32 v17, vcc, 0, v1, vcc
	v_add_co_u32_e32 v18, vcc, s28, v0
	s_mov_b32 s28, 0xe000
	s_nop 0
	v_addc_co_u32_e32 v19, vcc, 0, v1, vcc
	v_add_co_u32_e32 v20, vcc, s28, v0
	s_mov_b32 s28, 0x12000
	s_nop 0
	v_addc_co_u32_e32 v21, vcc, 0, v1, vcc
	v_add_co_u32_e32 v22, vcc, s67, v0
	global_load_dword v2, v[8:9], off offset:-4096 nt
	global_load_dword v3, v[0:1], off nt
	v_addc_co_u32_e32 v23, vcc, 0, v1, vcc
	global_load_dword v6, v[10:11], off offset:-4096 nt
	global_load_dword v7, v[8:9], off nt
	s_nop 0
	global_load_dword v8, v[12:13], off offset:-4096 nt
	global_load_dword v9, v[10:11], off nt
	s_nop 0
	global_load_dword v10, v[14:15], off offset:-4096 nt
	global_load_dword v11, v[12:13], off nt
	s_nop 0
	global_load_dword v12, v[16:17], off offset:-4096 nt
	global_load_dword v13, v[14:15], off nt
	s_nop 0
	global_load_dword v14, v[18:19], off offset:-4096 nt
	global_load_dword v15, v[16:17], off nt
	s_nop 0
	global_load_dword v16, v[20:21], off offset:-4096 nt
	global_load_dword v17, v[18:19], off nt
	s_nop 0
	global_load_dword v18, v[22:23], off offset:-4096 nt
	global_load_dword v19, v[20:21], off nt
	v_add_co_u32_e32 v20, vcc, s28, v0
	s_mov_b32 s28, 0x14000
	s_nop 0
	v_addc_co_u32_e32 v21, vcc, 0, v1, vcc
	global_load_dword v24, v[20:21], off offset:-4096 nt
	global_load_dword v25, v[22:23], off nt
	v_add_co_u32_e32 v22, vcc, s28, v0
	s_mov_b32 s28, 0x16000
	s_nop 0
	v_addc_co_u32_e32 v23, vcc, 0, v1, vcc
	global_load_dword v26, v[22:23], off offset:-4096 nt
	global_load_dword v27, v[20:21], off nt
	v_add_co_u32_e32 v20, vcc, s28, v0
	s_mov_b32 s28, 0x18000
	s_nop 0
	v_addc_co_u32_e32 v21, vcc, 0, v1, vcc
	global_load_dword v28, v[20:21], off offset:-4096 nt
	global_load_dword v29, v[22:23], off nt
	v_add_co_u32_e32 v22, vcc, s28, v0
	s_mov_b32 s28, 0x1a000
	s_nop 0
	v_addc_co_u32_e32 v23, vcc, 0, v1, vcc
	global_load_dword v30, v[22:23], off offset:-4096 nt
	global_load_dword v31, v[20:21], off nt
	v_add_co_u32_e32 v20, vcc, s28, v0
	s_mov_b32 s28, 0x1c000
	s_nop 0
	v_addc_co_u32_e32 v21, vcc, 0, v1, vcc
	global_load_dword v32, v[20:21], off offset:-4096 nt
	global_load_dword v33, v[22:23], off nt
	v_add_co_u32_e32 v22, vcc, s28, v0
	s_mov_b32 s28, 0x1e000
	s_nop 0
	v_addc_co_u32_e32 v23, vcc, 0, v1, vcc
	global_load_dword v34, v[22:23], off offset:-4096 nt
	global_load_dword v35, v[20:21], off nt
	v_add_co_u32_e32 v20, vcc, s28, v0
	s_mov_b32 s28, 0x20000
	s_nop 0
	v_addc_co_u32_e32 v21, vcc, 0, v1, vcc
	global_load_dword v36, v[20:21], off offset:-4096 nt
	global_load_dword v37, v[22:23], off nt
	v_add_co_u32_e32 v22, vcc, s28, v0
	s_mov_b32 s28, 0x22000
	s_nop 0
	v_addc_co_u32_e32 v23, vcc, 0, v1, vcc
	global_load_dword v38, v[22:23], off offset:-4096 nt
	global_load_dword v39, v[20:21], off nt
	v_add_co_u32_e32 v20, vcc, s28, v0
	s_mov_b32 s28, 0x24000
	s_nop 0
	v_addc_co_u32_e32 v21, vcc, 0, v1, vcc
	global_load_dword v40, v[20:21], off offset:-4096 nt
	global_load_dword v41, v[22:23], off nt
	v_add_co_u32_e32 v22, vcc, s28, v0
	s_mov_b32 s28, 0x26000
	s_nop 0
	v_addc_co_u32_e32 v23, vcc, 0, v1, vcc
	global_load_dword v42, v[22:23], off offset:-4096 nt
	global_load_dword v43, v[20:21], off nt
	v_add_co_u32_e32 v20, vcc, s28, v0
	s_mov_b32 s28, 0x2a000
	s_nop 0
	v_addc_co_u32_e32 v21, vcc, 0, v1, vcc
	global_load_dword v44, v[20:21], off offset:-4096 nt
	global_load_dword v45, v[22:23], off nt
	v_add_co_u32_e32 v22, vcc, s95, v0
	s_lshl_b32 s92, s0, 1
	s_nop 0
	v_addc_co_u32_e32 v23, vcc, 0, v1, vcc
	global_load_dword v46, v[22:23], off offset:-4096 nt
	global_load_dword v47, v[20:21], off nt
	v_add_co_u32_e32 v20, vcc, s28, v0
	s_mov_b32 s28, 0x2c000
	s_nop 0
	v_addc_co_u32_e32 v21, vcc, 0, v1, vcc
	global_load_dword v48, v[20:21], off offset:-4096 nt
	global_load_dword v49, v[22:23], off nt
	v_add_co_u32_e32 v22, vcc, s28, v0
	s_mov_b32 s28, 0x2e000
	s_nop 0
	v_addc_co_u32_e32 v23, vcc, 0, v1, vcc
	global_load_dword v50, v[22:23], off offset:-4096 nt
	global_load_dword v51, v[20:21], off nt
	v_add_co_u32_e32 v20, vcc, s28, v0
	s_mov_b32 s28, 0x30000
	s_nop 0
	v_addc_co_u32_e32 v21, vcc, 0, v1, vcc
	global_load_dword v52, v[20:21], off offset:-4096 nt
	global_load_dword v53, v[22:23], off nt
	v_add_co_u32_e32 v22, vcc, s28, v0
	s_mov_b32 s28, 0x32000
	s_nop 0
	v_addc_co_u32_e32 v23, vcc, 0, v1, vcc
	global_load_dword v54, v[22:23], off offset:-4096 nt
	global_load_dword v55, v[20:21], off nt
	v_add_co_u32_e32 v20, vcc, s28, v0
	s_mov_b32 s28, 0x34000
	s_nop 0
	v_addc_co_u32_e32 v21, vcc, 0, v1, vcc
	global_load_dword v56, v[20:21], off offset:-4096 nt
	global_load_dword v57, v[22:23], off nt
	v_add_co_u32_e32 v22, vcc, s28, v0
	s_mov_b32 s28, 0x36000
	s_nop 0
	v_addc_co_u32_e32 v23, vcc, 0, v1, vcc
	global_load_dword v58, v[22:23], off offset:-4096 nt
	global_load_dword v59, v[20:21], off nt
	v_add_co_u32_e32 v20, vcc, s28, v0
	s_mov_b32 s28, 0x38000
	s_nop 0
	v_addc_co_u32_e32 v21, vcc, 0, v1, vcc
	global_load_dword v60, v[20:21], off offset:-4096 nt
	global_load_dword v61, v[22:23], off nt
	v_add_co_u32_e32 v22, vcc, s28, v0
	s_mov_b32 s28, 0x3a000
	s_nop 0
	v_addc_co_u32_e32 v23, vcc, 0, v1, vcc
	global_load_dword v62, v[22:23], off offset:-4096 nt
	global_load_dword v63, v[20:21], off nt
	v_add_co_u32_e32 v20, vcc, s28, v0
	s_mov_b32 s28, 0x3c000
	s_nop 0
	v_addc_co_u32_e32 v21, vcc, 0, v1, vcc
	global_load_dword v64, v[20:21], off offset:-4096 nt
	global_load_dword v65, v[22:23], off nt
	v_add_co_u32_e32 v22, vcc, s28, v0
	s_mov_b32 s28, 0x3e000
	s_nop 0
	v_addc_co_u32_e32 v23, vcc, 0, v1, vcc
	global_load_dword v68, v[22:23], off offset:-4096 nt
	global_load_dword v69, v[20:21], off nt
	v_add_co_u32_e32 v20, vcc, s28, v0
	s_mov_b32 s28, 0x3f000
	s_nop 0
	v_addc_co_u32_e32 v21, vcc, 0, v1, vcc
	v_add_co_u32_e32 v0, vcc, s28, v0
	global_load_dword v70, v[20:21], off offset:-4096 nt
	s_nop 0
	global_load_dword v22, v[22:23], off nt
	v_addc_co_u32_e32 v1, vcc, 0, v1, vcc
	global_load_dword v23, v[0:1], off nt
	s_nop 0
	global_load_dword v20, v[20:21], off nt
	v_add_u32_e32 v0, s1, v4
	v_ashrrev_i32_e32 v1, 31, v0
	v_lshlrev_b64 v[0:1], 9, v[0:1]
	v_lshl_add_u64 v[0:1], s[52:53], 0, v[0:1]
	v_lshl_add_u64 v[66:67], v[0:1], 0, s[92:93]
	s_waitcnt vmcnt(62)
	v_cvt_pk_bf16_f32 v0, v3, v2
	s_waitcnt vmcnt(60)
	v_cvt_pk_bf16_f32 v1, v7, v6
	s_waitcnt vmcnt(58)
	v_cvt_pk_bf16_f32 v2, v9, v8
	s_waitcnt vmcnt(56)
	v_cvt_pk_bf16_f32 v3, v11, v10
	global_store_dwordx4 v[66:67], v[0:3], off
	s_waitcnt vmcnt(55)
	s_nop 0
	v_cvt_pk_bf16_f32 v0, v13, v12
	s_waitcnt vmcnt(53)
	v_cvt_pk_bf16_f32 v1, v15, v14
	s_waitcnt vmcnt(51)
	v_cvt_pk_bf16_f32 v2, v17, v16
	s_waitcnt vmcnt(49)
	v_cvt_pk_bf16_f32 v3, v19, v18
	global_store_dwordx4 v[66:67], v[0:3], off offset:16
	s_waitcnt vmcnt(48)
	s_nop 0
	v_cvt_pk_bf16_f32 v0, v25, v24
	s_waitcnt vmcnt(46)
	v_cvt_pk_bf16_f32 v1, v27, v26
	s_waitcnt vmcnt(44)
	v_cvt_pk_bf16_f32 v2, v29, v28
	s_waitcnt vmcnt(42)
	v_cvt_pk_bf16_f32 v3, v31, v30
	global_store_dwordx4 v[66:67], v[0:3], off offset:32
	s_waitcnt vmcnt(41)
	s_nop 0
	v_cvt_pk_bf16_f32 v0, v33, v32
	s_waitcnt vmcnt(39)
	v_cvt_pk_bf16_f32 v1, v35, v34
	s_waitcnt vmcnt(37)
	v_cvt_pk_bf16_f32 v2, v37, v36
	s_waitcnt vmcnt(35)
	v_cvt_pk_bf16_f32 v3, v39, v38
	global_store_dwordx4 v[66:67], v[0:3], off offset:48
	s_waitcnt vmcnt(34)
	s_nop 0
	v_cvt_pk_bf16_f32 v0, v41, v40
	s_waitcnt vmcnt(32)
	v_cvt_pk_bf16_f32 v1, v43, v42
	s_waitcnt vmcnt(30)
	v_cvt_pk_bf16_f32 v2, v45, v44
	s_waitcnt vmcnt(28)
	v_cvt_pk_bf16_f32 v3, v47, v46
	global_store_dwordx4 v[66:67], v[0:3], off offset:64
	s_waitcnt vmcnt(27)
	s_nop 0
	v_cvt_pk_bf16_f32 v0, v49, v48
	s_waitcnt vmcnt(25)
	v_cvt_pk_bf16_f32 v1, v51, v50
	s_waitcnt vmcnt(23)
	v_cvt_pk_bf16_f32 v2, v53, v52
	s_waitcnt vmcnt(21)
	v_cvt_pk_bf16_f32 v3, v55, v54
	global_store_dwordx4 v[66:67], v[0:3], off offset:80
	s_waitcnt vmcnt(20)
	s_nop 0
	v_cvt_pk_bf16_f32 v0, v57, v56
	s_waitcnt vmcnt(18)
	v_cvt_pk_bf16_f32 v1, v59, v58
	s_waitcnt vmcnt(16)
	v_cvt_pk_bf16_f32 v2, v61, v60
	s_waitcnt vmcnt(14)
	v_cvt_pk_bf16_f32 v3, v63, v62
	global_store_dwordx4 v[66:67], v[0:3], off offset:96
	s_waitcnt vmcnt(13)
	s_nop 0
	v_cvt_pk_bf16_f32 v0, v65, v64
	s_waitcnt vmcnt(11)
	v_cvt_pk_bf16_f32 v1, v69, v68
	s_waitcnt vmcnt(9)
	v_cvt_pk_bf16_f32 v2, v22, v70
	s_waitcnt vmcnt(7)
	v_cvt_pk_bf16_f32 v3, v20, v23

.LBB0_812:
	s_andn2_b64 vcc, exec, s[0:1]
	s_cbranch_vccnz .LBB0_814
	s_and_b32 s0, s60, 0x3c0
	s_and_b32 s1, s12, 0x3c0
	s_lshl_b32 s28, s0, 12
	s_add_u32 s28, s39, s28
	s_addc_u32 s29, s40, 0
	s_lshl_b32 s30, s1, 2
	s_add_u32 s28, s28, s30
	s_addc_u32 s29, s29, 0
	v_lshl_add_u64 v[0:1], v[4:5], 2, s[28:29]
	v_add_co_u32_e32 v8, vcc, s11, v0
	s_movk_i32 s28, 0x4000
	s_nop 0
	v_addc_co_u32_e32 v9, vcc, 0, v1, vcc
	v_add_co_u32_e32 v10, vcc, s28, v0
	s_movk_i32 s28, 0x6000
	s_nop 0
	v_addc_co_u32_e32 v11, vcc, 0, v1, vcc
	v_add_co_u32_e32 v12, vcc, s28, v0
	s_mov_b32 s28, 0x8000
	s_nop 0
	v_addc_co_u32_e32 v13, vcc, 0, v1, vcc
	v_add_co_u32_e32 v14, vcc, s28, v0
	s_mov_b32 s28, 0xa000
	s_nop 0
	v_addc_co_u32_e32 v15, vcc, 0, v1, vcc
	s_waitcnt vmcnt(5)
	v_add_co_u32_e32 v16, vcc, s28, v0
	s_mov_b32 s28, 0xc000
	s_nop 0
	v_addc_co_u32_e32 v17, vcc, 0, v1, vcc
	v_add_co_u32_e32 v18, vcc, s28, v0
	s_mov_b32 s28, 0xe000
	s_nop 0
	v_addc_co_u32_e32 v19, vcc, 0, v1, vcc
	v_add_co_u32_e32 v20, vcc, s28, v0
	s_mov_b32 s28, 0x12000
	s_nop 0
	v_addc_co_u32_e32 v21, vcc, 0, v1, vcc
	v_add_co_u32_e32 v22, vcc, s67, v0
	global_load_dword v2, v[8:9], off offset:-4096 nt
	global_load_dword v3, v[0:1], off nt
	v_addc_co_u32_e32 v23, vcc, 0, v1, vcc
	global_load_dword v6, v[10:11], off offset:-4096 nt
	global_load_dword v7, v[8:9], off nt
	s_nop 0
	global_load_dword v8, v[12:13], off offset:-4096 nt
	global_load_dword v9, v[10:11], off nt
	s_nop 0
	global_load_dword v10, v[14:15], off offset:-4096 nt
	global_load_dword v11, v[12:13], off nt
	s_nop 0
	global_load_dword v12, v[16:17], off offset:-4096 nt
	global_load_dword v13, v[14:15], off nt
	s_nop 0
	global_load_dword v14, v[18:19], off offset:-4096 nt
	global_load_dword v15, v[16:17], off nt
	s_nop 0
	global_load_dword v16, v[20:21], off offset:-4096 nt
	global_load_dword v17, v[18:19], off nt
	s_nop 0
	global_load_dword v18, v[22:23], off offset:-4096 nt
	global_load_dword v19, v[20:21], off nt
	v_add_co_u32_e32 v20, vcc, s28, v0
	s_mov_b32 s28, 0x14000
	s_nop 0
	v_addc_co_u32_e32 v21, vcc, 0, v1, vcc
	global_load_dword v24, v[20:21], off offset:-4096 nt
	global_load_dword v25, v[22:23], off nt
	v_add_co_u32_e32 v22, vcc, s28, v0
	s_mov_b32 s28, 0x16000
	s_nop 0
	v_addc_co_u32_e32 v23, vcc, 0, v1, vcc
	global_load_dword v26, v[22:23], off offset:-4096 nt
	global_load_dword v27, v[20:21], off nt
	v_add_co_u32_e32 v20, vcc, s28, v0
	s_mov_b32 s28, 0x18000
	s_nop 0
	v_addc_co_u32_e32 v21, vcc, 0, v1, vcc
	global_load_dword v28, v[20:21], off offset:-4096 nt
	global_load_dword v29, v[22:23], off nt
	v_add_co_u32_e32 v22, vcc, s28, v0
	s_mov_b32 s28, 0x1a000
	s_nop 0
	v_addc_co_u32_e32 v23, vcc, 0, v1, vcc
	global_load_dword v30, v[22:23], off offset:-4096 nt
	global_load_dword v31, v[20:21], off nt
	v_add_co_u32_e32 v20, vcc, s28, v0
	s_mov_b32 s28, 0x1c000
	s_nop 0
	v_addc_co_u32_e32 v21, vcc, 0, v1, vcc
	global_load_dword v32, v[20:21], off offset:-4096 nt
	global_load_dword v33, v[22:23], off nt
	v_add_co_u32_e32 v22, vcc, s28, v0
	s_mov_b32 s28, 0x1e000
	s_nop 0
	v_addc_co_u32_e32 v23, vcc, 0, v1, vcc
	global_load_dword v34, v[22:23], off offset:-4096 nt
	global_load_dword v35, v[20:21], off nt
	v_add_co_u32_e32 v20, vcc, s28, v0
	s_mov_b32 s28, 0x20000
	s_nop 0
	v_addc_co_u32_e32 v21, vcc, 0, v1, vcc
	global_load_dword v36, v[20:21], off offset:-4096 nt
	global_load_dword v37, v[22:23], off nt
	v_add_co_u32_e32 v22, vcc, s28, v0
	s_mov_b32 s28, 0x22000
	s_nop 0
	v_addc_co_u32_e32 v23, vcc, 0, v1, vcc
	global_load_dword v38, v[22:23], off offset:-4096 nt
	global_load_dword v39, v[20:21], off nt
	v_add_co_u32_e32 v20, vcc, s28, v0
	s_mov_b32 s28, 0x24000
	s_nop 0
	v_addc_co_u32_e32 v21, vcc, 0, v1, vcc
	global_load_dword v40, v[20:21], off offset:-4096 nt
	global_load_dword v41, v[22:23], off nt
	v_add_co_u32_e32 v22, vcc, s28, v0
	s_mov_b32 s28, 0x26000
	s_nop 0
	v_addc_co_u32_e32 v23, vcc, 0, v1, vcc
	global_load_dword v42, v[22:23], off offset:-4096 nt
	global_load_dword v43, v[20:21], off nt
	v_add_co_u32_e32 v20, vcc, s28, v0
	s_mov_b32 s28, 0x2a000
	s_nop 0
	v_addc_co_u32_e32 v21, vcc, 0, v1, vcc
	global_load_dword v44, v[20:21], off offset:-4096 nt
	global_load_dword v45, v[22:23], off nt
	v_add_co_u32_e32 v22, vcc, s95, v0
	s_lshl_b32 s92, s0, 1
	s_nop 0
	v_addc_co_u32_e32 v23, vcc, 0, v1, vcc
	global_load_dword v46, v[22:23], off offset:-4096 nt
	global_load_dword v47, v[20:21], off nt
	v_add_co_u32_e32 v20, vcc, s28, v0
	s_mov_b32 s28, 0x2c000
	s_nop 0
	v_addc_co_u32_e32 v21, vcc, 0, v1, vcc
	global_load_dword v48, v[20:21], off offset:-4096 nt
	global_load_dword v49, v[22:23], off nt
	v_add_co_u32_e32 v22, vcc, s28, v0
	s_mov_b32 s28, 0x2e000
	s_nop 0
	v_addc_co_u32_e32 v23, vcc, 0, v1, vcc
	global_load_dword v50, v[22:23], off offset:-4096 nt
	global_load_dword v51, v[20:21], off nt
	v_add_co_u32_e32 v20, vcc, s28, v0
	s_mov_b32 s28, 0x30000
	s_nop 0
	v_addc_co_u32_e32 v21, vcc, 0, v1, vcc
	global_load_dword v52, v[20:21], off offset:-4096 nt
	global_load_dword v53, v[22:23], off nt
	v_add_co_u32_e32 v22, vcc, s28, v0
	s_mov_b32 s28, 0x32000
	s_nop 0
	v_addc_co_u32_e32 v23, vcc, 0, v1, vcc
	global_load_dword v54, v[22:23], off offset:-4096 nt
	global_load_dword v55, v[20:21], off nt
	v_add_co_u32_e32 v20, vcc, s28, v0
	s_mov_b32 s28, 0x34000
	s_nop 0
	v_addc_co_u32_e32 v21, vcc, 0, v1, vcc
	global_load_dword v56, v[20:21], off offset:-4096 nt
	global_load_dword v57, v[22:23], off nt
	v_add_co_u32_e32 v22, vcc, s28, v0
	s_mov_b32 s28, 0x36000
	s_nop 0
	v_addc_co_u32_e32 v23, vcc, 0, v1, vcc
	global_load_dword v58, v[22:23], off offset:-4096 nt
	global_load_dword v59, v[20:21], off nt
	v_add_co_u32_e32 v20, vcc, s28, v0
	s_mov_b32 s28, 0x38000
	s_nop 0
	v_addc_co_u32_e32 v21, vcc, 0, v1, vcc
	global_load_dword v60, v[20:21], off offset:-4096 nt
	global_load_dword v61, v[22:23], off nt
	v_add_co_u32_e32 v22, vcc, s28, v0
	s_mov_b32 s28, 0x3a000
	s_nop 0
	v_addc_co_u32_e32 v23, vcc, 0, v1, vcc
	global_load_dword v62, v[22:23], off offset:-4096 nt
	global_load_dword v63, v[20:21], off nt
	v_add_co_u32_e32 v20, vcc, s28, v0
	s_mov_b32 s28, 0x3c000
	s_nop 0
	v_addc_co_u32_e32 v21, vcc, 0, v1, vcc
	global_load_dword v64, v[20:21], off offset:-4096 nt
	global_load_dword v65, v[22:23], off nt
	v_add_co_u32_e32 v22, vcc, s28, v0
	s_mov_b32 s28, 0x3e000
	s_nop 0
	v_addc_co_u32_e32 v23, vcc, 0, v1, vcc
	global_load_dword v68, v[22:23], off offset:-4096 nt
	global_load_dword v69, v[20:21], off nt
	v_add_co_u32_e32 v20, vcc, s28, v0
	s_mov_b32 s28, 0x3f000
	s_nop 0
	v_addc_co_u32_e32 v21, vcc, 0, v1, vcc
	v_add_co_u32_e32 v0, vcc, s28, v0
	global_load_dword v70, v[20:21], off offset:-4096 nt
	s_nop 0
	global_load_dword v22, v[22:23], off nt
	v_addc_co_u32_e32 v1, vcc, 0, v1, vcc
	global_load_dword v23, v[0:1], off nt
	s_nop 0
	global_load_dword v20, v[20:21], off nt
	v_add_u32_e32 v0, s1, v4
	v_ashrrev_i32_e32 v1, 31, v0
	v_lshlrev_b64 v[0:1], 9, v[0:1]
	v_lshl_add_u64 v[0:1], s[54:55], 0, v[0:1]
	v_lshl_add_u64 v[66:67], v[0:1], 0, s[92:93]
	s_waitcnt vmcnt(62)
	v_cvt_pk_bf16_f32 v0, v3, v2
	s_waitcnt vmcnt(60)
	v_cvt_pk_bf16_f32 v1, v7, v6
	s_waitcnt vmcnt(58)
	v_cvt_pk_bf16_f32 v2, v9, v8
	s_waitcnt vmcnt(56)
	v_cvt_pk_bf16_f32 v3, v11, v10
	global_store_dwordx4 v[66:67], v[0:3], off
	s_waitcnt vmcnt(55)
	s_nop 0
	v_cvt_pk_bf16_f32 v0, v13, v12
	s_waitcnt vmcnt(53)
	v_cvt_pk_bf16_f32 v1, v15, v14
	s_waitcnt vmcnt(51)
	v_cvt_pk_bf16_f32 v2, v17, v16
	s_waitcnt vmcnt(49)
	v_cvt_pk_bf16_f32 v3, v19, v18
	global_store_dwordx4 v[66:67], v[0:3], off offset:16
	s_waitcnt vmcnt(48)
	s_nop 0
	v_cvt_pk_bf16_f32 v0, v25, v24
	s_waitcnt vmcnt(46)
	v_cvt_pk_bf16_f32 v1, v27, v26
	s_waitcnt vmcnt(44)
	v_cvt_pk_bf16_f32 v2, v29, v28
	s_waitcnt vmcnt(42)
	v_cvt_pk_bf16_f32 v3, v31, v30
	global_store_dwordx4 v[66:67], v[0:3], off offset:32
	s_waitcnt vmcnt(41)
	s_nop 0
	v_cvt_pk_bf16_f32 v0, v33, v32
	s_waitcnt vmcnt(39)
	v_cvt_pk_bf16_f32 v1, v35, v34
	s_waitcnt vmcnt(37)
	v_cvt_pk_bf16_f32 v2, v37, v36
	s_waitcnt vmcnt(35)
	v_cvt_pk_bf16_f32 v3, v39, v38
	global_store_dwordx4 v[66:67], v[0:3], off offset:48
	s_waitcnt vmcnt(34)
	s_nop 0
	v_cvt_pk_bf16_f32 v0, v41, v40
	s_waitcnt vmcnt(32)
	v_cvt_pk_bf16_f32 v1, v43, v42
	s_waitcnt vmcnt(30)
	v_cvt_pk_bf16_f32 v2, v45, v44
	s_waitcnt vmcnt(28)
	v_cvt_pk_bf16_f32 v3, v47, v46
	global_store_dwordx4 v[66:67], v[0:3], off offset:64
	s_waitcnt vmcnt(27)
	s_nop 0
	v_cvt_pk_bf16_f32 v0, v49, v48
	s_waitcnt vmcnt(25)
	v_cvt_pk_bf16_f32 v1, v51, v50
	s_waitcnt vmcnt(23)
	v_cvt_pk_bf16_f32 v2, v53, v52
	s_waitcnt vmcnt(21)
	v_cvt_pk_bf16_f32 v3, v55, v54
	global_store_dwordx4 v[66:67], v[0:3], off offset:80
	s_waitcnt vmcnt(20)
	s_nop 0
	v_cvt_pk_bf16_f32 v0, v57, v56
	s_waitcnt vmcnt(18)
	v_cvt_pk_bf16_f32 v1, v59, v58
	s_waitcnt vmcnt(16)
	v_cvt_pk_bf16_f32 v2, v61, v60
	s_waitcnt vmcnt(14)
	v_cvt_pk_bf16_f32 v3, v63, v62
	global_store_dwordx4 v[66:67], v[0:3], off offset:96
	s_waitcnt vmcnt(13)
	s_nop 0
	v_cvt_pk_bf16_f32 v0, v65, v64
	s_waitcnt vmcnt(11)
	v_cvt_pk_bf16_f32 v1, v69, v68
	s_waitcnt vmcnt(9)
	v_cvt_pk_bf16_f32 v2, v22, v70
	s_waitcnt vmcnt(7)
	v_cvt_pk_bf16_f32 v3, v20, v23

.LBB0_815:
	s_andn2_b64 vcc, exec, s[0:1]
	s_cbranch_vccnz .LBB0_794
	s_mul_hi_i32 s0, s62, 0x66666667
	s_lshr_b32 s1, s0, 31
	s_ashr_i32 s0, s0, 5
	s_add_i32 s0, s0, s1
	s_lshl_b32 s28, s0, 6
	s_mul_i32 s1, s0, 0xffffec00
	s_add_i32 s30, s12, s1
	s_ashr_i32 s29, s28, 31
	s_mul_i32 s0, s0, 0x140000
	s_mul_hi_i32 s1, s28, 0x5000
	s_add_u32 s63, s41, s0
	s_addc_u32 s64, s47, s1
	s_ashr_i32 s31, s30, 31
	s_lshl_b64 s[0:1], s[30:31], 2
	s_add_u32 s0, s63, s0
	s_addc_u32 s1, s64, s1
	v_lshl_add_u64 v[66:67], v[4:5], 2, s[0:1]
	s_movk_i32 s0, 0x5000
	v_add_co_u32_e32 v2, vcc, s0, v66
	s_mov_b32 s0, 0xa000
	s_nop 0
	v_addc_co_u32_e32 v3, vcc, 0, v67, vcc
	global_load_dword v0, v[66:67], off nt
	global_load_dword v1, v[2:3], off nt
	v_add_co_u32_e32 v2, vcc, s0, v66
	s_mov_b32 s0, 0xf000
	s_nop 0
	v_addc_co_u32_e32 v3, vcc, 0, v67, vcc
	v_add_co_u32_e32 v6, vcc, s0, v66
	s_mov_b32 s0, 0x14000
	s_nop 0
	v_addc_co_u32_e32 v7, vcc, 0, v67, vcc
	global_load_dword v2, v[2:3], off nt
	s_nop 0
	global_load_dword v3, v[6:7], off nt
	v_add_co_u32_e32 v6, vcc, s0, v66
	s_mov_b32 s0, 0x1e000
	s_nop 0
	v_addc_co_u32_e32 v7, vcc, 0, v67, vcc
	v_add_co_u32_e32 v8, vcc, s66, v66
	global_load_dword v6, v[6:7], off nt
	s_nop 0
	v_addc_co_u32_e32 v9, vcc, 0, v67, vcc
	global_load_dword v7, v[8:9], off nt
	v_add_co_u32_e32 v8, vcc, s0, v66
	s_mov_b32 s0, 0x23000
	s_nop 0
	v_addc_co_u32_e32 v9, vcc, 0, v67, vcc
	v_add_co_u32_e32 v10, vcc, s0, v66
	global_load_dword v8, v[8:9], off nt
	s_nop 0
	v_addc_co_u32_e32 v11, vcc, 0, v67, vcc
	global_load_dword v9, v[10:11], off nt
	v_add_co_u32_e32 v10, vcc, s95, v66
	s_mov_b32 s0, 0x2d000
	s_nop 0
	v_addc_co_u32_e32 v11, vcc, 0, v67, vcc
	v_add_co_u32_e32 v12, vcc, s0, v66
	s_mov_b32 s0, 0x32000
	s_nop 0
	v_addc_co_u32_e32 v13, vcc, 0, v67, vcc
	global_load_dword v10, v[10:11], off nt
	s_nop 0
	global_load_dword v11, v[12:13], off nt
	v_add_co_u32_e32 v12, vcc, s0, v66
	s_mov_b32 s0, 0x37000
	s_nop 0
	v_addc_co_u32_e32 v13, vcc, 0, v67, vcc
	v_add_co_u32_e32 v14, vcc, s0, v66
	s_mov_b32 s0, 0x3c000
	s_nop 0
	v_addc_co_u32_e32 v15, vcc, 0, v67, vcc
	global_load_dword v12, v[12:13], off nt
	s_nop 0
	global_load_dword v13, v[14:15], off nt
	v_add_co_u32_e32 v14, vcc, s0, v66
	s_mov_b32 s0, 0x41000
	s_nop 0
	v_addc_co_u32_e32 v15, vcc, 0, v67, vcc
	s_waitcnt vmcnt(17)
	v_add_co_u32_e32 v16, vcc, s0, v66
	s_mov_b32 s0, 0x46000
	s_nop 0
	v_addc_co_u32_e32 v17, vcc, 0, v67, vcc
	global_load_dword v14, v[14:15], off nt
	s_nop 0
	global_load_dword v15, v[16:17], off nt
	v_add_co_u32_e32 v16, vcc, s0, v66
	s_mov_b32 s0, 0x4b000
	s_nop 0
	v_addc_co_u32_e32 v17, vcc, 0, v67, vcc
	v_add_co_u32_e32 v18, vcc, s0, v66
	s_mov_b32 s0, 0x50000
	s_nop 0
	v_addc_co_u32_e32 v19, vcc, 0, v67, vcc
	global_load_dword v16, v[16:17], off nt
	s_nop 0
	global_load_dword v17, v[18:19], off nt
	v_add_co_u32_e32 v18, vcc, s0, v66
	s_mov_b32 s0, 0x55000
	s_nop 0
	v_addc_co_u32_e32 v19, vcc, 0, v67, vcc
	v_add_co_u32_e32 v20, vcc, s0, v66
	s_mov_b32 s0, 0x5a000
	s_nop 0
	v_addc_co_u32_e32 v21, vcc, 0, v67, vcc
	global_load_dword v18, v[18:19], off nt
	s_nop 0
	global_load_dword v19, v[20:21], off nt
	v_add_co_u32_e32 v20, vcc, s0, v66
	s_mov_b32 s0, 0x5f000
	s_nop 0
	v_addc_co_u32_e32 v21, vcc, 0, v67, vcc
	v_add_co_u32_e32 v22, vcc, s0, v66
	s_mov_b32 s0, 0x64000
	s_nop 0
	v_addc_co_u32_e32 v23, vcc, 0, v67, vcc
	global_load_dword v20, v[20:21], off nt
	s_nop 0
	global_load_dword v21, v[22:23], off nt
	v_add_co_u32_e32 v22, vcc, s0, v66
	s_mov_b32 s0, 0x69000
	s_nop 0
	v_addc_co_u32_e32 v23, vcc, 0, v67, vcc
	v_add_co_u32_e32 v24, vcc, s0, v66
	s_mov_b32 s0, 0x6e000
	s_nop 0
	v_addc_co_u32_e32 v25, vcc, 0, v67, vcc
	global_load_dword v22, v[22:23], off nt
	s_nop 0
	global_load_dword v23, v[24:25], off nt
	v_add_co_u32_e32 v24, vcc, s0, v66
	s_mov_b32 s0, 0x73000
	s_nop 0
	v_addc_co_u32_e32 v25, vcc, 0, v67, vcc
	v_add_co_u32_e32 v26, vcc, s0, v66
	s_mov_b32 s0, 0x78000
	s_nop 0
	v_addc_co_u32_e32 v27, vcc, 0, v67, vcc
	global_load_dword v24, v[24:25], off nt
	s_nop 0
	global_load_dword v25, v[26:27], off nt
	v_add_co_u32_e32 v26, vcc, s0, v66
	s_mov_b32 s0, 0x7d000
	s_nop 0
	v_addc_co_u32_e32 v27, vcc, 0, v67, vcc
	s_waitcnt vmcnt(28)
	v_add_co_u32_e32 v28, vcc, s0, v66
	s_mov_b32 s0, 0x82000
	s_nop 0
	v_addc_co_u32_e32 v29, vcc, 0, v67, vcc
	global_load_dword v26, v[26:27], off nt
	s_nop 0
	global_load_dword v27, v[28:29], off nt
	v_add_co_u32_e32 v28, vcc, s0, v66
	s_mov_b32 s0, 0x87000
	s_nop 0
	v_addc_co_u32_e32 v29, vcc, 0, v67, vcc
	v_add_co_u32_e32 v30, vcc, s0, v66
	s_mov_b32 s0, 0x8c000
	s_nop 0
	v_addc_co_u32_e32 v31, vcc, 0, v67, vcc
	global_load_dword v28, v[28:29], off nt
	s_nop 0
	global_load_dword v29, v[30:31], off nt
	v_add_co_u32_e32 v30, vcc, s0, v66
	s_mov_b32 s0, 0x91000
	s_nop 0
	v_addc_co_u32_e32 v31, vcc, 0, v67, vcc
	s_waitcnt vmcnt(29)
	v_add_co_u32_e32 v32, vcc, s0, v66
	s_mov_b32 s0, 0x96000
	s_nop 0
	v_addc_co_u32_e32 v33, vcc, 0, v67, vcc
	global_load_dword v30, v[30:31], off nt
	s_nop 0
	global_load_dword v31, v[32:33], off nt
	v_add_co_u32_e32 v32, vcc, s0, v66
	s_mov_b32 s0, 0x9b000
	s_nop 0
	v_addc_co_u32_e32 v33, vcc, 0, v67, vcc
	v_add_co_u32_e32 v34, vcc, s0, v66
	s_mov_b32 s0, 0xa0000
	s_nop 0
	v_addc_co_u32_e32 v35, vcc, 0, v67, vcc
	global_load_dword v32, v[32:33], off nt
	s_nop 0
	global_load_dword v33, v[34:35], off nt
	v_add_co_u32_e32 v34, vcc, s0, v66
	s_mov_b32 s0, 0xa5000
	s_nop 0
	v_addc_co_u32_e32 v35, vcc, 0, v67, vcc
	s_waitcnt vmcnt(32)
	v_add_co_u32_e32 v36, vcc, s0, v66
	s_mov_b32 s0, 0xaa000
	s_nop 0
	v_addc_co_u32_e32 v37, vcc, 0, v67, vcc
	global_load_dword v34, v[34:35], off nt
	s_nop 0
	global_load_dword v35, v[36:37], off nt
	v_add_co_u32_e32 v36, vcc, s0, v66
	s_mov_b32 s0, 0xaf000
	s_nop 0
	v_addc_co_u32_e32 v37, vcc, 0, v67, vcc
	v_add_co_u32_e32 v38, vcc, s0, v66
	s_mov_b32 s0, 0xb4000
	s_nop 0
	v_addc_co_u32_e32 v39, vcc, 0, v67, vcc
	global_load_dword v36, v[36:37], off nt
	s_nop 0
	global_load_dword v37, v[38:39], off nt
	v_add_co_u32_e32 v38, vcc, s0, v66
	s_mov_b32 s0, 0xb9000
	s_nop 0
	v_addc_co_u32_e32 v39, vcc, 0, v67, vcc
	v_add_co_u32_e32 v40, vcc, s0, v66
	s_mov_b32 s0, 0xbe000
	s_nop 0
	v_addc_co_u32_e32 v41, vcc, 0, v67, vcc
	global_load_dword v38, v[38:39], off nt
	s_nop 0
	global_load_dword v39, v[40:41], off nt
	v_add_co_u32_e32 v40, vcc, s0, v66
	s_mov_b32 s0, 0xc3000
	s_nop 0
	v_addc_co_u32_e32 v41, vcc, 0, v67, vcc
	v_add_co_u32_e32 v42, vcc, s0, v66
	s_mov_b32 s0, 0xc8000
	s_nop 0
	v_addc_co_u32_e32 v43, vcc, 0, v67, vcc
	global_load_dword v40, v[40:41], off nt
	s_nop 0
	global_load_dword v41, v[42:43], off nt
	v_add_co_u32_e32 v42, vcc, s0, v66
	s_mov_b32 s0, 0xcd000
	s_nop 0
	v_addc_co_u32_e32 v43, vcc, 0, v67, vcc
	v_add_co_u32_e32 v44, vcc, s0, v66
	s_mov_b32 s0, 0xd2000
	s_nop 0
	v_addc_co_u32_e32 v45, vcc, 0, v67, vcc
	global_load_dword v42, v[42:43], off nt
	s_nop 0
	global_load_dword v43, v[44:45], off nt
	v_add_co_u32_e32 v44, vcc, s0, v66
	s_mov_b32 s0, 0xd7000
	s_nop 0
	v_addc_co_u32_e32 v45, vcc, 0, v67, vcc
	v_add_co_u32_e32 v46, vcc, s0, v66
	s_mov_b32 s0, 0xdc000
	s_nop 0
	v_addc_co_u32_e32 v47, vcc, 0, v67, vcc
	global_load_dword v44, v[44:45], off nt
	s_nop 0
	global_load_dword v45, v[46:47], off nt
	v_add_co_u32_e32 v46, vcc, s0, v66
	s_mov_b32 s0, 0xe1000
	s_nop 0
	v_addc_co_u32_e32 v47, vcc, 0, v67, vcc
	v_add_co_u32_e32 v48, vcc, s0, v66
	s_mov_b32 s0, 0xe6000
	s_nop 0
	v_addc_co_u32_e32 v49, vcc, 0, v67, vcc
	global_load_dword v46, v[46:47], off nt
	s_nop 0
	global_load_dword v47, v[48:49], off nt
	v_add_co_u32_e32 v48, vcc, s0, v66
	s_mov_b32 s0, 0xeb000
	s_nop 0
	v_addc_co_u32_e32 v49, vcc, 0, v67, vcc
	v_add_co_u32_e32 v50, vcc, s0, v66
	s_mov_b32 s0, 0xf0000
	s_nop 0
	v_addc_co_u32_e32 v51, vcc, 0, v67, vcc
	global_load_dword v48, v[48:49], off nt
	s_nop 0
	global_load_dword v49, v[50:51], off nt
	v_add_co_u32_e32 v50, vcc, s0, v66
	s_mov_b32 s0, 0xf5000
	s_nop 0
	v_addc_co_u32_e32 v51, vcc, 0, v67, vcc
	v_add_co_u32_e32 v52, vcc, s0, v66
	s_mov_b32 s0, 0xfa000
	s_nop 0
	v_addc_co_u32_e32 v53, vcc, 0, v67, vcc
	global_load_dword v50, v[50:51], off nt
	s_nop 0
	global_load_dword v51, v[52:53], off nt
	v_add_co_u32_e32 v52, vcc, s0, v66
	s_mov_b32 s0, 0xff000
	s_nop 0
	v_addc_co_u32_e32 v53, vcc, 0, v67, vcc
	v_add_co_u32_e32 v54, vcc, s0, v66
	s_mov_b32 s0, 0x104000
	s_nop 0
	v_addc_co_u32_e32 v55, vcc, 0, v67, vcc
	global_load_dword v52, v[52:53], off nt
	s_nop 0
	global_load_dword v53, v[54:55], off nt
	v_add_co_u32_e32 v54, vcc, s0, v66
	s_mov_b32 s0, 0x109000
	s_nop 0
	v_addc_co_u32_e32 v55, vcc, 0, v67, vcc
	v_add_co_u32_e32 v56, vcc, s0, v66
	s_mov_b32 s0, 0x10e000
	s_nop 0
	v_addc_co_u32_e32 v57, vcc, 0, v67, vcc
	global_load_dword v54, v[54:55], off nt
	s_nop 0
	global_load_dword v55, v[56:57], off nt
	v_add_co_u32_e32 v56, vcc, s0, v66
	s_mov_b32 s0, 0x113000
	s_nop 0
	v_addc_co_u32_e32 v57, vcc, 0, v67, vcc
	v_add_co_u32_e32 v58, vcc, s0, v66
	s_mov_b32 s0, 0x118000
	s_nop 0
	v_addc_co_u32_e32 v59, vcc, 0, v67, vcc
	global_load_dword v56, v[56:57], off nt
	s_nop 0
	global_load_dword v57, v[58:59], off nt
	v_add_co_u32_e32 v58, vcc, s0, v66
	s_mov_b32 s0, 0x11d000
	s_nop 0
	v_addc_co_u32_e32 v59, vcc, 0, v67, vcc
	v_add_co_u32_e32 v60, vcc, s0, v66
	s_mov_b32 s0, 0x122000
	s_nop 0
	v_addc_co_u32_e32 v61, vcc, 0, v67, vcc
	global_load_dword v58, v[58:59], off nt
	s_nop 0
	global_load_dword v59, v[60:61], off nt
	v_add_co_u32_e32 v60, vcc, s0, v66
	s_mov_b32 s0, 0x127000
	s_nop 0
	v_addc_co_u32_e32 v61, vcc, 0, v67, vcc
	v_add_co_u32_e32 v62, vcc, s0, v66
	s_mov_b32 s0, 0x12c000
	s_nop 0
	v_addc_co_u32_e32 v63, vcc, 0, v67, vcc
	global_load_dword v60, v[60:61], off nt
	s_nop 0
	global_load_dword v61, v[62:63], off nt
	v_add_co_u32_e32 v62, vcc, s0, v66
	v_readlane_b32 s0, v253, 57
	s_nop 0
	v_addc_co_u32_e32 v63, vcc, 0, v67, vcc
	v_add_co_u32_e32 v64, vcc, 0x131000, v66
	global_load_dword v62, v[62:63], off nt
	s_nop 0
	v_addc_co_u32_e32 v65, vcc, 0, v67, vcc
	global_load_dword v63, v[64:65], off nt
	v_add_co_u32_e32 v64, vcc, 0x136000, v66
	v_readlane_b32 s1, v253, 58
	s_nop 0
	v_addc_co_u32_e32 v65, vcc, 0, v67, vcc
	v_add_co_u32_e32 v66, vcc, 0x13b000, v66
	global_load_dword v64, v[64:65], off nt
	s_nop 0
	v_addc_co_u32_e32 v67, vcc, 0, v67, vcc
	global_load_dword v65, v[66:67], off nt
	s_andn2_b64 vcc, exec, s[0:1]
	s_cbranch_vccnz .LBB0_793
	s_lshl_b64 s[0:1], s[28:29], 2
	s_add_u32 s0, s86, s0
	s_addc_u32 s1, s87, s1
	global_load_dwordx4 v[66:69], v177, s[0:1] offset:48
	global_load_dwordx4 v[70:73], v177, s[0:1] offset:32
	global_load_dwordx4 v[74:77], v177, s[0:1] offset:16
	global_load_dwordx4 v[78:81], v177, s[0:1]
	s_waitcnt vmcnt(3)
	v_pk_mul_f32 v[14:15], v[14:15], v[66:67]
	s_waitcnt vmcnt(2)
	v_pk_mul_f32 v[10:11], v[10:11], v[70:71]
	s_waitcnt vmcnt(1)
	v_pk_mul_f32 v[6:7], v[6:7], v[74:75]
	s_waitcnt vmcnt(0)
	v_pk_mul_f32 v[0:1], v[0:1], v[78:79]
	v_pk_mul_f32 v[2:3], v[2:3], v[80:81]
	v_pk_mul_f32 v[8:9], v[8:9], v[76:77]
	v_pk_mul_f32 v[12:13], v[12:13], v[72:73]
	v_pk_mul_f32 v[16:17], v[16:17], v[68:69]
	global_load_dwordx4 v[66:69], v177, s[0:1] offset:112
	global_load_dwordx4 v[70:73], v177, s[0:1] offset:96
	global_load_dwordx4 v[74:77], v177, s[0:1] offset:80
	global_load_dwordx4 v[78:81], v177, s[0:1] offset:64
	s_waitcnt vmcnt(3)
	v_pk_mul_f32 v[30:31], v[30:31], v[66:67]
	s_waitcnt vmcnt(2)
	v_pk_mul_f32 v[26:27], v[26:27], v[70:71]
	s_waitcnt vmcnt(1)
	v_pk_mul_f32 v[22:23], v[22:23], v[74:75]
	s_waitcnt vmcnt(0)
	v_pk_mul_f32 v[18:19], v[18:19], v[78:79]
	v_pk_mul_f32 v[20:21], v[20:21], v[80:81]
	v_pk_mul_f32 v[24:25], v[24:25], v[76:77]
	v_pk_mul_f32 v[28:29], v[28:29], v[72:73]
	v_pk_mul_f32 v[32:33], v[32:33], v[68:69]
	global_load_dwordx4 v[66:69], v177, s[0:1] offset:176
	global_load_dwordx4 v[70:73], v177, s[0:1] offset:160
	global_load_dwordx4 v[74:77], v177, s[0:1] offset:144
	global_load_dwordx4 v[78:81], v177, s[0:1] offset:128
	s_waitcnt vmcnt(3)
	v_pk_mul_f32 v[46:47], v[46:47], v[66:67]
	s_waitcnt vmcnt(2)
	v_pk_mul_f32 v[42:43], v[42:43], v[70:71]
	s_waitcnt vmcnt(1)
	v_pk_mul_f32 v[38:39], v[38:39], v[74:75]
	s_waitcnt vmcnt(0)
	v_pk_mul_f32 v[34:35], v[34:35], v[78:79]
	v_pk_mul_f32 v[36:37], v[36:37], v[80:81]
	v_pk_mul_f32 v[40:41], v[40:41], v[76:77]
	v_pk_mul_f32 v[44:45], v[44:45], v[72:73]
	v_pk_mul_f32 v[48:49], v[48:49], v[68:69]
	global_load_dwordx4 v[66:69], v177, s[0:1] offset:240
	global_load_dwordx4 v[70:73], v177, s[0:1] offset:224
	global_load_dwordx4 v[74:77], v177, s[0:1] offset:208
	global_load_dwordx4 v[78:81], v177, s[0:1] offset:192
	s_waitcnt vmcnt(3)
	v_pk_mul_f32 v[62:63], v[62:63], v[66:67]
	s_waitcnt vmcnt(2)
	v_pk_mul_f32 v[58:59], v[58:59], v[70:71]
	s_waitcnt vmcnt(1)
	v_pk_mul_f32 v[54:55], v[54:55], v[74:75]
	s_waitcnt vmcnt(0)
	v_pk_mul_f32 v[50:51], v[50:51], v[78:79]
	v_pk_mul_f32 v[52:53], v[52:53], v[80:81]
	v_pk_mul_f32 v[56:57], v[56:57], v[76:77]
	v_pk_mul_f32 v[60:61], v[60:61], v[72:73]
	v_pk_mul_f32 v[64:65], v[64:65], v[68:69]
	s_branch .LBB0_793
